# K-loop LDS-DMA issue rebalance (4/4/4/4, waits 10/4) applied to all nine main GEMM loops; per-unit recompute of the moved stage address
# speedup vs baseline: 1.0069x; 1.0004x over previous
;     __device__ __forceinline__ bool next(int i, Unit& u) const { const int L = L0 + i * G + c; if (L >= L1) return false; u.pm = L >> 2; u.pn = L & 3; u.ko = 0; return true; }
; #define PG8_STAGE(bufoff, gbase, voff) do { _Pragma("unroll") for (int _i = 0; _i < 2; ++_i) \
;         __builtin_amdgcn_global_load_lds((const unsigned*)((const char*)(gbase) + (voff)[_i]), (PG8_LAS unsigned*)(lds + (bufoff) + ldsw + _i * 8192), 16, 0, 0); } while (0)
; #define PG8_LDA(dst, b, h) do { _Pragma("unroll") for (int m = 0; m < 4; ++m) _Pragma("unroll") for (int k = 0; k < 2; ++k) dst[m][k] = *(const PG8_LAS bf16x8*)(lds + PG8_SA(b, h) + aoff + m * 2048 + k * 1024); } while (0)
; #define PG8_LDB(dst, b, h) do { _Pragma("unroll") for (int n = 0; n < 2; ++n) _Pragma("unroll") for (int k = 0; k < 2; ++k) dst[n][k] = *(const PG8_LAS bf16x8*)(lds + PG8_SB(b, h) + boff + n * 2048 + k * 1024); } while (0)
; template <class Epi, class Sched, bool ALIGN_EPI = false, bool SP2 = false, bool HALFM = false>
; __device__ __forceinline__ void gemm_phase(PG8_LAS unsigned char* lds, const Gemm g, const Sched& S, const Epi& E) {
;     ...
;         const bool has_next = S.next(ui + 1, nxt);
;         const char* nA = has_next ? (const char*)g.A + (size_t)nxt.pm * tstep + (size_t)nxt.ko * 2 : cA; const char* nB = has_next ? (const char*)g.Bt + (size_t)nxt.pn * tstep + (size_t)nxt.ko * 2 : cB;
;         for (int t = 0; t < nt; t += 2) {
;             const bool last = (t == nt - 2);
;             const char* a1 = cA + (size_t)(t + 1) * kstep;
;             const char* a2 = last ? nA : cA + (size_t)(t + 2) * kstep; const char* b2 = last ? nB : cB + (size_t)(t + 2) * kstep;
;             const char* a3 = a2 + kstep; const char* b3 = b2 + kstep;
;             if (last && has_next) S.a_ready(nxt);
;             if constexpr (SP2) {
;             PG8_LDB(B0, 0, 0); PG8_LDB(B1, 0, 1); PG8_SCHED; PG8_LDA(At, 0, 0); PG8_STAGE(PG8_SA(1, 1), a1 + hstep, voffA);
;             PG8_WAIT_V(8); PG8_WAIT_L(0); PG8_BAR; PG8_MMA(0, 0, At, B0); PG8_MMA(0, 1, At, B1); PG8_BAR; PG8_SCHED;
;     ...
;         for (int a = 0; a < 2; ++a)
; #pragma unroll
;             for (int b = 0; b < 2; ++b)
; #pragma unroll
;                 for (int m = 0; m < 4; ++m)
; #pragma unroll
;                     for (int n = 0; n < 2; ++n) acc[a][b][m][n] = (f32x4){0.f, 0.f, 0.f, 0.f};
;         cur = nxt; cA = nA; cB = nB; ++ui;
.LBB0_495:
	s_ashr_i32 s15, s14, 31
	s_lshl_b64 s[16:17], s[14:15], 19
	s_add_u32 s16, s80, s16
	s_addc_u32 s17, s81, s17
	s_and_b64 s[18:19], s[4:5], exec
	s_cselect_b32 s15, s17, s23
	s_cselect_b32 s41, s16, s22
	s_ashr_i32 s13, s12, 31
	s_lshl_b64 s[18:19], s[12:13], 19
	s_add_u32 s18, s34, s18
	s_addc_u32 s19, s35, s19
	s_and_b64 s[26:27], s[4:5], exec
	s_cselect_b32 s13, s19, s25
	s_cselect_b32 s42, s18, s24
	s_add_u32 s22, s22, 0x40080
	s_addc_u32 s23, s23, 0
	s_add_u32 s43, s24, 0x100
	v_mov_b32_e32 v2, 0
	s_addc_u32 s44, s25, 0
	s_mov_b32 s45, -2
	v_mov_b32_e32 v3, v2
	v_mov_b32_e32 v4, v2
	v_mov_b32_e32 v5, v2
	v_mov_b32_e32 v6, v2
	v_mov_b32_e32 v7, v2
	v_mov_b32_e32 v8, v2
	v_mov_b32_e32 v9, v2
	v_mov_b32_e32 v18, v2
	v_mov_b32_e32 v19, v2
	v_mov_b32_e32 v20, v2
	v_mov_b32_e32 v21, v2
	v_mov_b32_e32 v22, v2
	v_mov_b32_e32 v23, v2
	v_mov_b32_e32 v24, v2
	v_mov_b32_e32 v25, v2
	v_mov_b32_e32 v34, v2
	v_mov_b32_e32 v35, v2
	v_mov_b32_e32 v36, v2
	v_mov_b32_e32 v37, v2
	v_mov_b32_e32 v38, v2
	v_mov_b32_e32 v39, v2
	v_mov_b32_e32 v40, v2
	v_mov_b32_e32 v41, v2
	v_mov_b32_e32 v50, v2
	v_mov_b32_e32 v51, v2
	v_mov_b32_e32 v52, v2
	v_mov_b32_e32 v53, v2
	v_mov_b32_e32 v54, v2
	v_mov_b32_e32 v55, v2
	v_mov_b32_e32 v56, v2
	v_mov_b32_e32 v57, v2
	v_mov_b32_e32 v10, v2
	v_mov_b32_e32 v11, v2
	v_mov_b32_e32 v12, v2
	v_mov_b32_e32 v13, v2
	v_mov_b32_e32 v14, v2
	v_mov_b32_e32 v15, v2
	v_mov_b32_e32 v16, v2
	v_mov_b32_e32 v17, v2
	v_mov_b32_e32 v26, v2
	v_mov_b32_e32 v27, v2
	v_mov_b32_e32 v28, v2
	v_mov_b32_e32 v29, v2
	v_mov_b32_e32 v30, v2
	v_mov_b32_e32 v31, v2
	v_mov_b32_e32 v32, v2
	v_mov_b32_e32 v33, v2
	v_mov_b32_e32 v42, v2
	v_mov_b32_e32 v43, v2
	v_mov_b32_e32 v44, v2
	v_mov_b32_e32 v45, v2
	v_mov_b32_e32 v46, v2
	v_mov_b32_e32 v47, v2
	v_mov_b32_e32 v48, v2
	v_mov_b32_e32 v49, v2
	v_mov_b32_e32 v58, v2
	v_mov_b32_e32 v59, v2
	v_mov_b32_e32 v60, v2
	v_mov_b32_e32 v61, v2
	v_mov_b32_e32 v62, v2
	v_mov_b32_e32 v63, v2
	v_mov_b32_e32 v64, v2
	v_mov_b32_e32 v65, v2
	v_mov_b32_e32 v66, v2
	v_mov_b32_e32 v67, v2
	v_mov_b32_e32 v68, v2
	v_mov_b32_e32 v69, v2
	v_mov_b32_e32 v70, v2
	v_mov_b32_e32 v71, v2
	v_mov_b32_e32 v72, v2
	v_mov_b32_e32 v73, v2
	v_mov_b32_e32 v82, v2
	v_mov_b32_e32 v83, v2
	v_mov_b32_e32 v84, v2
	v_mov_b32_e32 v85, v2
	v_mov_b32_e32 v86, v2
	v_mov_b32_e32 v87, v2
	v_mov_b32_e32 v88, v2
	v_mov_b32_e32 v89, v2
	v_mov_b32_e32 v98, v2
	v_mov_b32_e32 v99, v2
	v_mov_b32_e32 v100, v2
	v_mov_b32_e32 v101, v2
	v_mov_b32_e32 v102, v2
	v_mov_b32_e32 v103, v2
	v_mov_b32_e32 v104, v2
	v_mov_b32_e32 v105, v2
	v_mov_b32_e32 v114, v2
	v_mov_b32_e32 v115, v2
	v_mov_b32_e32 v116, v2
	v_mov_b32_e32 v117, v2
	v_mov_b32_e32 v118, v2
	v_mov_b32_e32 v119, v2
	v_mov_b32_e32 v120, v2
	v_mov_b32_e32 v121, v2
	v_mov_b32_e32 v74, v2
	v_mov_b32_e32 v75, v2
	v_mov_b32_e32 v76, v2
	v_mov_b32_e32 v77, v2
	v_mov_b32_e32 v78, v2
	v_mov_b32_e32 v79, v2
	v_mov_b32_e32 v80, v2
	v_mov_b32_e32 v81, v2
	v_mov_b32_e32 v90, v2
	v_mov_b32_e32 v91, v2
	v_mov_b32_e32 v92, v2
	v_mov_b32_e32 v93, v2
	v_mov_b32_e32 v94, v2
	v_mov_b32_e32 v95, v2
	v_mov_b32_e32 v96, v2
	v_mov_b32_e32 v97, v2
	v_mov_b32_e32 v106, v2
	v_mov_b32_e32 v107, v2
	v_mov_b32_e32 v108, v2
	v_mov_b32_e32 v109, v2
	v_mov_b32_e32 v110, v2
	v_mov_b32_e32 v111, v2
	v_mov_b32_e32 v112, v2
	v_mov_b32_e32 v113, v2
	v_mov_b32_e32 v122, v2
	v_mov_b32_e32 v123, v2
	v_mov_b32_e32 v124, v2
	v_mov_b32_e32 v125, v2
	v_mov_b32_e32 v126, v2
	v_mov_b32_e32 v127, v2
	v_mov_b32_e32 v128, v2
	v_mov_b32_e32 v129, v2
	s_mov_b32 s100, 0xfffbff80
	s_mov_b32 s101, -1
	v_lshl_add_u64 v[220:221], s[22:23], 0, v[138:139]
	v_lshl_add_u64 v[220:221], v[220:221], 0, s[100:101]
	v_lshl_add_u64 v[222:223], s[22:23], 0, v[140:141]
	v_lshl_add_u64 v[222:223], v[222:223], 0, s[100:101]
.LBB0_496:
	ds_read_b128 v[154:157], v150
	ds_read_b128 v[158:161], v150 offset:1024
	ds_read_b128 v[162:165], v150 offset:2048
	ds_read_b128 v[166:169], v150 offset:3072
	ds_read_b128 v[170:173], v151
	ds_read_b128 v[174:177], v151 offset:1024
	ds_read_b128 v[178:181], v151 offset:2048
	ds_read_b128 v[182:185], v151 offset:3072
	s_add_u32 s24, s22, 0xfffc0080
	s_addc_u32 s25, s23, -1
	s_cmp_eq_u32 s45, 12
	s_cselect_b32 s27, s15, s25
	s_cselect_b32 s26, s41, s24
	s_cselect_b32 s25, s13, s44
	s_cselect_b32 s24, s42, s43
	v_lshl_add_u64 v[146:147], s[22:23], 0, v[138:139]
	s_add_i32 m0, s2, 0xc000
	ds_read_b128 v[186:189], v152
	ds_read_b128 v[190:193], v152 offset:1024
	ds_read_b128 v[194:197], v152 offset:2048
	ds_read_b128 v[198:201], v152 offset:3072
	ds_read_b128 v[202:205], v152 offset:4096
	ds_read_b128 v[206:209], v152 offset:5120
	ds_read_b128 v[210:213], v152 offset:6144
	ds_read_b128 v[214:217], v152 offset:7168
	global_load_lds_dwordx4 v[146:147], off
	v_lshl_add_u64 v[146:147], s[22:23], 0, v[140:141]
	s_add_i32 m0, s2, 0xe000
	s_nop 0
	global_load_lds_dwordx4 v[146:147], off
	s_mov_b32 m0, s30
	v_lshl_add_u64 v[146:147], v[220:221], 0, s[8:9]
	global_load_lds_dwordx4 v[146:147], off
	s_mov_b32 m0, s31
	v_lshl_add_u64 v[146:147], v[222:223], 0, s[8:9]
	global_load_lds_dwordx4 v[146:147], off
	s_waitcnt vmcnt(10)
	s_waitcnt lgkmcnt(0)
	s_barrier
; #define PG8_STAGE(bufoff, gbase, voff) do { _Pragma("unroll") for (int _i = 0; _i < 2; ++_i) \
;         __builtin_amdgcn_global_load_lds((const unsigned*)((const char*)(gbase) + (voff)[_i]), (PG8_LAS unsigned*)(lds + (bufoff) + ldsw + _i * 8192), 16, 0, 0); } while (0)
; #define PG8_LDA(dst, b, h) do { _Pragma("unroll") for (int m = 0; m < 4; ++m) _Pragma("unroll") for (int k = 0; k < 2; ++k) dst[m][k] = *(const PG8_LAS bf16x8*)(lds + PG8_SA(b, h) + aoff + m * 2048 + k * 1024); } while (0)
; #define PG8_MMA(ai, bj, At, Bt) do { __builtin_amdgcn_s_setprio(1); _Pragma("unroll") for (int m = 0; m < 4; ++m) _Pragma("unroll") for (int n = 0; n < 2; ++n) _Pragma("unroll") for (int k = 0; k < 2; ++k) \
;         acc[ai][bj][m][n] = __builtin_amdgcn_mfma_f32_16x16x32_bf16(Bt[n][k], At[m][k], acc[ai][bj][m][n], 0, 0, 0); __builtin_amdgcn_s_setprio(0); } while (0)
; #define PG8_WAIT_V(n) asm volatile("s_waitcnt vmcnt(" #n ")" ::: "memory")
; #define PG8_WAIT_L(n) asm volatile("s_waitcnt lgkmcnt(" #n ")" ::: "memory")
; #define PG8_BAR __builtin_amdgcn_s_barrier()
; #define PG8_SCHED __builtin_amdgcn_sched_barrier(0)
; template <class Epi, class Sched, bool ALIGN_EPI = false, bool SP2 = false, bool HALFM = false>
; __device__ __forceinline__ void gemm_phase(PG8_LAS unsigned char* lds, const Gemm g, const Sched& S, const Epi& E) {
;     ...
;             PG8_WAIT_V(8); PG8_WAIT_L(0); PG8_BAR; PG8_MMA(0, 0, At, B0); PG8_MMA(0, 1, At, B1); PG8_BAR; PG8_SCHED;
;             PG8_LDA(At, 0, 1); PG8_STAGE(PG8_SB(0, 0), b2, voffB); PG8_STAGE(PG8_SB(0, 1), b2 + hstep, voffB); PG8_STAGE(PG8_SA(0, 0), a2, voffA);
;             PG8_WAIT_V(8); PG8_WAIT_L(0); PG8_BAR; if constexpr (!HALFM) { PG8_MMA(1, 0, At, B0); PG8_MMA(1, 1, At, B1); } PG8_BAR; PG8_SCHED;
	s_setprio 1
	s_waitcnt lgkmcnt(0)
	v_mfma_f32_16x16x32_bf16 v[126:129], v[154:157], v[186:189], v[126:129]
	v_mfma_f32_16x16x32_bf16 v[122:125], v[162:165], v[186:189], v[122:125]
	v_mfma_f32_16x16x32_bf16 v[110:113], v[154:157], v[194:197], v[110:113]
	v_mfma_f32_16x16x32_bf16 v[106:109], v[162:165], v[194:197], v[106:109]
	v_mfma_f32_16x16x32_bf16 v[94:97], v[154:157], v[202:205], v[94:97]
	v_mfma_f32_16x16x32_bf16 v[90:93], v[162:165], v[202:205], v[90:93]
	v_mfma_f32_16x16x32_bf16 v[78:81], v[154:157], v[210:213], v[78:81]
	v_mfma_f32_16x16x32_bf16 v[74:77], v[162:165], v[210:213], v[74:77]
	v_mfma_f32_16x16x32_bf16 v[126:129], v[158:161], v[190:193], v[126:129]
	v_mfma_f32_16x16x32_bf16 v[122:125], v[166:169], v[190:193], v[122:125]
	v_mfma_f32_16x16x32_bf16 v[110:113], v[158:161], v[198:201], v[110:113]
	v_mfma_f32_16x16x32_bf16 v[106:109], v[166:169], v[198:201], v[106:109]
	v_mfma_f32_16x16x32_bf16 v[94:97], v[158:161], v[206:209], v[94:97]
	v_mfma_f32_16x16x32_bf16 v[90:93], v[166:169], v[206:209], v[90:93]
	v_mfma_f32_16x16x32_bf16 v[78:81], v[158:161], v[214:217], v[78:81]
	v_mfma_f32_16x16x32_bf16 v[74:77], v[166:169], v[214:217], v[74:77]
	s_setprio 0
	s_setprio 1
	v_mfma_f32_16x16x32_bf16 v[118:121], v[170:173], v[186:189], v[118:121]
	v_mfma_f32_16x16x32_bf16 v[114:117], v[178:181], v[186:189], v[114:117]
	v_mfma_f32_16x16x32_bf16 v[102:105], v[170:173], v[194:197], v[102:105]
	v_mfma_f32_16x16x32_bf16 v[98:101], v[178:181], v[194:197], v[98:101]
	v_mfma_f32_16x16x32_bf16 v[86:89], v[170:173], v[202:205], v[86:89]
	v_mfma_f32_16x16x32_bf16 v[82:85], v[178:181], v[202:205], v[82:85]
	v_mfma_f32_16x16x32_bf16 v[70:73], v[170:173], v[210:213], v[70:73]
	v_mfma_f32_16x16x32_bf16 v[66:69], v[178:181], v[210:213], v[66:69]
	v_mfma_f32_16x16x32_bf16 v[118:121], v[174:177], v[190:193], v[118:121]
	v_mfma_f32_16x16x32_bf16 v[114:117], v[182:185], v[190:193], v[114:117]
	v_mfma_f32_16x16x32_bf16 v[102:105], v[174:177], v[198:201], v[102:105]
	v_mfma_f32_16x16x32_bf16 v[98:101], v[182:185], v[198:201], v[98:101]
	v_mfma_f32_16x16x32_bf16 v[86:89], v[174:177], v[206:209], v[86:89]
	v_mfma_f32_16x16x32_bf16 v[82:85], v[182:185], v[206:209], v[82:85]
	v_mfma_f32_16x16x32_bf16 v[70:73], v[174:177], v[214:217], v[70:73]
	v_mfma_f32_16x16x32_bf16 v[66:69], v[182:185], v[214:217], v[66:69]
	s_setprio 0
	s_barrier
	s_add_i32 s46, s37, s0
	v_lshl_add_u64 v[146:147], s[24:25], 0, v[134:135]
	s_mov_b32 m0, s46
	ds_read_b128 v[186:189], v152 offset:16384
	ds_read_b128 v[190:193], v152 offset:17408
	ds_read_b128 v[194:197], v152 offset:18432
	ds_read_b128 v[198:201], v152 offset:19456
	ds_read_b128 v[202:205], v152 offset:20480
	ds_read_b128 v[206:209], v152 offset:21504
	ds_read_b128 v[210:213], v152 offset:22528
	ds_read_b128 v[214:217], v152 offset:23552
	global_load_lds_dwordx4 v[146:147], off
	s_add_i32 m0, s46, 0x2000
	s_add_u32 s46, s24, 0x40000
	v_lshl_add_u64 v[218:219], s[24:25], 0, v[130:131]
	s_addc_u32 s47, s25, 0
	s_add_i32 s48, s38, s0
	global_load_lds_dwordx4 v[218:219], off
	v_lshl_add_u64 v[220:221], s[46:47], 0, v[134:135]
	s_mov_b32 m0, s48
	v_lshl_add_u64 v[222:223], s[26:27], 0, v[132:133]
	global_load_lds_dwordx4 v[220:221], off
	v_lshl_add_u64 v[220:221], s[46:47], 0, v[130:131]
	s_add_i32 m0, s48, 0x2000
	s_nop 0
	global_load_lds_dwordx4 v[220:221], off
	v_lshl_add_u64 v[220:221], s[26:27], 0, v[136:137]
	s_waitcnt vmcnt(4)
	s_waitcnt lgkmcnt(0)
	s_barrier
	s_setprio 1
	s_waitcnt lgkmcnt(0)
	v_mfma_f32_16x16x32_bf16 v[62:65], v[154:157], v[186:189], v[62:65]
	v_mfma_f32_16x16x32_bf16 v[58:61], v[162:165], v[186:189], v[58:61]
	v_mfma_f32_16x16x32_bf16 v[46:49], v[154:157], v[194:197], v[46:49]
	v_mfma_f32_16x16x32_bf16 v[42:45], v[162:165], v[194:197], v[42:45]
	v_mfma_f32_16x16x32_bf16 v[30:33], v[154:157], v[202:205], v[30:33]
	v_mfma_f32_16x16x32_bf16 v[26:29], v[162:165], v[202:205], v[26:29]
	v_mfma_f32_16x16x32_bf16 v[14:17], v[154:157], v[210:213], v[14:17]
	v_mfma_f32_16x16x32_bf16 v[10:13], v[162:165], v[210:213], v[10:13]
	v_mfma_f32_16x16x32_bf16 v[62:65], v[158:161], v[190:193], v[62:65]
	v_mfma_f32_16x16x32_bf16 v[58:61], v[166:169], v[190:193], v[58:61]
	v_mfma_f32_16x16x32_bf16 v[46:49], v[158:161], v[198:201], v[46:49]
	v_mfma_f32_16x16x32_bf16 v[42:45], v[166:169], v[198:201], v[42:45]
	v_mfma_f32_16x16x32_bf16 v[30:33], v[158:161], v[206:209], v[30:33]
	v_mfma_f32_16x16x32_bf16 v[26:29], v[166:169], v[206:209], v[26:29]
	v_mfma_f32_16x16x32_bf16 v[14:17], v[158:161], v[214:217], v[14:17]
	v_mfma_f32_16x16x32_bf16 v[10:13], v[166:169], v[214:217], v[10:13]
	s_setprio 0
	s_setprio 1
	v_mfma_f32_16x16x32_bf16 v[54:57], v[170:173], v[186:189], v[54:57]
	v_mfma_f32_16x16x32_bf16 v[50:53], v[178:181], v[186:189], v[50:53]
	v_mfma_f32_16x16x32_bf16 v[38:41], v[170:173], v[194:197], v[38:41]
	v_mfma_f32_16x16x32_bf16 v[34:37], v[178:181], v[194:197], v[34:37]
	v_mfma_f32_16x16x32_bf16 v[22:25], v[170:173], v[202:205], v[22:25]
	v_mfma_f32_16x16x32_bf16 v[18:21], v[178:181], v[202:205], v[18:21]
	v_mfma_f32_16x16x32_bf16 v[6:9], v[170:173], v[210:213], v[6:9]
	v_mfma_f32_16x16x32_bf16 v[2:5], v[178:181], v[210:213], v[2:5]
	v_mfma_f32_16x16x32_bf16 v[54:57], v[174:177], v[190:193], v[54:57]
	v_mfma_f32_16x16x32_bf16 v[50:53], v[182:185], v[190:193], v[50:53]
	v_mfma_f32_16x16x32_bf16 v[38:41], v[174:177], v[198:201], v[38:41]
	v_mfma_f32_16x16x32_bf16 v[34:37], v[182:185], v[198:201], v[34:37]
	v_mfma_f32_16x16x32_bf16 v[22:25], v[174:177], v[206:209], v[22:25]
	v_mfma_f32_16x16x32_bf16 v[18:21], v[182:185], v[206:209], v[18:21]
	v_mfma_f32_16x16x32_bf16 v[6:9], v[174:177], v[214:217], v[6:9]
	v_mfma_f32_16x16x32_bf16 v[2:5], v[182:185], v[214:217], v[2:5]
	s_setprio 0
	s_barrier
; #define PG8_STAGE(bufoff, gbase, voff) do { _Pragma("unroll") for (int _i = 0; _i < 2; ++_i) \
;         __builtin_amdgcn_global_load_lds((const unsigned*)((const char*)(gbase) + (voff)[_i]), (PG8_LAS unsigned*)(lds + (bufoff) + ldsw + _i * 8192), 16, 0, 0); } while (0)
; #define PG8_LDA(dst, b, h) do { _Pragma("unroll") for (int m = 0; m < 4; ++m) _Pragma("unroll") for (int k = 0; k < 2; ++k) dst[m][k] = *(const PG8_LAS bf16x8*)(lds + PG8_SA(b, h) + aoff + m * 2048 + k * 1024); } while (0)
; #define PG8_LDB(dst, b, h) do { _Pragma("unroll") for (int n = 0; n < 2; ++n) _Pragma("unroll") for (int k = 0; k < 2; ++k) dst[n][k] = *(const PG8_LAS bf16x8*)(lds + PG8_SB(b, h) + boff + n * 2048 + k * 1024); } while (0)
; #define PG8_MMA(ai, bj, At, Bt) do { __builtin_amdgcn_s_setprio(1); _Pragma("unroll") for (int m = 0; m < 4; ++m) _Pragma("unroll") for (int n = 0; n < 2; ++n) _Pragma("unroll") for (int k = 0; k < 2; ++k) \
;         acc[ai][bj][m][n] = __builtin_amdgcn_mfma_f32_16x16x32_bf16(Bt[n][k], At[m][k], acc[ai][bj][m][n], 0, 0, 0); __builtin_amdgcn_s_setprio(0); } while (0)
; #define PG8_WAIT_V(n) asm volatile("s_waitcnt vmcnt(" #n ")" ::: "memory")
; #define PG8_WAIT_L(n) asm volatile("s_waitcnt lgkmcnt(" #n ")" ::: "memory")
; #define PG8_BAR __builtin_amdgcn_s_barrier()
; #define PG8_SCHED __builtin_amdgcn_sched_barrier(0)
; template <class Epi, class Sched, bool ALIGN_EPI = false, bool SP2 = false, bool HALFM = false>
; __device__ __forceinline__ void gemm_phase(PG8_LAS unsigned char* lds, const Gemm g, const Sched& S, const Epi& E) {
;     ...
;             PG8_LDB(B0, 1, 0); PG8_LDB(B1, 1, 1); PG8_SCHED; PG8_LDA(At, 1, 0); PG8_STAGE(PG8_SA(0, 1), a2 + hstep, voffA);
;             PG8_WAIT_V(8); PG8_WAIT_L(0); PG8_BAR; PG8_MMA(0, 0, At, B0); PG8_MMA(0, 1, At, B1); PG8_BAR; PG8_SCHED;
	s_add_i32 s46, 0, 0x18000
	v_add_u32_e32 v153, s46, v148
	s_add_i32 s47, 0, 0x1c000
	ds_read_b128 v[154:157], v153
	ds_read_b128 v[158:161], v153 offset:1024
	ds_read_b128 v[162:165], v153 offset:2048
	ds_read_b128 v[166:169], v153 offset:3072
	v_add_u32_e32 v153, s47, v148
	ds_read_b128 v[170:173], v153
	ds_read_b128 v[174:177], v153 offset:1024
	ds_read_b128 v[178:181], v153 offset:2048
	ds_read_b128 v[182:185], v153 offset:3072
	s_add_u32 s26, s26, 0x40000
	s_addc_u32 s27, s27, 0
	s_mov_b32 m0, s21
	v_lshl_add_u64 v[224:225], s[26:27], 0, v[136:137]
	ds_read_b128 v[186:189], v152 offset:32768
	ds_read_b128 v[190:193], v152 offset:33792
	ds_read_b128 v[194:197], v152 offset:34816
	ds_read_b128 v[198:201], v152 offset:35840
	ds_read_b128 v[202:205], v152 offset:36864
	ds_read_b128 v[206:209], v152 offset:37888
	ds_read_b128 v[210:213], v152 offset:38912
	ds_read_b128 v[214:217], v152 offset:39936
	global_load_lds_dwordx4 v[224:225], off
	v_lshl_add_u64 v[224:225], s[26:27], 0, v[132:133]
	s_mov_b32 m0, s28
	s_nop 0
	global_load_lds_dwordx4 v[224:225], off
	s_mov_b32 m0, s2
	s_nop 0
	global_load_lds_dwordx4 v[220:221], off
	s_mov_b32 m0, s3
	s_nop 0
	global_load_lds_dwordx4 v[222:223], off
	s_waitcnt vmcnt(10)
	s_waitcnt lgkmcnt(0)
	s_barrier
	s_setprio 1
	s_waitcnt lgkmcnt(0)
	v_mfma_f32_16x16x32_bf16 v[126:129], v[154:157], v[186:189], v[126:129]
	v_mfma_f32_16x16x32_bf16 v[122:125], v[162:165], v[186:189], v[122:125]
	v_mfma_f32_16x16x32_bf16 v[110:113], v[154:157], v[194:197], v[110:113]
	v_mfma_f32_16x16x32_bf16 v[106:109], v[162:165], v[194:197], v[106:109]
	v_mfma_f32_16x16x32_bf16 v[94:97], v[154:157], v[202:205], v[94:97]
	v_mfma_f32_16x16x32_bf16 v[90:93], v[162:165], v[202:205], v[90:93]
	v_mfma_f32_16x16x32_bf16 v[78:81], v[154:157], v[210:213], v[78:81]
	v_mfma_f32_16x16x32_bf16 v[74:77], v[162:165], v[210:213], v[74:77]
	v_mfma_f32_16x16x32_bf16 v[126:129], v[158:161], v[190:193], v[126:129]
	v_mfma_f32_16x16x32_bf16 v[122:125], v[166:169], v[190:193], v[122:125]
	v_mfma_f32_16x16x32_bf16 v[110:113], v[158:161], v[198:201], v[110:113]
	v_mfma_f32_16x16x32_bf16 v[106:109], v[166:169], v[198:201], v[106:109]
	v_mfma_f32_16x16x32_bf16 v[94:97], v[158:161], v[206:209], v[94:97]
	v_mfma_f32_16x16x32_bf16 v[90:93], v[166:169], v[206:209], v[90:93]
	v_mfma_f32_16x16x32_bf16 v[78:81], v[158:161], v[214:217], v[78:81]
	v_mfma_f32_16x16x32_bf16 v[74:77], v[166:169], v[214:217], v[74:77]
	s_setprio 0
	s_setprio 1
	v_mfma_f32_16x16x32_bf16 v[118:121], v[170:173], v[186:189], v[118:121]
	v_mfma_f32_16x16x32_bf16 v[114:117], v[178:181], v[186:189], v[114:117]
	v_mfma_f32_16x16x32_bf16 v[102:105], v[170:173], v[194:197], v[102:105]
	v_mfma_f32_16x16x32_bf16 v[98:101], v[178:181], v[194:197], v[98:101]
	v_mfma_f32_16x16x32_bf16 v[86:89], v[170:173], v[202:205], v[86:89]
	v_mfma_f32_16x16x32_bf16 v[82:85], v[178:181], v[202:205], v[82:85]
	v_mfma_f32_16x16x32_bf16 v[70:73], v[170:173], v[210:213], v[70:73]
	v_mfma_f32_16x16x32_bf16 v[66:69], v[178:181], v[210:213], v[66:69]
	v_mfma_f32_16x16x32_bf16 v[118:121], v[174:177], v[190:193], v[118:121]
	v_mfma_f32_16x16x32_bf16 v[114:117], v[182:185], v[190:193], v[114:117]
	v_mfma_f32_16x16x32_bf16 v[102:105], v[174:177], v[198:201], v[102:105]
	v_mfma_f32_16x16x32_bf16 v[98:101], v[182:185], v[198:201], v[98:101]
	v_mfma_f32_16x16x32_bf16 v[86:89], v[174:177], v[206:209], v[86:89]
	v_mfma_f32_16x16x32_bf16 v[82:85], v[182:185], v[206:209], v[82:85]
	v_mfma_f32_16x16x32_bf16 v[70:73], v[174:177], v[214:217], v[70:73]
	v_mfma_f32_16x16x32_bf16 v[66:69], v[182:185], v[214:217], v[66:69]
	s_setprio 0
	s_barrier
; #define PG8_STAGE(bufoff, gbase, voff) do { _Pragma("unroll") for (int _i = 0; _i < 2; ++_i) \
;         __builtin_amdgcn_global_load_lds((const unsigned*)((const char*)(gbase) + (voff)[_i]), (PG8_LAS unsigned*)(lds + (bufoff) + ldsw + _i * 8192), 16, 0, 0); } while (0)
; #define PG8_LDA(dst, b, h) do { _Pragma("unroll") for (int m = 0; m < 4; ++m) _Pragma("unroll") for (int k = 0; k < 2; ++k) dst[m][k] = *(const PG8_LAS bf16x8*)(lds + PG8_SA(b, h) + aoff + m * 2048 + k * 1024); } while (0)
; #define PG8_MMA(ai, bj, At, Bt) do { __builtin_amdgcn_s_setprio(1); _Pragma("unroll") for (int m = 0; m < 4; ++m) _Pragma("unroll") for (int n = 0; n < 2; ++n) _Pragma("unroll") for (int k = 0; k < 2; ++k) \
;         acc[ai][bj][m][n] = __builtin_amdgcn_mfma_f32_16x16x32_bf16(Bt[n][k], At[m][k], acc[ai][bj][m][n], 0, 0, 0); __builtin_amdgcn_s_setprio(0); } while (0)
; #define PG8_WAIT_V(n) asm volatile("s_waitcnt vmcnt(" #n ")" ::: "memory")
; #define PG8_WAIT_L(n) asm volatile("s_waitcnt lgkmcnt(" #n ")" ::: "memory")
; #define PG8_BAR __builtin_amdgcn_s_barrier()
; #define PG8_SCHED __builtin_amdgcn_sched_barrier(0)
; template <class Epi, class Sched, bool ALIGN_EPI = false, bool SP2 = false, bool HALFM = false>
; __device__ __forceinline__ void gemm_phase(PG8_LAS unsigned char* lds, const Gemm g, const Sched& S, const Epi& E) {
;     ...
;             PG8_LDA(At, 1, 1); PG8_STAGE(PG8_SB(1, 0), b3, voffB); PG8_STAGE(PG8_SB(1, 1), b3 + hstep, voffB); PG8_STAGE(PG8_SA(1, 0), a3, voffA);
;             PG8_WAIT_V(8); PG8_WAIT_L(0); PG8_BAR; if constexpr (!HALFM) { PG8_MMA(1, 0, At, B0); PG8_MMA(1, 1, At, B1); } PG8_BAR; PG8_SCHED;
	s_add_i32 s26, s46, s0
	v_lshl_add_u64 v[146:147], v[146:147], 0, s[8:9]
	s_mov_b32 m0, s26
	ds_read_b128 v[186:189], v152 offset:49152
	ds_read_b128 v[190:193], v152 offset:50176
	ds_read_b128 v[194:197], v152 offset:51200
	ds_read_b128 v[198:201], v152 offset:52224
	ds_read_b128 v[202:205], v152 offset:53248
	ds_read_b128 v[206:209], v152 offset:54272
	ds_read_b128 v[210:213], v152 offset:55296
	ds_read_b128 v[214:217], v152 offset:56320
	global_load_lds_dwordx4 v[146:147], off
	s_add_i32 m0, s26, 0x2000
	s_add_u32 s24, s24, 0x40080
	v_lshl_add_u64 v[146:147], v[218:219], 0, s[8:9]
	s_addc_u32 s25, s25, 0
	s_add_i32 s26, s47, s0
	global_load_lds_dwordx4 v[146:147], off
	v_lshl_add_u64 v[146:147], s[24:25], 0, v[134:135]
	s_mov_b32 m0, s26
	s_nop 0
	global_load_lds_dwordx4 v[146:147], off
	v_lshl_add_u64 v[146:147], s[24:25], 0, v[130:131]
	s_add_i32 m0, s26, 0x2000
	s_nop 0
	global_load_lds_dwordx4 v[146:147], off
	s_waitcnt vmcnt(4)
	s_waitcnt lgkmcnt(0)
	s_barrier
	s_setprio 1
	s_waitcnt lgkmcnt(0)
	v_mfma_f32_16x16x32_bf16 v[62:65], v[154:157], v[186:189], v[62:65]
	v_mfma_f32_16x16x32_bf16 v[58:61], v[162:165], v[186:189], v[58:61]
	v_mfma_f32_16x16x32_bf16 v[46:49], v[154:157], v[194:197], v[46:49]
	v_mfma_f32_16x16x32_bf16 v[42:45], v[162:165], v[194:197], v[42:45]
	v_mfma_f32_16x16x32_bf16 v[30:33], v[154:157], v[202:205], v[30:33]
	v_mfma_f32_16x16x32_bf16 v[26:29], v[162:165], v[202:205], v[26:29]
	v_mfma_f32_16x16x32_bf16 v[14:17], v[154:157], v[210:213], v[14:17]
	v_mfma_f32_16x16x32_bf16 v[10:13], v[162:165], v[210:213], v[10:13]
	v_mfma_f32_16x16x32_bf16 v[62:65], v[158:161], v[190:193], v[62:65]
	v_mfma_f32_16x16x32_bf16 v[58:61], v[166:169], v[190:193], v[58:61]
	v_mfma_f32_16x16x32_bf16 v[46:49], v[158:161], v[198:201], v[46:49]
	v_mfma_f32_16x16x32_bf16 v[42:45], v[166:169], v[198:201], v[42:45]
	v_mfma_f32_16x16x32_bf16 v[30:33], v[158:161], v[206:209], v[30:33]
	v_mfma_f32_16x16x32_bf16 v[26:29], v[166:169], v[206:209], v[26:29]
	v_mfma_f32_16x16x32_bf16 v[14:17], v[158:161], v[214:217], v[14:17]
	v_mfma_f32_16x16x32_bf16 v[10:13], v[166:169], v[214:217], v[10:13]
	s_setprio 0
	s_setprio 1
	v_mfma_f32_16x16x32_bf16 v[54:57], v[170:173], v[186:189], v[54:57]
	v_mfma_f32_16x16x32_bf16 v[50:53], v[178:181], v[186:189], v[50:53]
	v_mfma_f32_16x16x32_bf16 v[38:41], v[170:173], v[194:197], v[38:41]
	v_mfma_f32_16x16x32_bf16 v[34:37], v[178:181], v[194:197], v[34:37]
	v_mfma_f32_16x16x32_bf16 v[22:25], v[170:173], v[202:205], v[22:25]
	v_mfma_f32_16x16x32_bf16 v[18:21], v[178:181], v[202:205], v[18:21]
	v_mfma_f32_16x16x32_bf16 v[6:9], v[170:173], v[210:213], v[6:9]
	v_mfma_f32_16x16x32_bf16 v[2:5], v[178:181], v[210:213], v[2:5]
	v_mfma_f32_16x16x32_bf16 v[54:57], v[174:177], v[190:193], v[54:57]
	v_mfma_f32_16x16x32_bf16 v[50:53], v[182:185], v[190:193], v[50:53]
	v_mfma_f32_16x16x32_bf16 v[38:41], v[174:177], v[198:201], v[38:41]
	v_mfma_f32_16x16x32_bf16 v[34:37], v[182:185], v[198:201], v[34:37]
	v_mfma_f32_16x16x32_bf16 v[22:25], v[174:177], v[206:209], v[22:25]
	v_mfma_f32_16x16x32_bf16 v[18:21], v[182:185], v[206:209], v[18:21]
	v_mfma_f32_16x16x32_bf16 v[6:9], v[174:177], v[214:217], v[6:9]
	v_mfma_f32_16x16x32_bf16 v[2:5], v[182:185], v[214:217], v[2:5]
	s_setprio 0
	s_barrier
	s_add_i32 s45, s45, 2
	s_add_u32 s22, s22, 0x100
	s_addc_u32 s23, s23, 0
	s_add_u32 s43, s43, 0x100
	s_addc_u32 s44, s44, 0
	s_cmp_gt_u32 s45, 13
	s_cbranch_scc0 .LBB0_496
	s_and_b64 vcc, exec, s[10:11]
	s_cbranch_vccz .LBB0_499
	s_barrier

;     __device__ __forceinline__ bool next(int i, Unit& u) const { const int L = L0 + i * G + c; if (L >= L1) return false; u.pm = L >> 2; u.pn = L & 3; u.ko = 0; return true; }
; #define PG8_STAGE(bufoff, gbase, voff) do { _Pragma("unroll") for (int _i = 0; _i < 2; ++_i) \
;         __builtin_amdgcn_global_load_lds((const unsigned*)((const char*)(gbase) + (voff)[_i]), (PG8_LAS unsigned*)(lds + (bufoff) + ldsw + _i * 8192), 16, 0, 0); } while (0)
; #define PG8_LDA(dst, b, h) do { _Pragma("unroll") for (int m = 0; m < 4; ++m) _Pragma("unroll") for (int k = 0; k < 2; ++k) dst[m][k] = *(const PG8_LAS bf16x8*)(lds + PG8_SA(b, h) + aoff + m * 2048 + k * 1024); } while (0)
; #define PG8_LDB(dst, b, h) do { _Pragma("unroll") for (int n = 0; n < 2; ++n) _Pragma("unroll") for (int k = 0; k < 2; ++k) dst[n][k] = *(const PG8_LAS bf16x8*)(lds + PG8_SB(b, h) + boff + n * 2048 + k * 1024); } while (0)
; template <class Epi, class Sched, bool ALIGN_EPI = false, bool SP2 = false, bool HALFM = false>
; __device__ __forceinline__ void gemm_phase(PG8_LAS unsigned char* lds, const Gemm g, const Sched& S, const Epi& E) {
;     ...
;         const bool has_next = S.next(ui + 1, nxt);
;         const char* nA = has_next ? (const char*)g.A + (size_t)nxt.pm * tstep + (size_t)nxt.ko * 2 : cA; const char* nB = has_next ? (const char*)g.Bt + (size_t)nxt.pn * tstep + (size_t)nxt.ko * 2 : cB;
;         for (int t = 0; t < nt; t += 2) {
;             const bool last = (t == nt - 2);
;             const char* a1 = cA + (size_t)(t + 1) * kstep;
;             const char* a2 = last ? nA : cA + (size_t)(t + 2) * kstep; const char* b2 = last ? nB : cB + (size_t)(t + 2) * kstep;
;             const char* a3 = a2 + kstep; const char* b3 = b2 + kstep;
;             if (last && has_next) S.a_ready(nxt);
;             if constexpr (SP2) {
;             PG8_LDB(B0, 0, 0); PG8_LDB(B1, 0, 1); PG8_SCHED; PG8_LDA(At, 0, 0); PG8_STAGE(PG8_SA(1, 1), a1 + hstep, voffA);
;             PG8_WAIT_V(8); PG8_WAIT_L(0); PG8_BAR; PG8_MMA(0, 0, At, B0); PG8_MMA(0, 1, At, B1); PG8_BAR; PG8_SCHED;
;     ...
;         for (int a = 0; a < 2; ++a)
; #pragma unroll
;             for (int b = 0; b < 2; ++b)
; #pragma unroll
;                 for (int m = 0; m < 4; ++m)
; #pragma unroll
;                     for (int n = 0; n < 2; ++n) acc[a][b][m][n] = (f32x4){0.f, 0.f, 0.f, 0.f};
;         cur = nxt; cA = nA; cB = nB; ++ui;
.LBB0_636:
	s_add_u32 s47, s26, 0x100
	v_mov_b32_e32 v2, 0
	s_addc_u32 s48, s27, 0
	s_mov_b32 s49, -2
	s_waitcnt lgkmcnt(0)
	v_mov_b32_e32 v3, v2
	v_mov_b32_e32 v4, v2
	v_mov_b32_e32 v5, v2
	v_mov_b32_e32 v6, v2
	v_mov_b32_e32 v7, v2
	v_mov_b32_e32 v8, v2
	v_mov_b32_e32 v9, v2
	v_mov_b32_e32 v18, v2
	v_mov_b32_e32 v19, v2
	v_mov_b32_e32 v20, v2
	v_mov_b32_e32 v21, v2
	v_mov_b32_e32 v22, v2
	v_mov_b32_e32 v23, v2
	v_mov_b32_e32 v24, v2
	v_mov_b32_e32 v25, v2
	v_mov_b32_e32 v34, v2
	v_mov_b32_e32 v35, v2
	v_mov_b32_e32 v36, v2
	v_mov_b32_e32 v37, v2
	v_mov_b32_e32 v38, v2
	v_mov_b32_e32 v39, v2
	v_mov_b32_e32 v40, v2
	v_mov_b32_e32 v41, v2
	v_mov_b32_e32 v50, v2
	v_mov_b32_e32 v51, v2
	v_mov_b32_e32 v52, v2
	v_mov_b32_e32 v53, v2
	v_mov_b32_e32 v54, v2
	v_mov_b32_e32 v55, v2
	v_mov_b32_e32 v56, v2
	v_mov_b32_e32 v57, v2
	v_mov_b32_e32 v10, v2
	v_mov_b32_e32 v11, v2
	v_mov_b32_e32 v12, v2
	v_mov_b32_e32 v13, v2
	v_mov_b32_e32 v14, v2
	v_mov_b32_e32 v15, v2
	v_mov_b32_e32 v16, v2
	v_mov_b32_e32 v17, v2
	v_mov_b32_e32 v26, v2
	v_mov_b32_e32 v27, v2
	v_mov_b32_e32 v28, v2
	v_mov_b32_e32 v29, v2
	v_mov_b32_e32 v30, v2
	v_mov_b32_e32 v31, v2
	v_mov_b32_e32 v32, v2
	v_mov_b32_e32 v33, v2
	v_mov_b32_e32 v42, v2
	v_mov_b32_e32 v43, v2
	v_mov_b32_e32 v44, v2
	v_mov_b32_e32 v45, v2
	v_mov_b32_e32 v46, v2
	v_mov_b32_e32 v47, v2
	v_mov_b32_e32 v48, v2
	v_mov_b32_e32 v49, v2
	v_mov_b32_e32 v58, v2
	v_mov_b32_e32 v59, v2
	v_mov_b32_e32 v60, v2
	v_mov_b32_e32 v61, v2
	v_mov_b32_e32 v62, v2
	v_mov_b32_e32 v63, v2
	v_mov_b32_e32 v64, v2
	v_mov_b32_e32 v65, v2
	v_mov_b32_e32 v66, v2
	v_mov_b32_e32 v67, v2
	v_mov_b32_e32 v68, v2
	v_mov_b32_e32 v69, v2
	v_mov_b32_e32 v70, v2
	v_mov_b32_e32 v71, v2
	v_mov_b32_e32 v72, v2
	v_mov_b32_e32 v73, v2
	v_mov_b32_e32 v82, v2
	v_mov_b32_e32 v83, v2
	v_mov_b32_e32 v84, v2
	v_mov_b32_e32 v85, v2
	v_mov_b32_e32 v86, v2
	v_mov_b32_e32 v87, v2
	v_mov_b32_e32 v88, v2
	v_mov_b32_e32 v89, v2
	v_mov_b32_e32 v98, v2
	v_mov_b32_e32 v99, v2
	v_mov_b32_e32 v100, v2
	v_mov_b32_e32 v101, v2
	v_mov_b32_e32 v102, v2
	v_mov_b32_e32 v103, v2
	v_mov_b32_e32 v104, v2
	v_mov_b32_e32 v105, v2
	v_mov_b32_e32 v114, v2
	v_mov_b32_e32 v115, v2
	v_mov_b32_e32 v116, v2
	v_mov_b32_e32 v117, v2
	v_mov_b32_e32 v118, v2
	v_mov_b32_e32 v119, v2
	v_mov_b32_e32 v120, v2
	v_mov_b32_e32 v121, v2
	v_mov_b32_e32 v74, v2
	v_mov_b32_e32 v75, v2
	v_mov_b32_e32 v76, v2
	v_mov_b32_e32 v77, v2
	v_mov_b32_e32 v78, v2
	v_mov_b32_e32 v79, v2
	v_mov_b32_e32 v80, v2
	v_mov_b32_e32 v81, v2
	v_mov_b32_e32 v90, v2
	v_mov_b32_e32 v91, v2
	v_mov_b32_e32 v92, v2
	v_mov_b32_e32 v93, v2
	v_mov_b32_e32 v94, v2
	v_mov_b32_e32 v95, v2
	v_mov_b32_e32 v96, v2
	v_mov_b32_e32 v97, v2
	v_mov_b32_e32 v106, v2
	v_mov_b32_e32 v107, v2
	v_mov_b32_e32 v108, v2
	v_mov_b32_e32 v109, v2
	v_mov_b32_e32 v110, v2
	v_mov_b32_e32 v111, v2
	v_mov_b32_e32 v112, v2
	v_mov_b32_e32 v113, v2
	v_mov_b32_e32 v122, v2
	v_mov_b32_e32 v123, v2
	v_mov_b32_e32 v124, v2
	v_mov_b32_e32 v125, v2
	v_mov_b32_e32 v126, v2
	v_mov_b32_e32 v127, v2
	v_mov_b32_e32 v128, v2
	v_mov_b32_e32 v129, v2
	s_mov_b32 s100, 0xfff4ff80
	s_mov_b32 s101, -1
	v_lshl_add_u64 v[220:221], s[24:25], 0, v[186:187]
	v_lshl_add_u64 v[220:221], v[220:221], 0, s[100:101]
	v_lshl_add_u64 v[222:223], s[24:25], 0, v[188:189]
	v_lshl_add_u64 v[222:223], v[222:223], 0, s[100:101]
.LBB0_637:
	ds_read_b128 v[130:133], v208
	ds_read_b128 v[134:137], v208 offset:1024
	ds_read_b128 v[138:141], v208 offset:2048
	ds_read_b128 v[142:145], v208 offset:3072
	ds_read_b128 v[146:149], v209
	ds_read_b128 v[150:153], v209 offset:1024
	ds_read_b128 v[154:157], v209 offset:2048
	ds_read_b128 v[158:161], v209 offset:3072
	s_add_u32 s26, s24, 0x100
	s_addc_u32 s27, s25, 0
	s_cmp_eq_u32 s49, 40
	s_cselect_b32 s31, s11, s27
	s_cselect_b32 s30, s10, s26
	s_cselect_b32 s29, s23, s48
	s_cselect_b32 s28, s22, s47
	v_lshl_add_u64 v[216:217], s[24:25], 0, v[186:187]
	s_add_i32 m0, s1, 0xc000
	ds_read_b128 v[162:165], v210
	ds_read_b128 v[166:169], v210 offset:1024
	ds_read_b128 v[170:173], v210 offset:2048
	ds_read_b128 v[174:177], v210 offset:3072
	ds_read_b128 v[194:197], v210 offset:4096
	ds_read_b128 v[198:201], v210 offset:5120
	ds_read_b128 v[202:205], v210 offset:6144
	ds_read_b128 v[212:215], v210 offset:7168
	global_load_lds_dwordx4 v[216:217], off
	v_lshl_add_u64 v[216:217], s[24:25], 0, v[188:189]
	s_add_i32 m0, s1, 0xe000
	s_nop 0
	global_load_lds_dwordx4 v[216:217], off
	s_mov_b32 m0, s38
	v_lshl_add_u64 v[216:217], v[220:221], 0, s[18:19]
	global_load_lds_dwordx4 v[216:217], off
	s_mov_b32 m0, s39
	v_lshl_add_u64 v[216:217], v[222:223], 0, s[18:19]
	global_load_lds_dwordx4 v[216:217], off
	s_waitcnt vmcnt(10)
	s_waitcnt lgkmcnt(0)
	s_barrier
; #define PG8_STAGE(bufoff, gbase, voff) do { _Pragma("unroll") for (int _i = 0; _i < 2; ++_i) \
;         __builtin_amdgcn_global_load_lds((const unsigned*)((const char*)(gbase) + (voff)[_i]), (PG8_LAS unsigned*)(lds + (bufoff) + ldsw + _i * 8192), 16, 0, 0); } while (0)
; #define PG8_LDA(dst, b, h) do { _Pragma("unroll") for (int m = 0; m < 4; ++m) _Pragma("unroll") for (int k = 0; k < 2; ++k) dst[m][k] = *(const PG8_LAS bf16x8*)(lds + PG8_SA(b, h) + aoff + m * 2048 + k * 1024); } while (0)
; #define PG8_MMA(ai, bj, At, Bt) do { __builtin_amdgcn_s_setprio(1); _Pragma("unroll") for (int m = 0; m < 4; ++m) _Pragma("unroll") for (int n = 0; n < 2; ++n) _Pragma("unroll") for (int k = 0; k < 2; ++k) \
;         acc[ai][bj][m][n] = __builtin_amdgcn_mfma_f32_16x16x32_bf16(Bt[n][k], At[m][k], acc[ai][bj][m][n], 0, 0, 0); __builtin_amdgcn_s_setprio(0); } while (0)
; #define PG8_WAIT_V(n) asm volatile("s_waitcnt vmcnt(" #n ")" ::: "memory")
; #define PG8_WAIT_L(n) asm volatile("s_waitcnt lgkmcnt(" #n ")" ::: "memory")
; #define PG8_BAR __builtin_amdgcn_s_barrier()
; #define PG8_SCHED __builtin_amdgcn_sched_barrier(0)
; template <class Epi, class Sched, bool ALIGN_EPI = false, bool SP2 = false, bool HALFM = false>
; __device__ __forceinline__ void gemm_phase(PG8_LAS unsigned char* lds, const Gemm g, const Sched& S, const Epi& E) {
;     ...
;             PG8_WAIT_V(8); PG8_WAIT_L(0); PG8_BAR; PG8_MMA(0, 0, At, B0); PG8_MMA(0, 1, At, B1); PG8_BAR; PG8_SCHED;
;             PG8_LDA(At, 0, 1); PG8_STAGE(PG8_SB(0, 0), b2, voffB); PG8_STAGE(PG8_SB(0, 1), b2 + hstep, voffB); PG8_STAGE(PG8_SA(0, 0), a2, voffA);
;             PG8_WAIT_V(8); PG8_WAIT_L(0); PG8_BAR; if constexpr (!HALFM) { PG8_MMA(1, 0, At, B0); PG8_MMA(1, 1, At, B1); } PG8_BAR; PG8_SCHED;
	s_setprio 1
	s_waitcnt lgkmcnt(0)
	v_mfma_f32_16x16x32_bf16 v[126:129], v[130:133], v[162:165], v[126:129]
	v_mfma_f32_16x16x32_bf16 v[122:125], v[138:141], v[162:165], v[122:125]
	v_mfma_f32_16x16x32_bf16 v[110:113], v[130:133], v[170:173], v[110:113]
	v_mfma_f32_16x16x32_bf16 v[106:109], v[138:141], v[170:173], v[106:109]
	v_mfma_f32_16x16x32_bf16 v[94:97], v[130:133], v[194:197], v[94:97]
	v_mfma_f32_16x16x32_bf16 v[90:93], v[138:141], v[194:197], v[90:93]
	v_mfma_f32_16x16x32_bf16 v[78:81], v[130:133], v[202:205], v[78:81]
	v_mfma_f32_16x16x32_bf16 v[74:77], v[138:141], v[202:205], v[74:77]
	v_mfma_f32_16x16x32_bf16 v[126:129], v[134:137], v[166:169], v[126:129]
	v_mfma_f32_16x16x32_bf16 v[122:125], v[142:145], v[166:169], v[122:125]
	v_mfma_f32_16x16x32_bf16 v[110:113], v[134:137], v[174:177], v[110:113]
	v_mfma_f32_16x16x32_bf16 v[106:109], v[142:145], v[174:177], v[106:109]
	v_mfma_f32_16x16x32_bf16 v[94:97], v[134:137], v[198:201], v[94:97]
	v_mfma_f32_16x16x32_bf16 v[90:93], v[142:145], v[198:201], v[90:93]
	v_mfma_f32_16x16x32_bf16 v[78:81], v[134:137], v[212:215], v[78:81]
	v_mfma_f32_16x16x32_bf16 v[74:77], v[142:145], v[212:215], v[74:77]
	s_setprio 0
	s_setprio 1
	v_mfma_f32_16x16x32_bf16 v[118:121], v[146:149], v[162:165], v[118:121]
	v_mfma_f32_16x16x32_bf16 v[114:117], v[154:157], v[162:165], v[114:117]
	v_mfma_f32_16x16x32_bf16 v[102:105], v[146:149], v[170:173], v[102:105]
	v_mfma_f32_16x16x32_bf16 v[98:101], v[154:157], v[170:173], v[98:101]
	v_mfma_f32_16x16x32_bf16 v[86:89], v[146:149], v[194:197], v[86:89]
	v_mfma_f32_16x16x32_bf16 v[82:85], v[154:157], v[194:197], v[82:85]
	v_mfma_f32_16x16x32_bf16 v[70:73], v[146:149], v[202:205], v[70:73]
	v_mfma_f32_16x16x32_bf16 v[66:69], v[154:157], v[202:205], v[66:69]
	v_mfma_f32_16x16x32_bf16 v[118:121], v[150:153], v[166:169], v[118:121]
	v_mfma_f32_16x16x32_bf16 v[114:117], v[158:161], v[166:169], v[114:117]
	v_mfma_f32_16x16x32_bf16 v[102:105], v[150:153], v[174:177], v[102:105]
	v_mfma_f32_16x16x32_bf16 v[98:101], v[158:161], v[174:177], v[98:101]
	v_mfma_f32_16x16x32_bf16 v[86:89], v[150:153], v[198:201], v[86:89]
	v_mfma_f32_16x16x32_bf16 v[82:85], v[158:161], v[198:201], v[82:85]
	v_mfma_f32_16x16x32_bf16 v[70:73], v[150:153], v[212:215], v[70:73]
	v_mfma_f32_16x16x32_bf16 v[66:69], v[158:161], v[212:215], v[66:69]
	s_setprio 0
	s_barrier
	s_add_i32 s24, s41, s0
	v_lshl_add_u64 v[216:217], s[28:29], 0, v[180:181]
	s_mov_b32 m0, s24
	ds_read_b128 v[162:165], v210 offset:16384
	ds_read_b128 v[166:169], v210 offset:17408
	ds_read_b128 v[170:173], v210 offset:18432
	ds_read_b128 v[174:177], v210 offset:19456
	ds_read_b128 v[194:197], v210 offset:20480
	ds_read_b128 v[198:201], v210 offset:21504
	ds_read_b128 v[202:205], v210 offset:22528
	ds_read_b128 v[212:215], v210 offset:23552
	global_load_lds_dwordx4 v[216:217], off
	s_add_i32 m0, s24, 0x2000
	s_add_u32 s24, s28, 0xb0000
	v_lshl_add_u64 v[218:219], s[28:29], 0, v[184:185]
	s_addc_u32 s25, s29, 0
	s_add_i32 s50, s42, s0
	global_load_lds_dwordx4 v[218:219], off
	v_lshl_add_u64 v[220:221], s[24:25], 0, v[180:181]
	s_mov_b32 m0, s50
	v_lshl_add_u64 v[222:223], s[30:31], 0, v[182:183]
	global_load_lds_dwordx4 v[220:221], off
	v_lshl_add_u64 v[220:221], s[24:25], 0, v[184:185]
	s_add_i32 m0, s50, 0x2000
	s_nop 0
	global_load_lds_dwordx4 v[220:221], off
	v_lshl_add_u64 v[220:221], s[30:31], 0, v[178:179]
	s_waitcnt vmcnt(4)
	s_waitcnt lgkmcnt(0)
	s_barrier
	s_setprio 1
	s_waitcnt lgkmcnt(0)
	v_mfma_f32_16x16x32_bf16 v[62:65], v[130:133], v[162:165], v[62:65]
	v_mfma_f32_16x16x32_bf16 v[58:61], v[138:141], v[162:165], v[58:61]
	v_mfma_f32_16x16x32_bf16 v[46:49], v[130:133], v[170:173], v[46:49]
	v_mfma_f32_16x16x32_bf16 v[42:45], v[138:141], v[170:173], v[42:45]
	v_mfma_f32_16x16x32_bf16 v[30:33], v[130:133], v[194:197], v[30:33]
	v_mfma_f32_16x16x32_bf16 v[26:29], v[138:141], v[194:197], v[26:29]
	v_mfma_f32_16x16x32_bf16 v[14:17], v[130:133], v[202:205], v[14:17]
	v_mfma_f32_16x16x32_bf16 v[10:13], v[138:141], v[202:205], v[10:13]
	v_mfma_f32_16x16x32_bf16 v[62:65], v[134:137], v[166:169], v[62:65]
	v_mfma_f32_16x16x32_bf16 v[58:61], v[142:145], v[166:169], v[58:61]
	v_mfma_f32_16x16x32_bf16 v[46:49], v[134:137], v[174:177], v[46:49]
	v_mfma_f32_16x16x32_bf16 v[42:45], v[142:145], v[174:177], v[42:45]
	v_mfma_f32_16x16x32_bf16 v[30:33], v[134:137], v[198:201], v[30:33]
	v_mfma_f32_16x16x32_bf16 v[26:29], v[142:145], v[198:201], v[26:29]
	v_mfma_f32_16x16x32_bf16 v[14:17], v[134:137], v[212:215], v[14:17]
	v_mfma_f32_16x16x32_bf16 v[10:13], v[142:145], v[212:215], v[10:13]
	s_setprio 0
	s_setprio 1
	v_mfma_f32_16x16x32_bf16 v[54:57], v[146:149], v[162:165], v[54:57]
	v_mfma_f32_16x16x32_bf16 v[50:53], v[154:157], v[162:165], v[50:53]
	v_mfma_f32_16x16x32_bf16 v[38:41], v[146:149], v[170:173], v[38:41]
	v_mfma_f32_16x16x32_bf16 v[34:37], v[154:157], v[170:173], v[34:37]
	v_mfma_f32_16x16x32_bf16 v[22:25], v[146:149], v[194:197], v[22:25]
	v_mfma_f32_16x16x32_bf16 v[18:21], v[154:157], v[194:197], v[18:21]
	v_mfma_f32_16x16x32_bf16 v[6:9], v[146:149], v[202:205], v[6:9]
	v_mfma_f32_16x16x32_bf16 v[2:5], v[154:157], v[202:205], v[2:5]
	v_mfma_f32_16x16x32_bf16 v[54:57], v[150:153], v[166:169], v[54:57]
	v_mfma_f32_16x16x32_bf16 v[50:53], v[158:161], v[166:169], v[50:53]
	v_mfma_f32_16x16x32_bf16 v[38:41], v[150:153], v[174:177], v[38:41]
	v_mfma_f32_16x16x32_bf16 v[34:37], v[158:161], v[174:177], v[34:37]
	v_mfma_f32_16x16x32_bf16 v[22:25], v[150:153], v[198:201], v[22:25]
	v_mfma_f32_16x16x32_bf16 v[18:21], v[158:161], v[198:201], v[18:21]
	v_mfma_f32_16x16x32_bf16 v[6:9], v[150:153], v[212:215], v[6:9]
	v_mfma_f32_16x16x32_bf16 v[2:5], v[158:161], v[212:215], v[2:5]
	s_setprio 0
	s_barrier
; #define PG8_STAGE(bufoff, gbase, voff) do { _Pragma("unroll") for (int _i = 0; _i < 2; ++_i) \
;         __builtin_amdgcn_global_load_lds((const unsigned*)((const char*)(gbase) + (voff)[_i]), (PG8_LAS unsigned*)(lds + (bufoff) + ldsw + _i * 8192), 16, 0, 0); } while (0)
; #define PG8_LDA(dst, b, h) do { _Pragma("unroll") for (int m = 0; m < 4; ++m) _Pragma("unroll") for (int k = 0; k < 2; ++k) dst[m][k] = *(const PG8_LAS bf16x8*)(lds + PG8_SA(b, h) + aoff + m * 2048 + k * 1024); } while (0)
; #define PG8_LDB(dst, b, h) do { _Pragma("unroll") for (int n = 0; n < 2; ++n) _Pragma("unroll") for (int k = 0; k < 2; ++k) dst[n][k] = *(const PG8_LAS bf16x8*)(lds + PG8_SB(b, h) + boff + n * 2048 + k * 1024); } while (0)
; #define PG8_MMA(ai, bj, At, Bt) do { __builtin_amdgcn_s_setprio(1); _Pragma("unroll") for (int m = 0; m < 4; ++m) _Pragma("unroll") for (int n = 0; n < 2; ++n) _Pragma("unroll") for (int k = 0; k < 2; ++k) \
;         acc[ai][bj][m][n] = __builtin_amdgcn_mfma_f32_16x16x32_bf16(Bt[n][k], At[m][k], acc[ai][bj][m][n], 0, 0, 0); __builtin_amdgcn_s_setprio(0); } while (0)
; #define PG8_WAIT_V(n) asm volatile("s_waitcnt vmcnt(" #n ")" ::: "memory")
; #define PG8_WAIT_L(n) asm volatile("s_waitcnt lgkmcnt(" #n ")" ::: "memory")
; #define PG8_BAR __builtin_amdgcn_s_barrier()
; #define PG8_SCHED __builtin_amdgcn_sched_barrier(0)
; template <class Epi, class Sched, bool ALIGN_EPI = false, bool SP2 = false, bool HALFM = false>
; __device__ __forceinline__ void gemm_phase(PG8_LAS unsigned char* lds, const Gemm g, const Sched& S, const Epi& E) {
;     ...
;             PG8_LDB(B0, 1, 0); PG8_LDB(B1, 1, 1); PG8_SCHED; PG8_LDA(At, 1, 0); PG8_STAGE(PG8_SA(0, 1), a2 + hstep, voffA);
;             PG8_WAIT_V(8); PG8_WAIT_L(0); PG8_BAR; PG8_MMA(0, 0, At, B0); PG8_MMA(0, 1, At, B1); PG8_BAR; PG8_SCHED;
	s_add_i32 s50, 0, 0x18000
	s_add_i32 s51, 0, 0x1c000
	v_add_u32_e32 v142, s50, v206
	v_add_u32_e32 v158, s51, v206
	ds_read_b128 v[130:133], v142
	ds_read_b128 v[134:137], v142 offset:1024
	ds_read_b128 v[138:141], v142 offset:2048
	ds_read_b128 v[142:145], v142 offset:3072
	ds_read_b128 v[146:149], v158
	ds_read_b128 v[150:153], v158 offset:1024
	ds_read_b128 v[154:157], v158 offset:2048
	ds_read_b128 v[158:161], v158 offset:3072
	s_add_u32 s24, s30, 0xb0000
	s_addc_u32 s25, s31, 0
	s_mov_b32 m0, s3
	v_lshl_add_u64 v[224:225], s[24:25], 0, v[178:179]
	ds_read_b128 v[162:165], v210 offset:32768
	ds_read_b128 v[166:169], v210 offset:33792
	ds_read_b128 v[170:173], v210 offset:34816
	ds_read_b128 v[174:177], v210 offset:35840
	ds_read_b128 v[194:197], v210 offset:36864
	ds_read_b128 v[198:201], v210 offset:37888
	ds_read_b128 v[202:205], v210 offset:38912
	ds_read_b128 v[212:215], v210 offset:39936
	global_load_lds_dwordx4 v[224:225], off
	v_lshl_add_u64 v[224:225], s[24:25], 0, v[182:183]
	s_mov_b32 m0, s36
	s_nop 0
	global_load_lds_dwordx4 v[224:225], off
	s_mov_b32 m0, s1
	s_nop 0
	global_load_lds_dwordx4 v[220:221], off
	s_mov_b32 m0, s2
	s_nop 0
	global_load_lds_dwordx4 v[222:223], off
	s_waitcnt vmcnt(10)
	s_waitcnt lgkmcnt(0)
	s_barrier
	s_setprio 1
	s_waitcnt lgkmcnt(0)
	v_mfma_f32_16x16x32_bf16 v[126:129], v[130:133], v[162:165], v[126:129]
	v_mfma_f32_16x16x32_bf16 v[122:125], v[138:141], v[162:165], v[122:125]
	v_mfma_f32_16x16x32_bf16 v[110:113], v[130:133], v[170:173], v[110:113]
	v_mfma_f32_16x16x32_bf16 v[106:109], v[138:141], v[170:173], v[106:109]
	v_mfma_f32_16x16x32_bf16 v[94:97], v[130:133], v[194:197], v[94:97]
	v_mfma_f32_16x16x32_bf16 v[90:93], v[138:141], v[194:197], v[90:93]
	v_mfma_f32_16x16x32_bf16 v[78:81], v[130:133], v[202:205], v[78:81]
	v_mfma_f32_16x16x32_bf16 v[74:77], v[138:141], v[202:205], v[74:77]
	v_mfma_f32_16x16x32_bf16 v[126:129], v[134:137], v[166:169], v[126:129]
	v_mfma_f32_16x16x32_bf16 v[122:125], v[142:145], v[166:169], v[122:125]
	v_mfma_f32_16x16x32_bf16 v[110:113], v[134:137], v[174:177], v[110:113]
	v_mfma_f32_16x16x32_bf16 v[106:109], v[142:145], v[174:177], v[106:109]
	v_mfma_f32_16x16x32_bf16 v[94:97], v[134:137], v[198:201], v[94:97]
	v_mfma_f32_16x16x32_bf16 v[90:93], v[142:145], v[198:201], v[90:93]
	v_mfma_f32_16x16x32_bf16 v[78:81], v[134:137], v[212:215], v[78:81]
	v_mfma_f32_16x16x32_bf16 v[74:77], v[142:145], v[212:215], v[74:77]
	s_setprio 0
	s_setprio 1
	v_mfma_f32_16x16x32_bf16 v[118:121], v[146:149], v[162:165], v[118:121]
	v_mfma_f32_16x16x32_bf16 v[114:117], v[154:157], v[162:165], v[114:117]
	v_mfma_f32_16x16x32_bf16 v[102:105], v[146:149], v[170:173], v[102:105]
	v_mfma_f32_16x16x32_bf16 v[98:101], v[154:157], v[170:173], v[98:101]
	v_mfma_f32_16x16x32_bf16 v[86:89], v[146:149], v[194:197], v[86:89]
	v_mfma_f32_16x16x32_bf16 v[82:85], v[154:157], v[194:197], v[82:85]
	v_mfma_f32_16x16x32_bf16 v[70:73], v[146:149], v[202:205], v[70:73]
	v_mfma_f32_16x16x32_bf16 v[66:69], v[154:157], v[202:205], v[66:69]
	v_mfma_f32_16x16x32_bf16 v[118:121], v[150:153], v[166:169], v[118:121]
	v_mfma_f32_16x16x32_bf16 v[114:117], v[158:161], v[166:169], v[114:117]
	v_mfma_f32_16x16x32_bf16 v[102:105], v[150:153], v[174:177], v[102:105]
	v_mfma_f32_16x16x32_bf16 v[98:101], v[158:161], v[174:177], v[98:101]
	v_mfma_f32_16x16x32_bf16 v[86:89], v[150:153], v[198:201], v[86:89]
	v_mfma_f32_16x16x32_bf16 v[82:85], v[158:161], v[198:201], v[82:85]
	v_mfma_f32_16x16x32_bf16 v[70:73], v[150:153], v[212:215], v[70:73]
	v_mfma_f32_16x16x32_bf16 v[66:69], v[158:161], v[212:215], v[66:69]
	s_setprio 0
	s_barrier
; #define PG8_STAGE(bufoff, gbase, voff) do { _Pragma("unroll") for (int _i = 0; _i < 2; ++_i) \
;         __builtin_amdgcn_global_load_lds((const unsigned*)((const char*)(gbase) + (voff)[_i]), (PG8_LAS unsigned*)(lds + (bufoff) + ldsw + _i * 8192), 16, 0, 0); } while (0)
; #define PG8_LDA(dst, b, h) do { _Pragma("unroll") for (int m = 0; m < 4; ++m) _Pragma("unroll") for (int k = 0; k < 2; ++k) dst[m][k] = *(const PG8_LAS bf16x8*)(lds + PG8_SA(b, h) + aoff + m * 2048 + k * 1024); } while (0)
; #define PG8_MMA(ai, bj, At, Bt) do { __builtin_amdgcn_s_setprio(1); _Pragma("unroll") for (int m = 0; m < 4; ++m) _Pragma("unroll") for (int n = 0; n < 2; ++n) _Pragma("unroll") for (int k = 0; k < 2; ++k) \
;         acc[ai][bj][m][n] = __builtin_amdgcn_mfma_f32_16x16x32_bf16(Bt[n][k], At[m][k], acc[ai][bj][m][n], 0, 0, 0); __builtin_amdgcn_s_setprio(0); } while (0)
; #define PG8_WAIT_V(n) asm volatile("s_waitcnt vmcnt(" #n ")" ::: "memory")
; #define PG8_WAIT_L(n) asm volatile("s_waitcnt lgkmcnt(" #n ")" ::: "memory")
; #define PG8_BAR __builtin_amdgcn_s_barrier()
; #define PG8_SCHED __builtin_amdgcn_sched_barrier(0)
; template <class Epi, class Sched, bool ALIGN_EPI = false, bool SP2 = false, bool HALFM = false>
; __device__ __forceinline__ void gemm_phase(PG8_LAS unsigned char* lds, const Gemm g, const Sched& S, const Epi& E) {
;     ...
;             PG8_LDA(At, 1, 1); PG8_STAGE(PG8_SB(1, 0), b3, voffB); PG8_STAGE(PG8_SB(1, 1), b3 + hstep, voffB); PG8_STAGE(PG8_SA(1, 0), a3, voffA);
;             PG8_WAIT_V(8); PG8_WAIT_L(0); PG8_BAR; if constexpr (!HALFM) { PG8_MMA(1, 0, At, B0); PG8_MMA(1, 1, At, B1); } PG8_BAR; PG8_SCHED;
	s_add_i32 s24, s50, s0
	v_lshl_add_u64 v[216:217], v[216:217], 0, s[18:19]
	s_mov_b32 m0, s24
	ds_read_b128 v[162:165], v210 offset:49152
	ds_read_b128 v[166:169], v210 offset:50176
	ds_read_b128 v[170:173], v210 offset:51200
	ds_read_b128 v[174:177], v210 offset:52224
	ds_read_b128 v[194:197], v210 offset:53248
	ds_read_b128 v[198:201], v210 offset:54272
	ds_read_b128 v[202:205], v210 offset:55296
	ds_read_b128 v[212:215], v210 offset:56320
	global_load_lds_dwordx4 v[216:217], off
	s_add_i32 m0, s24, 0x2000
	s_add_u32 s24, s28, 0xb0080
	v_lshl_add_u64 v[216:217], v[218:219], 0, s[18:19]
	s_addc_u32 s25, s29, 0
	s_add_i32 s28, s51, s0
	global_load_lds_dwordx4 v[216:217], off
	v_lshl_add_u64 v[216:217], s[24:25], 0, v[180:181]
	s_mov_b32 m0, s28
	s_nop 0
	global_load_lds_dwordx4 v[216:217], off
	v_lshl_add_u64 v[216:217], s[24:25], 0, v[184:185]
	s_add_i32 m0, s28, 0x2000
	s_nop 0
	global_load_lds_dwordx4 v[216:217], off
	s_waitcnt vmcnt(4)
	s_waitcnt lgkmcnt(0)
	s_barrier
	s_setprio 1
	s_waitcnt lgkmcnt(0)
	v_mfma_f32_16x16x32_bf16 v[62:65], v[130:133], v[162:165], v[62:65]
	v_mfma_f32_16x16x32_bf16 v[58:61], v[138:141], v[162:165], v[58:61]
	v_mfma_f32_16x16x32_bf16 v[46:49], v[130:133], v[170:173], v[46:49]
	v_mfma_f32_16x16x32_bf16 v[42:45], v[138:141], v[170:173], v[42:45]
	v_mfma_f32_16x16x32_bf16 v[30:33], v[130:133], v[194:197], v[30:33]
	v_mfma_f32_16x16x32_bf16 v[26:29], v[138:141], v[194:197], v[26:29]
	v_mfma_f32_16x16x32_bf16 v[14:17], v[130:133], v[202:205], v[14:17]
	v_mfma_f32_16x16x32_bf16 v[10:13], v[138:141], v[202:205], v[10:13]
	v_mfma_f32_16x16x32_bf16 v[62:65], v[134:137], v[166:169], v[62:65]
	v_mfma_f32_16x16x32_bf16 v[58:61], v[142:145], v[166:169], v[58:61]
	v_mfma_f32_16x16x32_bf16 v[46:49], v[134:137], v[174:177], v[46:49]
	v_mfma_f32_16x16x32_bf16 v[42:45], v[142:145], v[174:177], v[42:45]
	v_mfma_f32_16x16x32_bf16 v[30:33], v[134:137], v[198:201], v[30:33]
	v_mfma_f32_16x16x32_bf16 v[26:29], v[142:145], v[198:201], v[26:29]
	v_mfma_f32_16x16x32_bf16 v[14:17], v[134:137], v[212:215], v[14:17]
	v_mfma_f32_16x16x32_bf16 v[10:13], v[142:145], v[212:215], v[10:13]
	s_setprio 0
	s_setprio 1
	v_mfma_f32_16x16x32_bf16 v[54:57], v[146:149], v[162:165], v[54:57]
	v_mfma_f32_16x16x32_bf16 v[50:53], v[154:157], v[162:165], v[50:53]
	v_mfma_f32_16x16x32_bf16 v[38:41], v[146:149], v[170:173], v[38:41]
	v_mfma_f32_16x16x32_bf16 v[34:37], v[154:157], v[170:173], v[34:37]
	v_mfma_f32_16x16x32_bf16 v[22:25], v[146:149], v[194:197], v[22:25]
	v_mfma_f32_16x16x32_bf16 v[18:21], v[154:157], v[194:197], v[18:21]
	v_mfma_f32_16x16x32_bf16 v[6:9], v[146:149], v[202:205], v[6:9]
	v_mfma_f32_16x16x32_bf16 v[2:5], v[154:157], v[202:205], v[2:5]
	v_mfma_f32_16x16x32_bf16 v[54:57], v[150:153], v[166:169], v[54:57]
	v_mfma_f32_16x16x32_bf16 v[50:53], v[158:161], v[166:169], v[50:53]
	v_mfma_f32_16x16x32_bf16 v[38:41], v[150:153], v[174:177], v[38:41]
	v_mfma_f32_16x16x32_bf16 v[34:37], v[158:161], v[174:177], v[34:37]
	v_mfma_f32_16x16x32_bf16 v[22:25], v[150:153], v[198:201], v[22:25]
	v_mfma_f32_16x16x32_bf16 v[18:21], v[158:161], v[198:201], v[18:21]
	v_mfma_f32_16x16x32_bf16 v[6:9], v[150:153], v[212:215], v[6:9]
	v_mfma_f32_16x16x32_bf16 v[2:5], v[158:161], v[212:215], v[2:5]
	s_setprio 0
	s_barrier
	s_add_i32 s49, s49, 2
	s_add_u32 s47, s47, 0x100
	s_addc_u32 s48, s48, 0
	s_cmp_gt_u32 s49, 41
	s_mov_b64 s[24:25], s[26:27]
	s_cbranch_scc0 .LBB0_637
	s_and_b64 vcc, exec, s[20:21]
	s_cbranch_vccz .LBB0_640
	s_barrier

;     __device__ __forceinline__ bool next(int i, Unit& u) const { const int L = L0 + i * G + c; if (L >= L1) return false; u.pm = L >> 2; u.pn = L & 3; u.ko = 0; return true; }
; template <class Epi, class Sched, bool ALIGN_EPI = false, bool SP2 = false, bool HALFM = false>
; __device__ __forceinline__ void gemm_phase(PG8_LAS unsigned char* lds, const Gemm g, const Sched& S, const Epi& E) {
;     ...
;         const bool has_next = S.next(ui + 1, nxt);
;         const char* nA = has_next ? (const char*)g.A + (size_t)nxt.pm * tstep + (size_t)nxt.ko * 2 : cA; const char* nB = has_next ? (const char*)g.Bt + (size_t)nxt.pn * tstep + (size_t)nxt.ko * 2 : cB;
;     ...
;         for (int a = 0; a < 2; ++a)
; #pragma unroll
;             for (int b = 0; b < 2; ++b)
; #pragma unroll
;                 for (int m = 0; m < 4; ++m)
; #pragma unroll
;                     for (int n = 0; n < 2; ++n) acc[a][b][m][n] = (f32x4){0.f, 0.f, 0.f, 0.f};
;         cur = nxt; cA = nA; cB = nB; ++ui;
.LBB0_751:
	s_ashr_i32 s31, s30, 31
	s_lshl_b64 s[0:1], s[30:31], 19
	s_add_u32 s34, s80, s0
	s_addc_u32 s35, s81, s1
	s_and_b64 s[0:1], s[6:7], exec
	s_cselect_b32 s0, s35, s9
	s_cselect_b32 s1, s34, s8
	s_ashr_i32 s29, s28, 31
	s_lshl_b64 s[2:3], s[28:29], 19
	s_add_u32 s36, s46, s2
	s_addc_u32 s37, s47, s3
	s_and_b64 s[2:3], s[6:7], exec
	s_cselect_b32 s2, s37, s39
	s_cselect_b32 s3, s36, s38
	s_add_u32 s8, s8, 0x40080
	s_addc_u32 s9, s9, 0
	s_add_u32 s5, s38, 0x100
	v_mov_b32_e32 v2, 0
	s_addc_u32 s11, s39, 0
	s_mov_b32 s29, -2
	v_mov_b32_e32 v3, v2
	v_mov_b32_e32 v4, v2
	v_mov_b32_e32 v5, v2
	v_mov_b32_e32 v6, v2
	v_mov_b32_e32 v7, v2
	v_mov_b32_e32 v8, v2
	v_mov_b32_e32 v9, v2
	v_mov_b32_e32 v18, v2
	v_mov_b32_e32 v19, v2
	v_mov_b32_e32 v20, v2
	v_mov_b32_e32 v21, v2
	v_mov_b32_e32 v22, v2
	v_mov_b32_e32 v23, v2
	v_mov_b32_e32 v24, v2
	v_mov_b32_e32 v25, v2
	v_mov_b32_e32 v34, v2
	v_mov_b32_e32 v35, v2
	v_mov_b32_e32 v36, v2
	v_mov_b32_e32 v37, v2
	v_mov_b32_e32 v38, v2
	v_mov_b32_e32 v39, v2
	v_mov_b32_e32 v40, v2
	v_mov_b32_e32 v41, v2
	v_mov_b32_e32 v50, v2
	v_mov_b32_e32 v51, v2
	v_mov_b32_e32 v52, v2
	v_mov_b32_e32 v53, v2
	v_mov_b32_e32 v54, v2
	v_mov_b32_e32 v55, v2
	v_mov_b32_e32 v56, v2
	v_mov_b32_e32 v57, v2
	v_mov_b32_e32 v10, v2
	v_mov_b32_e32 v11, v2
	v_mov_b32_e32 v12, v2
	v_mov_b32_e32 v13, v2
	v_mov_b32_e32 v14, v2
	v_mov_b32_e32 v15, v2
	v_mov_b32_e32 v16, v2
	v_mov_b32_e32 v17, v2
	v_mov_b32_e32 v26, v2
	v_mov_b32_e32 v27, v2
	v_mov_b32_e32 v28, v2
	v_mov_b32_e32 v29, v2
	v_mov_b32_e32 v30, v2
	v_mov_b32_e32 v31, v2
	v_mov_b32_e32 v32, v2
	v_mov_b32_e32 v33, v2
	v_mov_b32_e32 v42, v2
	v_mov_b32_e32 v43, v2
	v_mov_b32_e32 v44, v2
	v_mov_b32_e32 v45, v2
	v_mov_b32_e32 v46, v2
	v_mov_b32_e32 v47, v2
	v_mov_b32_e32 v48, v2
	v_mov_b32_e32 v49, v2
	v_mov_b32_e32 v58, v2
	v_mov_b32_e32 v59, v2
	v_mov_b32_e32 v60, v2
	v_mov_b32_e32 v61, v2
	v_mov_b32_e32 v62, v2
	v_mov_b32_e32 v63, v2
	v_mov_b32_e32 v64, v2
	v_mov_b32_e32 v65, v2
	v_mov_b32_e32 v66, v2
	v_mov_b32_e32 v67, v2
	v_mov_b32_e32 v68, v2
	v_mov_b32_e32 v69, v2
	v_mov_b32_e32 v70, v2
	v_mov_b32_e32 v71, v2
	v_mov_b32_e32 v72, v2
	v_mov_b32_e32 v73, v2
	v_mov_b32_e32 v86, v2
	v_mov_b32_e32 v87, v2
	v_mov_b32_e32 v88, v2
	v_mov_b32_e32 v89, v2
	v_mov_b32_e32 v90, v2
	v_mov_b32_e32 v91, v2
	v_mov_b32_e32 v92, v2
	v_mov_b32_e32 v93, v2
	v_mov_b32_e32 v102, v2
	v_mov_b32_e32 v103, v2
	v_mov_b32_e32 v104, v2
	v_mov_b32_e32 v105, v2
	v_mov_b32_e32 v106, v2
	v_mov_b32_e32 v107, v2
	v_mov_b32_e32 v108, v2
	v_mov_b32_e32 v109, v2
	v_mov_b32_e32 v118, v2
	v_mov_b32_e32 v119, v2
	v_mov_b32_e32 v120, v2
	v_mov_b32_e32 v121, v2
	v_mov_b32_e32 v122, v2
	v_mov_b32_e32 v123, v2
	v_mov_b32_e32 v124, v2
	v_mov_b32_e32 v125, v2
	v_mov_b32_e32 v74, v2
	v_mov_b32_e32 v75, v2
	v_mov_b32_e32 v76, v2
	v_mov_b32_e32 v77, v2
	v_mov_b32_e32 v78, v2
	v_mov_b32_e32 v79, v2
	v_mov_b32_e32 v80, v2
	v_mov_b32_e32 v81, v2
	v_mov_b32_e32 v94, v2
	v_mov_b32_e32 v95, v2
	v_mov_b32_e32 v96, v2
	v_mov_b32_e32 v97, v2
	v_mov_b32_e32 v98, v2
	v_mov_b32_e32 v99, v2
	v_mov_b32_e32 v100, v2
	v_mov_b32_e32 v101, v2
	v_mov_b32_e32 v110, v2
	v_mov_b32_e32 v111, v2
	v_mov_b32_e32 v112, v2
	v_mov_b32_e32 v113, v2
	v_mov_b32_e32 v114, v2
	v_mov_b32_e32 v115, v2
	v_mov_b32_e32 v116, v2
	v_mov_b32_e32 v117, v2
	v_mov_b32_e32 v126, v2
	v_mov_b32_e32 v127, v2
	v_mov_b32_e32 v128, v2
	v_mov_b32_e32 v129, v2
	v_mov_b32_e32 v130, v2
	v_mov_b32_e32 v131, v2
	v_mov_b32_e32 v132, v2
	v_mov_b32_e32 v133, v2
	s_mov_b32 s100, 0xfffbff80
	s_mov_b32 s101, -1
	v_lshl_add_u64 v[228:229], s[8:9], 0, v[152:153]
	v_lshl_add_u64 v[228:229], v[228:229], 0, s[100:101]
	v_lshl_add_u64 v[230:231], s[8:9], 0, v[154:155]
	v_lshl_add_u64 v[230:231], v[230:231], 0, s[100:101]

;     __device__ __forceinline__ bool next(int i, Unit& u) const { const int L = L0 + i * G + c; if (L >= L1) return false; u.pm = L >> 2; u.pn = L & 3; u.ko = 0; return true; }
; #define PG8_STAGE(bufoff, gbase, voff) do { _Pragma("unroll") for (int _i = 0; _i < 2; ++_i) \
;         __builtin_amdgcn_global_load_lds((const unsigned*)((const char*)(gbase) + (voff)[_i]), (PG8_LAS unsigned*)(lds + (bufoff) + ldsw + _i * 8192), 16, 0, 0); } while (0)
; #define PG8_LDA(dst, b, h) do { _Pragma("unroll") for (int m = 0; m < 4; ++m) _Pragma("unroll") for (int k = 0; k < 2; ++k) dst[m][k] = *(const PG8_LAS bf16x8*)(lds + PG8_SA(b, h) + aoff + m * 2048 + k * 1024); } while (0)
; #define PG8_LDB(dst, b, h) do { _Pragma("unroll") for (int n = 0; n < 2; ++n) _Pragma("unroll") for (int k = 0; k < 2; ++k) dst[n][k] = *(const PG8_LAS bf16x8*)(lds + PG8_SB(b, h) + boff + n * 2048 + k * 1024); } while (0)
; template <class Epi, class Sched, bool ALIGN_EPI = false, bool SP2 = false, bool HALFM = false>
; __device__ __forceinline__ void gemm_phase(PG8_LAS unsigned char* lds, const Gemm g, const Sched& S, const Epi& E) {
;     ...
;         const bool has_next = S.next(ui + 1, nxt);
;         const char* nA = has_next ? (const char*)g.A + (size_t)nxt.pm * tstep + (size_t)nxt.ko * 2 : cA; const char* nB = has_next ? (const char*)g.Bt + (size_t)nxt.pn * tstep + (size_t)nxt.ko * 2 : cB;
;         for (int t = 0; t < nt; t += 2) {
;             const bool last = (t == nt - 2);
;             const char* a1 = cA + (size_t)(t + 1) * kstep;
;             const char* a2 = last ? nA : cA + (size_t)(t + 2) * kstep; const char* b2 = last ? nB : cB + (size_t)(t + 2) * kstep;
;             const char* a3 = a2 + kstep; const char* b3 = b2 + kstep;
;             if (last && has_next) S.a_ready(nxt);
;             if constexpr (SP2) {
;             PG8_LDB(B0, 0, 0); PG8_LDB(B1, 0, 1); PG8_SCHED; PG8_LDA(At, 0, 0); PG8_STAGE(PG8_SA(1, 1), a1 + hstep, voffA);
;             PG8_WAIT_V(8); PG8_WAIT_L(0); PG8_BAR; PG8_MMA(0, 0, At, B0); PG8_MMA(0, 1, At, B1); PG8_BAR; PG8_SCHED;
;     ...
;         for (int a = 0; a < 2; ++a)
; #pragma unroll
;             for (int b = 0; b < 2; ++b)
; #pragma unroll
;                 for (int m = 0; m < 4; ++m)
; #pragma unroll
;                     for (int n = 0; n < 2; ++n) acc[a][b][m][n] = (f32x4){0.f, 0.f, 0.f, 0.f};
;         cur = nxt; cA = nA; cB = nB; ++ui;
.LBB0_1509:
	s_ashr_i32 s35, s34, 31
	s_lshl_b64 s[36:37], s[34:35], 20
	s_add_u32 s36, s52, s36
	s_addc_u32 s37, s53, s37
	s_and_b64 s[38:39], s[6:7], exec
	s_cselect_b32 s35, s37, s41
	s_cselect_b32 s57, s36, s40
	s_ashr_i32 s31, s30, 31
	s_lshl_b64 s[38:39], s[30:31], 20
	s_add_u32 s38, s54, s38
	s_addc_u32 s39, s55, s39
	s_and_b64 s[44:45], s[6:7], exec
	s_cselect_b32 s31, s39, s43
	s_cselect_b32 s58, s38, s42
	s_add_u32 s40, s40, 0x80080
	s_addc_u32 s41, s41, 0
	s_add_u32 s59, s42, 0x100
	v_mov_b32_e32 v2, 0
	s_addc_u32 s60, s43, 0
	s_mov_b32 s61, -2
	v_mov_b32_e32 v3, v2
	v_mov_b32_e32 v4, v2
	v_mov_b32_e32 v5, v2
	v_mov_b32_e32 v6, v2
	v_mov_b32_e32 v7, v2
	v_mov_b32_e32 v8, v2
	v_mov_b32_e32 v9, v2
	v_mov_b32_e32 v14, v2
	v_mov_b32_e32 v15, v2
	v_mov_b32_e32 v16, v2
	v_mov_b32_e32 v17, v2
	v_mov_b32_e32 v22, v2
	v_mov_b32_e32 v23, v2
	v_mov_b32_e32 v24, v2
	v_mov_b32_e32 v25, v2
	v_mov_b32_e32 v30, v2
	v_mov_b32_e32 v31, v2
	v_mov_b32_e32 v32, v2
	v_mov_b32_e32 v33, v2
	v_mov_b32_e32 v38, v2
	v_mov_b32_e32 v39, v2
	v_mov_b32_e32 v40, v2
	v_mov_b32_e32 v41, v2
	v_mov_b32_e32 v46, v2
	v_mov_b32_e32 v47, v2
	v_mov_b32_e32 v48, v2
	v_mov_b32_e32 v49, v2
	v_mov_b32_e32 v54, v2
	v_mov_b32_e32 v55, v2
	v_mov_b32_e32 v56, v2
	v_mov_b32_e32 v57, v2
	v_mov_b32_e32 v10, v2
	v_mov_b32_e32 v11, v2
	v_mov_b32_e32 v12, v2
	v_mov_b32_e32 v13, v2
	v_mov_b32_e32 v18, v2
	v_mov_b32_e32 v19, v2
	v_mov_b32_e32 v20, v2
	v_mov_b32_e32 v21, v2
	v_mov_b32_e32 v26, v2
	v_mov_b32_e32 v27, v2
	v_mov_b32_e32 v28, v2
	v_mov_b32_e32 v29, v2
	v_mov_b32_e32 v34, v2
	v_mov_b32_e32 v35, v2
	v_mov_b32_e32 v36, v2
	v_mov_b32_e32 v37, v2
	v_mov_b32_e32 v42, v2
	v_mov_b32_e32 v43, v2
	v_mov_b32_e32 v44, v2
	v_mov_b32_e32 v45, v2
	v_mov_b32_e32 v50, v2
	v_mov_b32_e32 v51, v2
	v_mov_b32_e32 v52, v2
	v_mov_b32_e32 v53, v2
	v_mov_b32_e32 v58, v2
	v_mov_b32_e32 v59, v2
	v_mov_b32_e32 v60, v2
	v_mov_b32_e32 v61, v2
	v_mov_b32_e32 v62, v2
	v_mov_b32_e32 v63, v2
	v_mov_b32_e32 v64, v2
	v_mov_b32_e32 v65, v2
	v_mov_b32_e32 v66, v2
	v_mov_b32_e32 v67, v2
	v_mov_b32_e32 v68, v2
	v_mov_b32_e32 v69, v2
	v_mov_b32_e32 v70, v2
	v_mov_b32_e32 v71, v2
	v_mov_b32_e32 v72, v2
	v_mov_b32_e32 v73, v2
	v_mov_b32_e32 v78, v2
	v_mov_b32_e32 v79, v2
	v_mov_b32_e32 v80, v2
	v_mov_b32_e32 v81, v2
	v_mov_b32_e32 v86, v2
	v_mov_b32_e32 v87, v2
	v_mov_b32_e32 v88, v2
	v_mov_b32_e32 v89, v2
	v_mov_b32_e32 v94, v2
	v_mov_b32_e32 v95, v2
	v_mov_b32_e32 v96, v2
	v_mov_b32_e32 v97, v2
	v_mov_b32_e32 v102, v2
	v_mov_b32_e32 v103, v2
	v_mov_b32_e32 v104, v2
	v_mov_b32_e32 v105, v2
	v_mov_b32_e32 v110, v2
	v_mov_b32_e32 v111, v2
	v_mov_b32_e32 v112, v2
	v_mov_b32_e32 v113, v2
	v_mov_b32_e32 v118, v2
	v_mov_b32_e32 v119, v2
	v_mov_b32_e32 v120, v2
	v_mov_b32_e32 v121, v2
	v_mov_b32_e32 v74, v2
	v_mov_b32_e32 v75, v2
	v_mov_b32_e32 v76, v2
	v_mov_b32_e32 v77, v2
	v_mov_b32_e32 v82, v2
	v_mov_b32_e32 v83, v2
	v_mov_b32_e32 v84, v2
	v_mov_b32_e32 v85, v2
	v_mov_b32_e32 v90, v2
	v_mov_b32_e32 v91, v2
	v_mov_b32_e32 v92, v2
	v_mov_b32_e32 v93, v2
	v_mov_b32_e32 v98, v2
	v_mov_b32_e32 v99, v2
	v_mov_b32_e32 v100, v2
	v_mov_b32_e32 v101, v2
	v_mov_b32_e32 v106, v2
	v_mov_b32_e32 v107, v2
	v_mov_b32_e32 v108, v2
	v_mov_b32_e32 v109, v2
	v_mov_b32_e32 v114, v2
	v_mov_b32_e32 v115, v2
	v_mov_b32_e32 v116, v2
	v_mov_b32_e32 v117, v2
	v_mov_b32_e32 v122, v2
	v_mov_b32_e32 v123, v2
	v_mov_b32_e32 v124, v2
	v_mov_b32_e32 v125, v2
	v_mov_b32_e32 v126, v2
	v_mov_b32_e32 v127, v2
	v_mov_b32_e32 v128, v2
	v_mov_b32_e32 v129, v2
	s_mov_b32 s100, 0xfff7ff80
	s_mov_b32 s101, -1
	v_lshl_add_u64 v[220:221], s[40:41], 0, v[174:175]
	v_lshl_add_u64 v[220:221], v[220:221], 0, s[100:101]
	v_lshl_add_u64 v[222:223], s[40:41], 0, v[176:177]
	v_lshl_add_u64 v[222:223], v[222:223], 0, s[100:101]
.LBB0_1510:
	ds_read_b128 v[130:133], v196
	ds_read_b128 v[134:137], v196 offset:1024
	ds_read_b128 v[138:141], v196 offset:2048
	ds_read_b128 v[142:145], v196 offset:3072
	ds_read_b128 v[146:149], v197
	ds_read_b128 v[150:153], v197 offset:1024
	ds_read_b128 v[154:157], v197 offset:2048
	ds_read_b128 v[158:161], v197 offset:3072
	s_add_u32 s42, s40, 0xfff80080
	s_addc_u32 s43, s41, -1
	s_cmp_eq_u32 s61, 28
	s_cselect_b32 s45, s35, s43
	s_cselect_b32 s44, s57, s42
	s_cselect_b32 s43, s31, s60
	s_cselect_b32 s42, s58, s59
	v_lshl_add_u64 v[216:217], s[40:41], 0, v[174:175]
	s_add_i32 m0, s1, 0xc000
	ds_read_b128 v[162:165], v198
	ds_read_b128 v[182:185], v198 offset:1024
	ds_read_b128 v[186:189], v198 offset:2048
	ds_read_b128 v[190:193], v198 offset:3072
	ds_read_b128 v[200:203], v198 offset:4096
	ds_read_b128 v[204:207], v198 offset:5120
	ds_read_b128 v[208:211], v198 offset:6144
	ds_read_b128 v[212:215], v198 offset:7168
	global_load_lds_dwordx4 v[216:217], off
	v_lshl_add_u64 v[216:217], s[40:41], 0, v[176:177]
	s_add_i32 m0, s1, 0xe000
	s_nop 0
	global_load_lds_dwordx4 v[216:217], off
	s_mov_b32 m0, s47
	v_lshl_add_u64 v[216:217], v[220:221], 0, s[18:19]
	global_load_lds_dwordx4 v[216:217], off
	s_mov_b32 m0, s48
	v_lshl_add_u64 v[216:217], v[222:223], 0, s[18:19]
	global_load_lds_dwordx4 v[216:217], off
	s_waitcnt vmcnt(10)
	s_waitcnt lgkmcnt(0)
	s_barrier
; #define PG8_STAGE(bufoff, gbase, voff) do { _Pragma("unroll") for (int _i = 0; _i < 2; ++_i) \
;         __builtin_amdgcn_global_load_lds((const unsigned*)((const char*)(gbase) + (voff)[_i]), (PG8_LAS unsigned*)(lds + (bufoff) + ldsw + _i * 8192), 16, 0, 0); } while (0)
; #define PG8_LDA(dst, b, h) do { _Pragma("unroll") for (int m = 0; m < 4; ++m) _Pragma("unroll") for (int k = 0; k < 2; ++k) dst[m][k] = *(const PG8_LAS bf16x8*)(lds + PG8_SA(b, h) + aoff + m * 2048 + k * 1024); } while (0)
; #define PG8_MMA(ai, bj, At, Bt) do { __builtin_amdgcn_s_setprio(1); _Pragma("unroll") for (int m = 0; m < 4; ++m) _Pragma("unroll") for (int n = 0; n < 2; ++n) _Pragma("unroll") for (int k = 0; k < 2; ++k) \
;         acc[ai][bj][m][n] = __builtin_amdgcn_mfma_f32_16x16x32_bf16(Bt[n][k], At[m][k], acc[ai][bj][m][n], 0, 0, 0); __builtin_amdgcn_s_setprio(0); } while (0)
; #define PG8_WAIT_V(n) asm volatile("s_waitcnt vmcnt(" #n ")" ::: "memory")
; #define PG8_WAIT_L(n) asm volatile("s_waitcnt lgkmcnt(" #n ")" ::: "memory")
; #define PG8_BAR __builtin_amdgcn_s_barrier()
; #define PG8_SCHED __builtin_amdgcn_sched_barrier(0)
; template <class Epi, class Sched, bool ALIGN_EPI = false, bool SP2 = false, bool HALFM = false>
; __device__ __forceinline__ void gemm_phase(PG8_LAS unsigned char* lds, const Gemm g, const Sched& S, const Epi& E) {
;     ...
;             PG8_WAIT_V(8); PG8_WAIT_L(0); PG8_BAR; PG8_MMA(0, 0, At, B0); PG8_MMA(0, 1, At, B1); PG8_BAR; PG8_SCHED;
;             PG8_LDA(At, 0, 1); PG8_STAGE(PG8_SB(0, 0), b2, voffB); PG8_STAGE(PG8_SB(0, 1), b2 + hstep, voffB); PG8_STAGE(PG8_SA(0, 0), a2, voffA);
;             PG8_WAIT_V(8); PG8_WAIT_L(0); PG8_BAR; if constexpr (!HALFM) { PG8_MMA(1, 0, At, B0); PG8_MMA(1, 1, At, B1); } PG8_BAR; PG8_SCHED;
	s_setprio 1
	s_waitcnt lgkmcnt(0)
	v_mfma_f32_16x16x32_bf16 v[126:129], v[130:133], v[162:165], v[126:129]
	v_mfma_f32_16x16x32_bf16 v[122:125], v[138:141], v[162:165], v[122:125]
	v_mfma_f32_16x16x32_bf16 v[114:117], v[130:133], v[186:189], v[114:117]
	v_mfma_f32_16x16x32_bf16 v[106:109], v[138:141], v[186:189], v[106:109]
	v_mfma_f32_16x16x32_bf16 v[98:101], v[130:133], v[200:203], v[98:101]
	v_mfma_f32_16x16x32_bf16 v[90:93], v[138:141], v[200:203], v[90:93]
	v_mfma_f32_16x16x32_bf16 v[82:85], v[130:133], v[208:211], v[82:85]
	v_mfma_f32_16x16x32_bf16 v[74:77], v[138:141], v[208:211], v[74:77]
	v_mfma_f32_16x16x32_bf16 v[126:129], v[134:137], v[182:185], v[126:129]
	v_mfma_f32_16x16x32_bf16 v[122:125], v[142:145], v[182:185], v[122:125]
	v_mfma_f32_16x16x32_bf16 v[114:117], v[134:137], v[190:193], v[114:117]
	v_mfma_f32_16x16x32_bf16 v[106:109], v[142:145], v[190:193], v[106:109]
	v_mfma_f32_16x16x32_bf16 v[98:101], v[134:137], v[204:207], v[98:101]
	v_mfma_f32_16x16x32_bf16 v[90:93], v[142:145], v[204:207], v[90:93]
	v_mfma_f32_16x16x32_bf16 v[82:85], v[134:137], v[212:215], v[82:85]
	v_mfma_f32_16x16x32_bf16 v[74:77], v[142:145], v[212:215], v[74:77]
	s_setprio 0
	s_setprio 1
	v_mfma_f32_16x16x32_bf16 v[118:121], v[146:149], v[162:165], v[118:121]
	v_mfma_f32_16x16x32_bf16 v[110:113], v[154:157], v[162:165], v[110:113]
	v_mfma_f32_16x16x32_bf16 v[102:105], v[146:149], v[186:189], v[102:105]
	v_mfma_f32_16x16x32_bf16 v[94:97], v[154:157], v[186:189], v[94:97]
	v_mfma_f32_16x16x32_bf16 v[86:89], v[146:149], v[200:203], v[86:89]
	v_mfma_f32_16x16x32_bf16 v[78:81], v[154:157], v[200:203], v[78:81]
	v_mfma_f32_16x16x32_bf16 v[70:73], v[146:149], v[208:211], v[70:73]
	v_mfma_f32_16x16x32_bf16 v[66:69], v[154:157], v[208:211], v[66:69]
	v_mfma_f32_16x16x32_bf16 v[118:121], v[150:153], v[182:185], v[118:121]
	v_mfma_f32_16x16x32_bf16 v[110:113], v[158:161], v[182:185], v[110:113]
	v_mfma_f32_16x16x32_bf16 v[102:105], v[150:153], v[190:193], v[102:105]
	v_mfma_f32_16x16x32_bf16 v[94:97], v[158:161], v[190:193], v[94:97]
	v_mfma_f32_16x16x32_bf16 v[86:89], v[150:153], v[204:207], v[86:89]
	v_mfma_f32_16x16x32_bf16 v[78:81], v[158:161], v[204:207], v[78:81]
	v_mfma_f32_16x16x32_bf16 v[70:73], v[150:153], v[212:215], v[70:73]
	v_mfma_f32_16x16x32_bf16 v[66:69], v[158:161], v[212:215], v[66:69]
	s_setprio 0
	s_barrier
	s_add_i32 s62, s50, s0
	v_lshl_add_u64 v[216:217], s[42:43], 0, v[168:169]
	s_mov_b32 m0, s62
	ds_read_b128 v[162:165], v198 offset:16384
	ds_read_b128 v[182:185], v198 offset:17408
	ds_read_b128 v[186:189], v198 offset:18432
	ds_read_b128 v[190:193], v198 offset:19456
	ds_read_b128 v[200:203], v198 offset:20480
	ds_read_b128 v[204:207], v198 offset:21504
	ds_read_b128 v[208:211], v198 offset:22528
	ds_read_b128 v[212:215], v198 offset:23552
	global_load_lds_dwordx4 v[216:217], off
	s_add_i32 m0, s62, 0x2000
	s_add_u32 s62, s42, 0x80000
	v_lshl_add_u64 v[218:219], s[42:43], 0, v[172:173]
	s_addc_u32 s63, s43, 0
	s_add_i32 s64, s51, s0
	global_load_lds_dwordx4 v[218:219], off
	v_lshl_add_u64 v[220:221], s[62:63], 0, v[168:169]
	s_mov_b32 m0, s64
	v_lshl_add_u64 v[222:223], s[44:45], 0, v[170:171]
	global_load_lds_dwordx4 v[220:221], off
	v_lshl_add_u64 v[220:221], s[62:63], 0, v[172:173]
	s_add_i32 m0, s64, 0x2000
	s_nop 0
	global_load_lds_dwordx4 v[220:221], off
	v_lshl_add_u64 v[220:221], s[44:45], 0, v[166:167]
	s_waitcnt vmcnt(4)
	s_waitcnt lgkmcnt(0)
	s_barrier
	s_setprio 1
	s_waitcnt lgkmcnt(0)
	v_mfma_f32_16x16x32_bf16 v[62:65], v[130:133], v[162:165], v[62:65]
	v_mfma_f32_16x16x32_bf16 v[58:61], v[138:141], v[162:165], v[58:61]
	v_mfma_f32_16x16x32_bf16 v[50:53], v[130:133], v[186:189], v[50:53]
	v_mfma_f32_16x16x32_bf16 v[42:45], v[138:141], v[186:189], v[42:45]
	v_mfma_f32_16x16x32_bf16 v[34:37], v[130:133], v[200:203], v[34:37]
	v_mfma_f32_16x16x32_bf16 v[26:29], v[138:141], v[200:203], v[26:29]
	v_mfma_f32_16x16x32_bf16 v[18:21], v[130:133], v[208:211], v[18:21]
	v_mfma_f32_16x16x32_bf16 v[10:13], v[138:141], v[208:211], v[10:13]
	v_mfma_f32_16x16x32_bf16 v[62:65], v[134:137], v[182:185], v[62:65]
	v_mfma_f32_16x16x32_bf16 v[58:61], v[142:145], v[182:185], v[58:61]
	v_mfma_f32_16x16x32_bf16 v[50:53], v[134:137], v[190:193], v[50:53]
	v_mfma_f32_16x16x32_bf16 v[42:45], v[142:145], v[190:193], v[42:45]
	v_mfma_f32_16x16x32_bf16 v[34:37], v[134:137], v[204:207], v[34:37]
	v_mfma_f32_16x16x32_bf16 v[26:29], v[142:145], v[204:207], v[26:29]
	v_mfma_f32_16x16x32_bf16 v[18:21], v[134:137], v[212:215], v[18:21]
	v_mfma_f32_16x16x32_bf16 v[10:13], v[142:145], v[212:215], v[10:13]
	s_setprio 0
	s_setprio 1
	v_mfma_f32_16x16x32_bf16 v[54:57], v[146:149], v[162:165], v[54:57]
	v_mfma_f32_16x16x32_bf16 v[46:49], v[154:157], v[162:165], v[46:49]
	v_mfma_f32_16x16x32_bf16 v[38:41], v[146:149], v[186:189], v[38:41]
	v_mfma_f32_16x16x32_bf16 v[30:33], v[154:157], v[186:189], v[30:33]
	v_mfma_f32_16x16x32_bf16 v[22:25], v[146:149], v[200:203], v[22:25]
	v_mfma_f32_16x16x32_bf16 v[14:17], v[154:157], v[200:203], v[14:17]
	v_mfma_f32_16x16x32_bf16 v[6:9], v[146:149], v[208:211], v[6:9]
	v_mfma_f32_16x16x32_bf16 v[2:5], v[154:157], v[208:211], v[2:5]
	v_mfma_f32_16x16x32_bf16 v[54:57], v[150:153], v[182:185], v[54:57]
	v_mfma_f32_16x16x32_bf16 v[46:49], v[158:161], v[182:185], v[46:49]
	v_mfma_f32_16x16x32_bf16 v[38:41], v[150:153], v[190:193], v[38:41]
	v_mfma_f32_16x16x32_bf16 v[30:33], v[158:161], v[190:193], v[30:33]
	v_mfma_f32_16x16x32_bf16 v[22:25], v[150:153], v[204:207], v[22:25]
	v_mfma_f32_16x16x32_bf16 v[14:17], v[158:161], v[204:207], v[14:17]
	v_mfma_f32_16x16x32_bf16 v[6:9], v[150:153], v[212:215], v[6:9]
	v_mfma_f32_16x16x32_bf16 v[2:5], v[158:161], v[212:215], v[2:5]
	s_setprio 0
	s_barrier
; #define PG8_STAGE(bufoff, gbase, voff) do { _Pragma("unroll") for (int _i = 0; _i < 2; ++_i) \
;         __builtin_amdgcn_global_load_lds((const unsigned*)((const char*)(gbase) + (voff)[_i]), (PG8_LAS unsigned*)(lds + (bufoff) + ldsw + _i * 8192), 16, 0, 0); } while (0)
; #define PG8_LDA(dst, b, h) do { _Pragma("unroll") for (int m = 0; m < 4; ++m) _Pragma("unroll") for (int k = 0; k < 2; ++k) dst[m][k] = *(const PG8_LAS bf16x8*)(lds + PG8_SA(b, h) + aoff + m * 2048 + k * 1024); } while (0)
; #define PG8_LDB(dst, b, h) do { _Pragma("unroll") for (int n = 0; n < 2; ++n) _Pragma("unroll") for (int k = 0; k < 2; ++k) dst[n][k] = *(const PG8_LAS bf16x8*)(lds + PG8_SB(b, h) + boff + n * 2048 + k * 1024); } while (0)
; #define PG8_MMA(ai, bj, At, Bt) do { __builtin_amdgcn_s_setprio(1); _Pragma("unroll") for (int m = 0; m < 4; ++m) _Pragma("unroll") for (int n = 0; n < 2; ++n) _Pragma("unroll") for (int k = 0; k < 2; ++k) \
;         acc[ai][bj][m][n] = __builtin_amdgcn_mfma_f32_16x16x32_bf16(Bt[n][k], At[m][k], acc[ai][bj][m][n], 0, 0, 0); __builtin_amdgcn_s_setprio(0); } while (0)
; #define PG8_WAIT_V(n) asm volatile("s_waitcnt vmcnt(" #n ")" ::: "memory")
; #define PG8_WAIT_L(n) asm volatile("s_waitcnt lgkmcnt(" #n ")" ::: "memory")
; #define PG8_BAR __builtin_amdgcn_s_barrier()
; #define PG8_SCHED __builtin_amdgcn_sched_barrier(0)
; template <class Epi, class Sched, bool ALIGN_EPI = false, bool SP2 = false, bool HALFM = false>
; __device__ __forceinline__ void gemm_phase(PG8_LAS unsigned char* lds, const Gemm g, const Sched& S, const Epi& E) {
;     ...
;             PG8_LDB(B0, 1, 0); PG8_LDB(B1, 1, 1); PG8_SCHED; PG8_LDA(At, 1, 0); PG8_STAGE(PG8_SA(0, 1), a2 + hstep, voffA);
;             PG8_WAIT_V(8); PG8_WAIT_L(0); PG8_BAR; PG8_MMA(0, 0, At, B0); PG8_MMA(0, 1, At, B1); PG8_BAR; PG8_SCHED;
	s_add_i32 s62, 0, 0x18000
	s_add_i32 s63, 0, 0x1c000
	v_add_u32_e32 v142, s62, v194
	v_add_u32_e32 v158, s63, v194
	ds_read_b128 v[130:133], v142
	ds_read_b128 v[134:137], v142 offset:1024
	ds_read_b128 v[138:141], v142 offset:2048
	ds_read_b128 v[142:145], v142 offset:3072
	ds_read_b128 v[146:149], v158
	ds_read_b128 v[150:153], v158 offset:1024
	ds_read_b128 v[154:157], v158 offset:2048
	ds_read_b128 v[158:161], v158 offset:3072
	s_add_u32 s44, s44, 0x80000
	s_addc_u32 s45, s45, 0
	s_mov_b32 m0, s3
	v_lshl_add_u64 v[224:225], s[44:45], 0, v[166:167]
	ds_read_b128 v[162:165], v198 offset:32768
	ds_read_b128 v[182:185], v198 offset:33792
	ds_read_b128 v[186:189], v198 offset:34816
	ds_read_b128 v[190:193], v198 offset:35840
	ds_read_b128 v[200:203], v198 offset:36864
	ds_read_b128 v[204:207], v198 offset:37888
	ds_read_b128 v[208:211], v198 offset:38912
	ds_read_b128 v[212:215], v198 offset:39936
	global_load_lds_dwordx4 v[224:225], off
	v_lshl_add_u64 v[224:225], s[44:45], 0, v[170:171]
	s_mov_b32 m0, s46
	s_nop 0
	global_load_lds_dwordx4 v[224:225], off
	s_mov_b32 m0, s1
	s_nop 0
	global_load_lds_dwordx4 v[220:221], off
	s_mov_b32 m0, s2
	s_nop 0
	global_load_lds_dwordx4 v[222:223], off
	s_waitcnt vmcnt(10)
	s_waitcnt lgkmcnt(0)
	s_barrier
	s_setprio 1
	s_waitcnt lgkmcnt(0)
	v_mfma_f32_16x16x32_bf16 v[126:129], v[130:133], v[162:165], v[126:129]
	v_mfma_f32_16x16x32_bf16 v[122:125], v[138:141], v[162:165], v[122:125]
	v_mfma_f32_16x16x32_bf16 v[114:117], v[130:133], v[186:189], v[114:117]
	v_mfma_f32_16x16x32_bf16 v[106:109], v[138:141], v[186:189], v[106:109]
	v_mfma_f32_16x16x32_bf16 v[98:101], v[130:133], v[200:203], v[98:101]
	v_mfma_f32_16x16x32_bf16 v[90:93], v[138:141], v[200:203], v[90:93]
	v_mfma_f32_16x16x32_bf16 v[82:85], v[130:133], v[208:211], v[82:85]
	v_mfma_f32_16x16x32_bf16 v[74:77], v[138:141], v[208:211], v[74:77]
	v_mfma_f32_16x16x32_bf16 v[126:129], v[134:137], v[182:185], v[126:129]
	v_mfma_f32_16x16x32_bf16 v[122:125], v[142:145], v[182:185], v[122:125]
	v_mfma_f32_16x16x32_bf16 v[114:117], v[134:137], v[190:193], v[114:117]
	v_mfma_f32_16x16x32_bf16 v[106:109], v[142:145], v[190:193], v[106:109]
	v_mfma_f32_16x16x32_bf16 v[98:101], v[134:137], v[204:207], v[98:101]
	v_mfma_f32_16x16x32_bf16 v[90:93], v[142:145], v[204:207], v[90:93]
	v_mfma_f32_16x16x32_bf16 v[82:85], v[134:137], v[212:215], v[82:85]
	v_mfma_f32_16x16x32_bf16 v[74:77], v[142:145], v[212:215], v[74:77]
	s_setprio 0
	s_setprio 1
	v_mfma_f32_16x16x32_bf16 v[118:121], v[146:149], v[162:165], v[118:121]
	v_mfma_f32_16x16x32_bf16 v[110:113], v[154:157], v[162:165], v[110:113]
	v_mfma_f32_16x16x32_bf16 v[102:105], v[146:149], v[186:189], v[102:105]
	v_mfma_f32_16x16x32_bf16 v[94:97], v[154:157], v[186:189], v[94:97]
	v_mfma_f32_16x16x32_bf16 v[86:89], v[146:149], v[200:203], v[86:89]
	v_mfma_f32_16x16x32_bf16 v[78:81], v[154:157], v[200:203], v[78:81]
	v_mfma_f32_16x16x32_bf16 v[70:73], v[146:149], v[208:211], v[70:73]
	v_mfma_f32_16x16x32_bf16 v[66:69], v[154:157], v[208:211], v[66:69]
	v_mfma_f32_16x16x32_bf16 v[118:121], v[150:153], v[182:185], v[118:121]
	v_mfma_f32_16x16x32_bf16 v[110:113], v[158:161], v[182:185], v[110:113]
	v_mfma_f32_16x16x32_bf16 v[102:105], v[150:153], v[190:193], v[102:105]
	v_mfma_f32_16x16x32_bf16 v[94:97], v[158:161], v[190:193], v[94:97]
	v_mfma_f32_16x16x32_bf16 v[86:89], v[150:153], v[204:207], v[86:89]
	v_mfma_f32_16x16x32_bf16 v[78:81], v[158:161], v[204:207], v[78:81]
	v_mfma_f32_16x16x32_bf16 v[70:73], v[150:153], v[212:215], v[70:73]
	v_mfma_f32_16x16x32_bf16 v[66:69], v[158:161], v[212:215], v[66:69]
	s_setprio 0
	s_barrier
; #define PG8_STAGE(bufoff, gbase, voff) do { _Pragma("unroll") for (int _i = 0; _i < 2; ++_i) \
;         __builtin_amdgcn_global_load_lds((const unsigned*)((const char*)(gbase) + (voff)[_i]), (PG8_LAS unsigned*)(lds + (bufoff) + ldsw + _i * 8192), 16, 0, 0); } while (0)
; #define PG8_LDA(dst, b, h) do { _Pragma("unroll") for (int m = 0; m < 4; ++m) _Pragma("unroll") for (int k = 0; k < 2; ++k) dst[m][k] = *(const PG8_LAS bf16x8*)(lds + PG8_SA(b, h) + aoff + m * 2048 + k * 1024); } while (0)
; #define PG8_MMA(ai, bj, At, Bt) do { __builtin_amdgcn_s_setprio(1); _Pragma("unroll") for (int m = 0; m < 4; ++m) _Pragma("unroll") for (int n = 0; n < 2; ++n) _Pragma("unroll") for (int k = 0; k < 2; ++k) \
;         acc[ai][bj][m][n] = __builtin_amdgcn_mfma_f32_16x16x32_bf16(Bt[n][k], At[m][k], acc[ai][bj][m][n], 0, 0, 0); __builtin_amdgcn_s_setprio(0); } while (0)
; #define PG8_WAIT_V(n) asm volatile("s_waitcnt vmcnt(" #n ")" ::: "memory")
; #define PG8_WAIT_L(n) asm volatile("s_waitcnt lgkmcnt(" #n ")" ::: "memory")
; #define PG8_BAR __builtin_amdgcn_s_barrier()
; #define PG8_SCHED __builtin_amdgcn_sched_barrier(0)
; template <class Epi, class Sched, bool ALIGN_EPI = false, bool SP2 = false, bool HALFM = false>
; __device__ __forceinline__ void gemm_phase(PG8_LAS unsigned char* lds, const Gemm g, const Sched& S, const Epi& E) {
;     ...
;             PG8_LDA(At, 1, 1); PG8_STAGE(PG8_SB(1, 0), b3, voffB); PG8_STAGE(PG8_SB(1, 1), b3 + hstep, voffB); PG8_STAGE(PG8_SA(1, 0), a3, voffA);
;             PG8_WAIT_V(8); PG8_WAIT_L(0); PG8_BAR; if constexpr (!HALFM) { PG8_MMA(1, 0, At, B0); PG8_MMA(1, 1, At, B1); } PG8_BAR; PG8_SCHED;
	s_add_i32 s44, s62, s0
	v_lshl_add_u64 v[216:217], v[216:217], 0, s[18:19]
	s_mov_b32 m0, s44
	ds_read_b128 v[162:165], v198 offset:49152
	ds_read_b128 v[182:185], v198 offset:50176
	ds_read_b128 v[186:189], v198 offset:51200
	ds_read_b128 v[190:193], v198 offset:52224
	ds_read_b128 v[200:203], v198 offset:53248
	ds_read_b128 v[204:207], v198 offset:54272
	ds_read_b128 v[208:211], v198 offset:55296
	ds_read_b128 v[212:215], v198 offset:56320
	global_load_lds_dwordx4 v[216:217], off
	s_add_i32 m0, s44, 0x2000
	s_add_u32 s42, s42, 0x80080
	v_lshl_add_u64 v[216:217], v[218:219], 0, s[18:19]
	s_addc_u32 s43, s43, 0
	s_add_i32 s44, s63, s0
	global_load_lds_dwordx4 v[216:217], off
	v_lshl_add_u64 v[216:217], s[42:43], 0, v[168:169]
	s_mov_b32 m0, s44
	s_nop 0
	global_load_lds_dwordx4 v[216:217], off
	v_lshl_add_u64 v[216:217], s[42:43], 0, v[172:173]
	s_add_i32 m0, s44, 0x2000
	s_nop 0
	global_load_lds_dwordx4 v[216:217], off
	s_waitcnt vmcnt(4)
	s_waitcnt lgkmcnt(0)
	s_barrier
	s_setprio 1
	s_waitcnt lgkmcnt(0)
	v_mfma_f32_16x16x32_bf16 v[62:65], v[130:133], v[162:165], v[62:65]
	v_mfma_f32_16x16x32_bf16 v[58:61], v[138:141], v[162:165], v[58:61]
	v_mfma_f32_16x16x32_bf16 v[50:53], v[130:133], v[186:189], v[50:53]
	v_mfma_f32_16x16x32_bf16 v[42:45], v[138:141], v[186:189], v[42:45]
	v_mfma_f32_16x16x32_bf16 v[34:37], v[130:133], v[200:203], v[34:37]
	v_mfma_f32_16x16x32_bf16 v[26:29], v[138:141], v[200:203], v[26:29]
	v_mfma_f32_16x16x32_bf16 v[18:21], v[130:133], v[208:211], v[18:21]
	v_mfma_f32_16x16x32_bf16 v[10:13], v[138:141], v[208:211], v[10:13]
	v_mfma_f32_16x16x32_bf16 v[62:65], v[134:137], v[182:185], v[62:65]
	v_mfma_f32_16x16x32_bf16 v[58:61], v[142:145], v[182:185], v[58:61]
	v_mfma_f32_16x16x32_bf16 v[50:53], v[134:137], v[190:193], v[50:53]
	v_mfma_f32_16x16x32_bf16 v[42:45], v[142:145], v[190:193], v[42:45]
	v_mfma_f32_16x16x32_bf16 v[34:37], v[134:137], v[204:207], v[34:37]
	v_mfma_f32_16x16x32_bf16 v[26:29], v[142:145], v[204:207], v[26:29]
	v_mfma_f32_16x16x32_bf16 v[18:21], v[134:137], v[212:215], v[18:21]
	v_mfma_f32_16x16x32_bf16 v[10:13], v[142:145], v[212:215], v[10:13]
	s_setprio 0
	s_setprio 1
	v_mfma_f32_16x16x32_bf16 v[54:57], v[146:149], v[162:165], v[54:57]
	v_mfma_f32_16x16x32_bf16 v[46:49], v[154:157], v[162:165], v[46:49]
	v_mfma_f32_16x16x32_bf16 v[38:41], v[146:149], v[186:189], v[38:41]
	v_mfma_f32_16x16x32_bf16 v[30:33], v[154:157], v[186:189], v[30:33]
	v_mfma_f32_16x16x32_bf16 v[22:25], v[146:149], v[200:203], v[22:25]
	v_mfma_f32_16x16x32_bf16 v[14:17], v[154:157], v[200:203], v[14:17]
	v_mfma_f32_16x16x32_bf16 v[6:9], v[146:149], v[208:211], v[6:9]
	v_mfma_f32_16x16x32_bf16 v[2:5], v[154:157], v[208:211], v[2:5]
	v_mfma_f32_16x16x32_bf16 v[54:57], v[150:153], v[182:185], v[54:57]
	v_mfma_f32_16x16x32_bf16 v[46:49], v[158:161], v[182:185], v[46:49]
	v_mfma_f32_16x16x32_bf16 v[38:41], v[150:153], v[190:193], v[38:41]
	v_mfma_f32_16x16x32_bf16 v[30:33], v[158:161], v[190:193], v[30:33]
	v_mfma_f32_16x16x32_bf16 v[22:25], v[150:153], v[204:207], v[22:25]
	v_mfma_f32_16x16x32_bf16 v[14:17], v[158:161], v[204:207], v[14:17]
	v_mfma_f32_16x16x32_bf16 v[6:9], v[150:153], v[212:215], v[6:9]
	v_mfma_f32_16x16x32_bf16 v[2:5], v[158:161], v[212:215], v[2:5]
	s_setprio 0
	s_barrier
	s_add_i32 s61, s61, 2
	s_add_u32 s40, s40, 0x100
	s_addc_u32 s41, s41, 0
	s_add_u32 s59, s59, 0x100
	s_addc_u32 s60, s60, 0
	s_cmp_gt_u32 s61, 29
	s_cbranch_scc0 .LBB0_1510
	s_and_b64 vcc, exec, s[20:21]
	s_cbranch_vccz .LBB0_1513
	s_barrier

;     __device__ __forceinline__ bool next(int i, Unit& u) const { const int L = L0 + i * G + c; if (L >= L1) return false; u.pm = L >> 2; u.pn = L & 3; u.ko = 0; return true; }
; #define PG8_STAGE(bufoff, gbase, voff) do { _Pragma("unroll") for (int _i = 0; _i < 2; ++_i) \
;         __builtin_amdgcn_global_load_lds((const unsigned*)((const char*)(gbase) + (voff)[_i]), (PG8_LAS unsigned*)(lds + (bufoff) + ldsw + _i * 8192), 16, 0, 0); } while (0)
; #define PG8_LDA(dst, b, h) do { _Pragma("unroll") for (int m = 0; m < 4; ++m) _Pragma("unroll") for (int k = 0; k < 2; ++k) dst[m][k] = *(const PG8_LAS bf16x8*)(lds + PG8_SA(b, h) + aoff + m * 2048 + k * 1024); } while (0)
; #define PG8_LDB(dst, b, h) do { _Pragma("unroll") for (int n = 0; n < 2; ++n) _Pragma("unroll") for (int k = 0; k < 2; ++k) dst[n][k] = *(const PG8_LAS bf16x8*)(lds + PG8_SB(b, h) + boff + n * 2048 + k * 1024); } while (0)
; template <class Epi, class Sched, bool ALIGN_EPI = false, bool SP2 = false, bool HALFM = false>
; __device__ __forceinline__ void gemm_phase(PG8_LAS unsigned char* lds, const Gemm g, const Sched& S, const Epi& E) {
;     ...
;         const bool has_next = S.next(ui + 1, nxt);
;         const char* nA = has_next ? (const char*)g.A + (size_t)nxt.pm * tstep + (size_t)nxt.ko * 2 : cA; const char* nB = has_next ? (const char*)g.Bt + (size_t)nxt.pn * tstep + (size_t)nxt.ko * 2 : cB;
;         for (int t = 0; t < nt; t += 2) {
;             const bool last = (t == nt - 2);
;             const char* a1 = cA + (size_t)(t + 1) * kstep;
;             const char* a2 = last ? nA : cA + (size_t)(t + 2) * kstep; const char* b2 = last ? nB : cB + (size_t)(t + 2) * kstep;
;             const char* a3 = a2 + kstep; const char* b3 = b2 + kstep;
;             if (last && has_next) S.a_ready(nxt);
;             if constexpr (SP2) {
;             PG8_LDB(B0, 0, 0); PG8_LDB(B1, 0, 1); PG8_SCHED; PG8_LDA(At, 0, 0); PG8_STAGE(PG8_SA(1, 1), a1 + hstep, voffA);
;             PG8_WAIT_V(8); PG8_WAIT_L(0); PG8_BAR; PG8_MMA(0, 0, At, B0); PG8_MMA(0, 1, At, B1); PG8_BAR; PG8_SCHED;
;     ...
;         for (int a = 0; a < 2; ++a)
; #pragma unroll
;             for (int b = 0; b < 2; ++b)
; #pragma unroll
;                 for (int m = 0; m < 4; ++m)
; #pragma unroll
;                     for (int n = 0; n < 2; ++n) acc[a][b][m][n] = (f32x4){0.f, 0.f, 0.f, 0.f};
;         cur = nxt; cA = nA; cB = nB; ++ui;
.LBB0_1599:
	s_ashr_i32 s27, s26, 31
	s_lshl_b64 s[28:29], s[26:27], 18
	s_add_u32 s28, s60, s28
	s_addc_u32 s29, s61, s29
	s_and_b64 s[30:31], s[6:7], exec
	s_cselect_b32 s27, s29, s37
	s_cselect_b32 s50, s28, s36
	s_ashr_i32 s25, s24, 31
	s_lshl_b64 s[30:31], s[24:25], 18
	s_add_u32 s30, s63, s30
	s_addc_u32 s31, s64, s31
	s_and_b64 s[40:41], s[6:7], exec
	s_cselect_b32 s25, s31, s39
	s_cselect_b32 s51, s30, s38
	s_add_u32 s36, s36, 0x20080
	s_addc_u32 s37, s37, 0
	s_add_u32 s52, s38, 0x100
	v_mov_b32_e32 v2, 0
	s_addc_u32 s53, s39, 0
	s_mov_b32 s54, -2
	v_mov_b32_e32 v3, v2
	v_mov_b32_e32 v4, v2
	v_mov_b32_e32 v5, v2
	v_mov_b32_e32 v6, v2
	v_mov_b32_e32 v7, v2
	v_mov_b32_e32 v8, v2
	v_mov_b32_e32 v9, v2
	v_mov_b32_e32 v18, v2
	v_mov_b32_e32 v19, v2
	v_mov_b32_e32 v20, v2
	v_mov_b32_e32 v21, v2
	v_mov_b32_e32 v22, v2
	v_mov_b32_e32 v23, v2
	v_mov_b32_e32 v24, v2
	v_mov_b32_e32 v25, v2
	v_mov_b32_e32 v34, v2
	v_mov_b32_e32 v35, v2
	v_mov_b32_e32 v36, v2
	v_mov_b32_e32 v37, v2
	v_mov_b32_e32 v38, v2
	v_mov_b32_e32 v39, v2
	v_mov_b32_e32 v40, v2
	v_mov_b32_e32 v41, v2
	v_mov_b32_e32 v50, v2
	v_mov_b32_e32 v51, v2
	v_mov_b32_e32 v52, v2
	v_mov_b32_e32 v53, v2
	v_mov_b32_e32 v54, v2
	v_mov_b32_e32 v55, v2
	v_mov_b32_e32 v56, v2
	v_mov_b32_e32 v57, v2
	v_mov_b32_e32 v10, v2
	v_mov_b32_e32 v11, v2
	v_mov_b32_e32 v12, v2
	v_mov_b32_e32 v13, v2
	v_mov_b32_e32 v14, v2
	v_mov_b32_e32 v15, v2
	v_mov_b32_e32 v16, v2
	v_mov_b32_e32 v17, v2
	v_mov_b32_e32 v26, v2
	v_mov_b32_e32 v27, v2
	v_mov_b32_e32 v28, v2
	v_mov_b32_e32 v29, v2
	v_mov_b32_e32 v30, v2
	v_mov_b32_e32 v31, v2
	v_mov_b32_e32 v32, v2
	v_mov_b32_e32 v33, v2
	v_mov_b32_e32 v42, v2
	v_mov_b32_e32 v43, v2
	v_mov_b32_e32 v44, v2
	v_mov_b32_e32 v45, v2
	v_mov_b32_e32 v46, v2
	v_mov_b32_e32 v47, v2
	v_mov_b32_e32 v48, v2
	v_mov_b32_e32 v49, v2
	v_mov_b32_e32 v58, v2
	v_mov_b32_e32 v59, v2
	v_mov_b32_e32 v60, v2
	v_mov_b32_e32 v61, v2
	v_mov_b32_e32 v62, v2
	v_mov_b32_e32 v63, v2
	v_mov_b32_e32 v64, v2
	v_mov_b32_e32 v65, v2
	v_mov_b32_e32 v66, v2
	v_mov_b32_e32 v67, v2
	v_mov_b32_e32 v68, v2
	v_mov_b32_e32 v69, v2
	v_mov_b32_e32 v70, v2
	v_mov_b32_e32 v71, v2
	v_mov_b32_e32 v72, v2
	v_mov_b32_e32 v73, v2
	v_mov_b32_e32 v82, v2
	v_mov_b32_e32 v83, v2
	v_mov_b32_e32 v84, v2
	v_mov_b32_e32 v85, v2
	v_mov_b32_e32 v86, v2
	v_mov_b32_e32 v87, v2
	v_mov_b32_e32 v88, v2
	v_mov_b32_e32 v89, v2
	v_mov_b32_e32 v98, v2
	v_mov_b32_e32 v99, v2
	v_mov_b32_e32 v100, v2
	v_mov_b32_e32 v101, v2
	v_mov_b32_e32 v102, v2
	v_mov_b32_e32 v103, v2
	v_mov_b32_e32 v104, v2
	v_mov_b32_e32 v105, v2
	v_mov_b32_e32 v114, v2
	v_mov_b32_e32 v115, v2
	v_mov_b32_e32 v116, v2
	v_mov_b32_e32 v117, v2
	v_mov_b32_e32 v118, v2
	v_mov_b32_e32 v119, v2
	v_mov_b32_e32 v120, v2
	v_mov_b32_e32 v121, v2
	v_mov_b32_e32 v74, v2
	v_mov_b32_e32 v75, v2
	v_mov_b32_e32 v76, v2
	v_mov_b32_e32 v77, v2
	v_mov_b32_e32 v78, v2
	v_mov_b32_e32 v79, v2
	v_mov_b32_e32 v80, v2
	v_mov_b32_e32 v81, v2
	v_mov_b32_e32 v90, v2
	v_mov_b32_e32 v91, v2
	v_mov_b32_e32 v92, v2
	v_mov_b32_e32 v93, v2
	v_mov_b32_e32 v94, v2
	v_mov_b32_e32 v95, v2
	v_mov_b32_e32 v96, v2
	v_mov_b32_e32 v97, v2
	v_mov_b32_e32 v106, v2
	v_mov_b32_e32 v107, v2
	v_mov_b32_e32 v108, v2
	v_mov_b32_e32 v109, v2
	v_mov_b32_e32 v110, v2
	v_mov_b32_e32 v111, v2
	v_mov_b32_e32 v112, v2
	v_mov_b32_e32 v113, v2
	v_mov_b32_e32 v122, v2
	v_mov_b32_e32 v123, v2
	v_mov_b32_e32 v124, v2
	v_mov_b32_e32 v125, v2
	v_mov_b32_e32 v126, v2
	v_mov_b32_e32 v127, v2
	v_mov_b32_e32 v128, v2
	v_mov_b32_e32 v129, v2
	s_mov_b32 s100, 0xfffdff80
	s_mov_b32 s101, -1
	v_lshl_add_u64 v[220:221], s[36:37], 0, v[158:159]
	v_lshl_add_u64 v[220:221], v[220:221], 0, s[100:101]
	v_lshl_add_u64 v[222:223], s[36:37], 0, v[160:161]
	v_lshl_add_u64 v[222:223], v[222:223], 0, s[100:101]
.LBB0_1600:
	ds_read_b128 v[130:133], v178
	ds_read_b128 v[134:137], v178 offset:1024
	ds_read_b128 v[138:141], v178 offset:2048
	ds_read_b128 v[142:145], v178 offset:3072
	ds_read_b128 v[146:149], v179
	ds_read_b128 v[166:169], v179 offset:1024
	ds_read_b128 v[170:173], v179 offset:2048
	ds_read_b128 v[182:185], v179 offset:3072
	s_add_u32 s38, s36, 0xfffe0080
	s_addc_u32 s39, s37, -1
	s_cmp_eq_u32 s54, 4
	s_cselect_b32 s41, s27, s39
	s_cselect_b32 s40, s50, s38
	s_cselect_b32 s39, s25, s53
	s_cselect_b32 s38, s51, s52
	v_lshl_add_u64 v[174:175], s[36:37], 0, v[158:159]
	s_add_i32 m0, s1, 0xc000
	ds_read_b128 v[186:189], v180
	ds_read_b128 v[190:193], v180 offset:1024
	ds_read_b128 v[194:197], v180 offset:2048
	ds_read_b128 v[198:201], v180 offset:3072
	ds_read_b128 v[202:205], v180 offset:4096
	ds_read_b128 v[206:209], v180 offset:5120
	ds_read_b128 v[210:213], v180 offset:6144
	ds_read_b128 v[214:217], v180 offset:7168
	global_load_lds_dwordx4 v[174:175], off
	v_lshl_add_u64 v[174:175], s[36:37], 0, v[160:161]
	s_add_i32 m0, s1, 0xe000
	s_nop 0
	global_load_lds_dwordx4 v[174:175], off
	s_mov_b32 m0, s43
	v_lshl_add_u64 v[174:175], v[220:221], 0, s[14:15]
	global_load_lds_dwordx4 v[174:175], off
	s_mov_b32 m0, s44
	v_lshl_add_u64 v[174:175], v[222:223], 0, s[14:15]
	global_load_lds_dwordx4 v[174:175], off
	s_waitcnt vmcnt(10)
	s_waitcnt lgkmcnt(0)
	s_barrier
; #define PG8_STAGE(bufoff, gbase, voff) do { _Pragma("unroll") for (int _i = 0; _i < 2; ++_i) \
;         __builtin_amdgcn_global_load_lds((const unsigned*)((const char*)(gbase) + (voff)[_i]), (PG8_LAS unsigned*)(lds + (bufoff) + ldsw + _i * 8192), 16, 0, 0); } while (0)
; #define PG8_LDA(dst, b, h) do { _Pragma("unroll") for (int m = 0; m < 4; ++m) _Pragma("unroll") for (int k = 0; k < 2; ++k) dst[m][k] = *(const PG8_LAS bf16x8*)(lds + PG8_SA(b, h) + aoff + m * 2048 + k * 1024); } while (0)
; #define PG8_MMA(ai, bj, At, Bt) do { __builtin_amdgcn_s_setprio(1); _Pragma("unroll") for (int m = 0; m < 4; ++m) _Pragma("unroll") for (int n = 0; n < 2; ++n) _Pragma("unroll") for (int k = 0; k < 2; ++k) \
;         acc[ai][bj][m][n] = __builtin_amdgcn_mfma_f32_16x16x32_bf16(Bt[n][k], At[m][k], acc[ai][bj][m][n], 0, 0, 0); __builtin_amdgcn_s_setprio(0); } while (0)
; #define PG8_WAIT_V(n) asm volatile("s_waitcnt vmcnt(" #n ")" ::: "memory")
; #define PG8_WAIT_L(n) asm volatile("s_waitcnt lgkmcnt(" #n ")" ::: "memory")
; #define PG8_BAR __builtin_amdgcn_s_barrier()
; #define PG8_SCHED __builtin_amdgcn_sched_barrier(0)
; template <class Epi, class Sched, bool ALIGN_EPI = false, bool SP2 = false, bool HALFM = false>
; __device__ __forceinline__ void gemm_phase(PG8_LAS unsigned char* lds, const Gemm g, const Sched& S, const Epi& E) {
;     ...
;             PG8_WAIT_V(8); PG8_WAIT_L(0); PG8_BAR; PG8_MMA(0, 0, At, B0); PG8_MMA(0, 1, At, B1); PG8_BAR; PG8_SCHED;
;             PG8_LDA(At, 0, 1); PG8_STAGE(PG8_SB(0, 0), b2, voffB); PG8_STAGE(PG8_SB(0, 1), b2 + hstep, voffB); PG8_STAGE(PG8_SA(0, 0), a2, voffA);
;             PG8_WAIT_V(8); PG8_WAIT_L(0); PG8_BAR; if constexpr (!HALFM) { PG8_MMA(1, 0, At, B0); PG8_MMA(1, 1, At, B1); } PG8_BAR; PG8_SCHED;
	s_setprio 1
	s_waitcnt lgkmcnt(0)
	v_mfma_f32_16x16x32_bf16 v[126:129], v[130:133], v[186:189], v[126:129]
	v_mfma_f32_16x16x32_bf16 v[122:125], v[138:141], v[186:189], v[122:125]
	v_mfma_f32_16x16x32_bf16 v[110:113], v[130:133], v[194:197], v[110:113]
	v_mfma_f32_16x16x32_bf16 v[106:109], v[138:141], v[194:197], v[106:109]
	v_mfma_f32_16x16x32_bf16 v[94:97], v[130:133], v[202:205], v[94:97]
	v_mfma_f32_16x16x32_bf16 v[90:93], v[138:141], v[202:205], v[90:93]
	v_mfma_f32_16x16x32_bf16 v[78:81], v[130:133], v[210:213], v[78:81]
	v_mfma_f32_16x16x32_bf16 v[74:77], v[138:141], v[210:213], v[74:77]
	v_mfma_f32_16x16x32_bf16 v[126:129], v[134:137], v[190:193], v[126:129]
	v_mfma_f32_16x16x32_bf16 v[122:125], v[142:145], v[190:193], v[122:125]
	v_mfma_f32_16x16x32_bf16 v[110:113], v[134:137], v[198:201], v[110:113]
	v_mfma_f32_16x16x32_bf16 v[106:109], v[142:145], v[198:201], v[106:109]
	v_mfma_f32_16x16x32_bf16 v[94:97], v[134:137], v[206:209], v[94:97]
	v_mfma_f32_16x16x32_bf16 v[90:93], v[142:145], v[206:209], v[90:93]
	v_mfma_f32_16x16x32_bf16 v[78:81], v[134:137], v[214:217], v[78:81]
	v_mfma_f32_16x16x32_bf16 v[74:77], v[142:145], v[214:217], v[74:77]
	s_setprio 0
	s_setprio 1
	v_mfma_f32_16x16x32_bf16 v[118:121], v[146:149], v[186:189], v[118:121]
	v_mfma_f32_16x16x32_bf16 v[114:117], v[170:173], v[186:189], v[114:117]
	v_mfma_f32_16x16x32_bf16 v[102:105], v[146:149], v[194:197], v[102:105]
	v_mfma_f32_16x16x32_bf16 v[98:101], v[170:173], v[194:197], v[98:101]
	v_mfma_f32_16x16x32_bf16 v[86:89], v[146:149], v[202:205], v[86:89]
	v_mfma_f32_16x16x32_bf16 v[82:85], v[170:173], v[202:205], v[82:85]
	v_mfma_f32_16x16x32_bf16 v[70:73], v[146:149], v[210:213], v[70:73]
	v_mfma_f32_16x16x32_bf16 v[66:69], v[170:173], v[210:213], v[66:69]
	v_mfma_f32_16x16x32_bf16 v[118:121], v[166:169], v[190:193], v[118:121]
	v_mfma_f32_16x16x32_bf16 v[114:117], v[182:185], v[190:193], v[114:117]
	v_mfma_f32_16x16x32_bf16 v[102:105], v[166:169], v[198:201], v[102:105]
	v_mfma_f32_16x16x32_bf16 v[98:101], v[182:185], v[198:201], v[98:101]
	v_mfma_f32_16x16x32_bf16 v[86:89], v[166:169], v[206:209], v[86:89]
	v_mfma_f32_16x16x32_bf16 v[82:85], v[182:185], v[206:209], v[82:85]
	v_mfma_f32_16x16x32_bf16 v[70:73], v[166:169], v[214:217], v[70:73]
	v_mfma_f32_16x16x32_bf16 v[66:69], v[182:185], v[214:217], v[66:69]
	s_setprio 0
	s_barrier
	s_add_i32 s55, s46, s0
	v_lshl_add_u64 v[174:175], s[38:39], 0, v[152:153]
	s_mov_b32 m0, s55
	ds_read_b128 v[186:189], v180 offset:16384
	ds_read_b128 v[190:193], v180 offset:17408
	ds_read_b128 v[194:197], v180 offset:18432
	ds_read_b128 v[198:201], v180 offset:19456
	ds_read_b128 v[202:205], v180 offset:20480
	ds_read_b128 v[206:209], v180 offset:21504
	ds_read_b128 v[210:213], v180 offset:22528
	ds_read_b128 v[214:217], v180 offset:23552
	global_load_lds_dwordx4 v[174:175], off
	s_add_i32 m0, s55, 0x2000
	s_add_u32 s56, s38, 0x20000
	v_lshl_add_u64 v[218:219], s[38:39], 0, v[156:157]
	s_addc_u32 s57, s39, 0
	s_add_i32 s55, s47, s0
	global_load_lds_dwordx4 v[218:219], off
	v_lshl_add_u64 v[220:221], s[56:57], 0, v[152:153]
	s_mov_b32 m0, s55
	v_lshl_add_u64 v[222:223], s[40:41], 0, v[154:155]
	global_load_lds_dwordx4 v[220:221], off
	v_lshl_add_u64 v[220:221], s[56:57], 0, v[156:157]
	s_add_i32 m0, s55, 0x2000
	s_nop 0
	global_load_lds_dwordx4 v[220:221], off
	v_lshl_add_u64 v[220:221], s[40:41], 0, v[150:151]
	s_waitcnt vmcnt(4)
	s_waitcnt lgkmcnt(0)
	s_barrier
	s_setprio 1
	s_waitcnt lgkmcnt(0)
	v_mfma_f32_16x16x32_bf16 v[62:65], v[130:133], v[186:189], v[62:65]
	v_mfma_f32_16x16x32_bf16 v[58:61], v[138:141], v[186:189], v[58:61]
	v_mfma_f32_16x16x32_bf16 v[46:49], v[130:133], v[194:197], v[46:49]
	v_mfma_f32_16x16x32_bf16 v[42:45], v[138:141], v[194:197], v[42:45]
	v_mfma_f32_16x16x32_bf16 v[30:33], v[130:133], v[202:205], v[30:33]
	v_mfma_f32_16x16x32_bf16 v[26:29], v[138:141], v[202:205], v[26:29]
	v_mfma_f32_16x16x32_bf16 v[14:17], v[130:133], v[210:213], v[14:17]
	v_mfma_f32_16x16x32_bf16 v[10:13], v[138:141], v[210:213], v[10:13]
	v_mfma_f32_16x16x32_bf16 v[62:65], v[134:137], v[190:193], v[62:65]
	v_mfma_f32_16x16x32_bf16 v[58:61], v[142:145], v[190:193], v[58:61]
	v_mfma_f32_16x16x32_bf16 v[46:49], v[134:137], v[198:201], v[46:49]
	v_mfma_f32_16x16x32_bf16 v[42:45], v[142:145], v[198:201], v[42:45]
	v_mfma_f32_16x16x32_bf16 v[30:33], v[134:137], v[206:209], v[30:33]
	v_mfma_f32_16x16x32_bf16 v[26:29], v[142:145], v[206:209], v[26:29]
	v_mfma_f32_16x16x32_bf16 v[14:17], v[134:137], v[214:217], v[14:17]
	v_mfma_f32_16x16x32_bf16 v[10:13], v[142:145], v[214:217], v[10:13]
	s_setprio 0
	s_setprio 1
	v_mfma_f32_16x16x32_bf16 v[54:57], v[146:149], v[186:189], v[54:57]
	v_mfma_f32_16x16x32_bf16 v[50:53], v[170:173], v[186:189], v[50:53]
	v_mfma_f32_16x16x32_bf16 v[38:41], v[146:149], v[194:197], v[38:41]
	v_mfma_f32_16x16x32_bf16 v[34:37], v[170:173], v[194:197], v[34:37]
	v_mfma_f32_16x16x32_bf16 v[22:25], v[146:149], v[202:205], v[22:25]
	v_mfma_f32_16x16x32_bf16 v[18:21], v[170:173], v[202:205], v[18:21]
	v_mfma_f32_16x16x32_bf16 v[6:9], v[146:149], v[210:213], v[6:9]
	v_mfma_f32_16x16x32_bf16 v[2:5], v[170:173], v[210:213], v[2:5]
	v_mfma_f32_16x16x32_bf16 v[54:57], v[166:169], v[190:193], v[54:57]
	v_mfma_f32_16x16x32_bf16 v[50:53], v[182:185], v[190:193], v[50:53]
	v_mfma_f32_16x16x32_bf16 v[38:41], v[166:169], v[198:201], v[38:41]
	v_mfma_f32_16x16x32_bf16 v[34:37], v[182:185], v[198:201], v[34:37]
	v_mfma_f32_16x16x32_bf16 v[22:25], v[166:169], v[206:209], v[22:25]
	v_mfma_f32_16x16x32_bf16 v[18:21], v[182:185], v[206:209], v[18:21]
	v_mfma_f32_16x16x32_bf16 v[6:9], v[166:169], v[214:217], v[6:9]
	v_mfma_f32_16x16x32_bf16 v[2:5], v[182:185], v[214:217], v[2:5]
	s_setprio 0
	s_barrier
; #define PG8_STAGE(bufoff, gbase, voff) do { _Pragma("unroll") for (int _i = 0; _i < 2; ++_i) \
;         __builtin_amdgcn_global_load_lds((const unsigned*)((const char*)(gbase) + (voff)[_i]), (PG8_LAS unsigned*)(lds + (bufoff) + ldsw + _i * 8192), 16, 0, 0); } while (0)
; #define PG8_LDA(dst, b, h) do { _Pragma("unroll") for (int m = 0; m < 4; ++m) _Pragma("unroll") for (int k = 0; k < 2; ++k) dst[m][k] = *(const PG8_LAS bf16x8*)(lds + PG8_SA(b, h) + aoff + m * 2048 + k * 1024); } while (0)
; #define PG8_LDB(dst, b, h) do { _Pragma("unroll") for (int n = 0; n < 2; ++n) _Pragma("unroll") for (int k = 0; k < 2; ++k) dst[n][k] = *(const PG8_LAS bf16x8*)(lds + PG8_SB(b, h) + boff + n * 2048 + k * 1024); } while (0)
; #define PG8_MMA(ai, bj, At, Bt) do { __builtin_amdgcn_s_setprio(1); _Pragma("unroll") for (int m = 0; m < 4; ++m) _Pragma("unroll") for (int n = 0; n < 2; ++n) _Pragma("unroll") for (int k = 0; k < 2; ++k) \
;         acc[ai][bj][m][n] = __builtin_amdgcn_mfma_f32_16x16x32_bf16(Bt[n][k], At[m][k], acc[ai][bj][m][n], 0, 0, 0); __builtin_amdgcn_s_setprio(0); } while (0)
; #define PG8_WAIT_V(n) asm volatile("s_waitcnt vmcnt(" #n ")" ::: "memory")
; #define PG8_WAIT_L(n) asm volatile("s_waitcnt lgkmcnt(" #n ")" ::: "memory")
; #define PG8_BAR __builtin_amdgcn_s_barrier()
; #define PG8_SCHED __builtin_amdgcn_sched_barrier(0)
; template <class Epi, class Sched, bool ALIGN_EPI = false, bool SP2 = false, bool HALFM = false>
; __device__ __forceinline__ void gemm_phase(PG8_LAS unsigned char* lds, const Gemm g, const Sched& S, const Epi& E) {
;     ...
;             PG8_LDB(B0, 1, 0); PG8_LDB(B1, 1, 1); PG8_SCHED; PG8_LDA(At, 1, 0); PG8_STAGE(PG8_SA(0, 1), a2 + hstep, voffA);
;             PG8_WAIT_V(8); PG8_WAIT_L(0); PG8_BAR; PG8_MMA(0, 0, At, B0); PG8_MMA(0, 1, At, B1); PG8_BAR; PG8_SCHED;
	s_add_i32 s55, 0, 0x18000
	s_add_i32 s56, 0, 0x1c000
	v_add_u32_e32 v142, s55, v176
	v_add_u32_e32 v181, s56, v176
	ds_read_b128 v[130:133], v142
	ds_read_b128 v[134:137], v142 offset:1024
	ds_read_b128 v[138:141], v142 offset:2048
	ds_read_b128 v[142:145], v142 offset:3072
	ds_read_b128 v[146:149], v181
	ds_read_b128 v[166:169], v181 offset:1024
	ds_read_b128 v[170:173], v181 offset:2048
	ds_read_b128 v[182:185], v181 offset:3072
	s_add_u32 s40, s40, 0x20000
	s_addc_u32 s41, s41, 0
	s_mov_b32 m0, s3
	v_lshl_add_u64 v[224:225], s[40:41], 0, v[150:151]
	ds_read_b128 v[186:189], v180 offset:32768
	ds_read_b128 v[190:193], v180 offset:33792
	ds_read_b128 v[194:197], v180 offset:34816
	ds_read_b128 v[198:201], v180 offset:35840
	ds_read_b128 v[202:205], v180 offset:36864
	ds_read_b128 v[206:209], v180 offset:37888
	ds_read_b128 v[210:213], v180 offset:38912
	ds_read_b128 v[214:217], v180 offset:39936
	global_load_lds_dwordx4 v[224:225], off
	v_lshl_add_u64 v[224:225], s[40:41], 0, v[154:155]
	s_mov_b32 m0, s35
	s_nop 0
	global_load_lds_dwordx4 v[224:225], off
	s_mov_b32 m0, s1
	s_nop 0
	global_load_lds_dwordx4 v[220:221], off
	s_mov_b32 m0, s2
	s_nop 0
	global_load_lds_dwordx4 v[222:223], off
	s_waitcnt vmcnt(10)
	s_waitcnt lgkmcnt(0)
	s_barrier
	s_setprio 1
	s_waitcnt lgkmcnt(0)
	v_mfma_f32_16x16x32_bf16 v[126:129], v[130:133], v[186:189], v[126:129]
	v_mfma_f32_16x16x32_bf16 v[122:125], v[138:141], v[186:189], v[122:125]
	v_mfma_f32_16x16x32_bf16 v[110:113], v[130:133], v[194:197], v[110:113]
	v_mfma_f32_16x16x32_bf16 v[106:109], v[138:141], v[194:197], v[106:109]
	v_mfma_f32_16x16x32_bf16 v[94:97], v[130:133], v[202:205], v[94:97]
	v_mfma_f32_16x16x32_bf16 v[90:93], v[138:141], v[202:205], v[90:93]
	v_mfma_f32_16x16x32_bf16 v[78:81], v[130:133], v[210:213], v[78:81]
	v_mfma_f32_16x16x32_bf16 v[74:77], v[138:141], v[210:213], v[74:77]
	v_mfma_f32_16x16x32_bf16 v[126:129], v[134:137], v[190:193], v[126:129]
	v_mfma_f32_16x16x32_bf16 v[122:125], v[142:145], v[190:193], v[122:125]
	v_mfma_f32_16x16x32_bf16 v[110:113], v[134:137], v[198:201], v[110:113]
	v_mfma_f32_16x16x32_bf16 v[106:109], v[142:145], v[198:201], v[106:109]
	v_mfma_f32_16x16x32_bf16 v[94:97], v[134:137], v[206:209], v[94:97]
	v_mfma_f32_16x16x32_bf16 v[90:93], v[142:145], v[206:209], v[90:93]
	v_mfma_f32_16x16x32_bf16 v[78:81], v[134:137], v[214:217], v[78:81]
	v_mfma_f32_16x16x32_bf16 v[74:77], v[142:145], v[214:217], v[74:77]
	s_setprio 0
	s_setprio 1
	v_mfma_f32_16x16x32_bf16 v[118:121], v[146:149], v[186:189], v[118:121]
	v_mfma_f32_16x16x32_bf16 v[114:117], v[170:173], v[186:189], v[114:117]
	v_mfma_f32_16x16x32_bf16 v[102:105], v[146:149], v[194:197], v[102:105]
	v_mfma_f32_16x16x32_bf16 v[98:101], v[170:173], v[194:197], v[98:101]
	v_mfma_f32_16x16x32_bf16 v[86:89], v[146:149], v[202:205], v[86:89]
	v_mfma_f32_16x16x32_bf16 v[82:85], v[170:173], v[202:205], v[82:85]
	v_mfma_f32_16x16x32_bf16 v[70:73], v[146:149], v[210:213], v[70:73]
	v_mfma_f32_16x16x32_bf16 v[66:69], v[170:173], v[210:213], v[66:69]
	v_mfma_f32_16x16x32_bf16 v[118:121], v[166:169], v[190:193], v[118:121]
	v_mfma_f32_16x16x32_bf16 v[114:117], v[182:185], v[190:193], v[114:117]
	v_mfma_f32_16x16x32_bf16 v[102:105], v[166:169], v[198:201], v[102:105]
	v_mfma_f32_16x16x32_bf16 v[98:101], v[182:185], v[198:201], v[98:101]
	v_mfma_f32_16x16x32_bf16 v[86:89], v[166:169], v[206:209], v[86:89]
	v_mfma_f32_16x16x32_bf16 v[82:85], v[182:185], v[206:209], v[82:85]
	v_mfma_f32_16x16x32_bf16 v[70:73], v[166:169], v[214:217], v[70:73]
	v_mfma_f32_16x16x32_bf16 v[66:69], v[182:185], v[214:217], v[66:69]
	s_setprio 0
	s_barrier
; #define PG8_STAGE(bufoff, gbase, voff) do { _Pragma("unroll") for (int _i = 0; _i < 2; ++_i) \
;         __builtin_amdgcn_global_load_lds((const unsigned*)((const char*)(gbase) + (voff)[_i]), (PG8_LAS unsigned*)(lds + (bufoff) + ldsw + _i * 8192), 16, 0, 0); } while (0)
; #define PG8_LDA(dst, b, h) do { _Pragma("unroll") for (int m = 0; m < 4; ++m) _Pragma("unroll") for (int k = 0; k < 2; ++k) dst[m][k] = *(const PG8_LAS bf16x8*)(lds + PG8_SA(b, h) + aoff + m * 2048 + k * 1024); } while (0)
; #define PG8_MMA(ai, bj, At, Bt) do { __builtin_amdgcn_s_setprio(1); _Pragma("unroll") for (int m = 0; m < 4; ++m) _Pragma("unroll") for (int n = 0; n < 2; ++n) _Pragma("unroll") for (int k = 0; k < 2; ++k) \
;         acc[ai][bj][m][n] = __builtin_amdgcn_mfma_f32_16x16x32_bf16(Bt[n][k], At[m][k], acc[ai][bj][m][n], 0, 0, 0); __builtin_amdgcn_s_setprio(0); } while (0)
; #define PG8_WAIT_V(n) asm volatile("s_waitcnt vmcnt(" #n ")" ::: "memory")
; #define PG8_WAIT_L(n) asm volatile("s_waitcnt lgkmcnt(" #n ")" ::: "memory")
; #define PG8_BAR __builtin_amdgcn_s_barrier()
; #define PG8_SCHED __builtin_amdgcn_sched_barrier(0)
; template <class Epi, class Sched, bool ALIGN_EPI = false, bool SP2 = false, bool HALFM = false>
; __device__ __forceinline__ void gemm_phase(PG8_LAS unsigned char* lds, const Gemm g, const Sched& S, const Epi& E) {
;     ...
;             PG8_LDA(At, 1, 1); PG8_STAGE(PG8_SB(1, 0), b3, voffB); PG8_STAGE(PG8_SB(1, 1), b3 + hstep, voffB); PG8_STAGE(PG8_SA(1, 0), a3, voffA);
;             PG8_WAIT_V(8); PG8_WAIT_L(0); PG8_BAR; if constexpr (!HALFM) { PG8_MMA(1, 0, At, B0); PG8_MMA(1, 1, At, B1); } PG8_BAR; PG8_SCHED;
	s_add_i32 s40, s55, s0
	v_lshl_add_u64 v[174:175], v[174:175], 0, s[14:15]
	s_mov_b32 m0, s40
	ds_read_b128 v[186:189], v180 offset:49152
	ds_read_b128 v[190:193], v180 offset:50176
	ds_read_b128 v[194:197], v180 offset:51200
	ds_read_b128 v[198:201], v180 offset:52224
	ds_read_b128 v[202:205], v180 offset:53248
	ds_read_b128 v[206:209], v180 offset:54272
	ds_read_b128 v[210:213], v180 offset:55296
	ds_read_b128 v[214:217], v180 offset:56320
	global_load_lds_dwordx4 v[174:175], off
	s_add_i32 m0, s40, 0x2000
	s_add_u32 s38, s38, 0x20080
	v_lshl_add_u64 v[174:175], v[218:219], 0, s[14:15]
	s_addc_u32 s39, s39, 0
	s_add_i32 s40, s56, s0
	global_load_lds_dwordx4 v[174:175], off
	v_lshl_add_u64 v[174:175], s[38:39], 0, v[152:153]
	s_mov_b32 m0, s40
	s_nop 0
	global_load_lds_dwordx4 v[174:175], off
	v_lshl_add_u64 v[174:175], s[38:39], 0, v[156:157]
	s_add_i32 m0, s40, 0x2000
	s_nop 0
	global_load_lds_dwordx4 v[174:175], off
	s_waitcnt vmcnt(4)
	s_waitcnt lgkmcnt(0)
	s_barrier
	s_setprio 1
	s_waitcnt lgkmcnt(0)
	v_mfma_f32_16x16x32_bf16 v[62:65], v[130:133], v[186:189], v[62:65]
	v_mfma_f32_16x16x32_bf16 v[58:61], v[138:141], v[186:189], v[58:61]
	v_mfma_f32_16x16x32_bf16 v[46:49], v[130:133], v[194:197], v[46:49]
	v_mfma_f32_16x16x32_bf16 v[42:45], v[138:141], v[194:197], v[42:45]
	v_mfma_f32_16x16x32_bf16 v[30:33], v[130:133], v[202:205], v[30:33]
	v_mfma_f32_16x16x32_bf16 v[26:29], v[138:141], v[202:205], v[26:29]
	v_mfma_f32_16x16x32_bf16 v[14:17], v[130:133], v[210:213], v[14:17]
	v_mfma_f32_16x16x32_bf16 v[10:13], v[138:141], v[210:213], v[10:13]
	v_mfma_f32_16x16x32_bf16 v[62:65], v[134:137], v[190:193], v[62:65]
	v_mfma_f32_16x16x32_bf16 v[58:61], v[142:145], v[190:193], v[58:61]
	v_mfma_f32_16x16x32_bf16 v[46:49], v[134:137], v[198:201], v[46:49]
	v_mfma_f32_16x16x32_bf16 v[42:45], v[142:145], v[198:201], v[42:45]
	v_mfma_f32_16x16x32_bf16 v[30:33], v[134:137], v[206:209], v[30:33]
	v_mfma_f32_16x16x32_bf16 v[26:29], v[142:145], v[206:209], v[26:29]
	v_mfma_f32_16x16x32_bf16 v[14:17], v[134:137], v[214:217], v[14:17]
	v_mfma_f32_16x16x32_bf16 v[10:13], v[142:145], v[214:217], v[10:13]
	s_setprio 0
	s_setprio 1
	v_mfma_f32_16x16x32_bf16 v[54:57], v[146:149], v[186:189], v[54:57]
	v_mfma_f32_16x16x32_bf16 v[50:53], v[170:173], v[186:189], v[50:53]
	v_mfma_f32_16x16x32_bf16 v[38:41], v[146:149], v[194:197], v[38:41]
	v_mfma_f32_16x16x32_bf16 v[34:37], v[170:173], v[194:197], v[34:37]
	v_mfma_f32_16x16x32_bf16 v[22:25], v[146:149], v[202:205], v[22:25]
	v_mfma_f32_16x16x32_bf16 v[18:21], v[170:173], v[202:205], v[18:21]
	v_mfma_f32_16x16x32_bf16 v[6:9], v[146:149], v[210:213], v[6:9]
	v_mfma_f32_16x16x32_bf16 v[2:5], v[170:173], v[210:213], v[2:5]
	v_mfma_f32_16x16x32_bf16 v[54:57], v[166:169], v[190:193], v[54:57]
	v_mfma_f32_16x16x32_bf16 v[50:53], v[182:185], v[190:193], v[50:53]
	v_mfma_f32_16x16x32_bf16 v[38:41], v[166:169], v[198:201], v[38:41]
	v_mfma_f32_16x16x32_bf16 v[34:37], v[182:185], v[198:201], v[34:37]
	v_mfma_f32_16x16x32_bf16 v[22:25], v[166:169], v[206:209], v[22:25]
	v_mfma_f32_16x16x32_bf16 v[18:21], v[182:185], v[206:209], v[18:21]
	v_mfma_f32_16x16x32_bf16 v[6:9], v[166:169], v[214:217], v[6:9]
	v_mfma_f32_16x16x32_bf16 v[2:5], v[182:185], v[214:217], v[2:5]
	s_setprio 0
	s_barrier
	s_add_i32 s54, s54, 2
	s_add_u32 s36, s36, 0x100
	s_addc_u32 s37, s37, 0
	s_add_u32 s52, s52, 0x100
	s_addc_u32 s53, s53, 0
	s_cmp_gt_u32 s54, 5
	s_cbranch_scc0 .LBB0_1600
	s_and_b64 vcc, exec, s[20:21]
	s_cbranch_vccz .LBB0_1603
	s_barrier

;     __device__ __forceinline__ bool next(int i, Unit& u) const { const int L = L0 + i * G + c; if (L >= L1) return false; u.pm = L >> 2; u.pn = L & 3; u.ko = 0; return true; }
; #define PG8_STAGE(bufoff, gbase, voff) do { _Pragma("unroll") for (int _i = 0; _i < 2; ++_i) \
;         __builtin_amdgcn_global_load_lds((const unsigned*)((const char*)(gbase) + (voff)[_i]), (PG8_LAS unsigned*)(lds + (bufoff) + ldsw + _i * 8192), 16, 0, 0); } while (0)
; #define PG8_LDA(dst, b, h) do { _Pragma("unroll") for (int m = 0; m < 4; ++m) _Pragma("unroll") for (int k = 0; k < 2; ++k) dst[m][k] = *(const PG8_LAS bf16x8*)(lds + PG8_SA(b, h) + aoff + m * 2048 + k * 1024); } while (0)
; #define PG8_LDB(dst, b, h) do { _Pragma("unroll") for (int n = 0; n < 2; ++n) _Pragma("unroll") for (int k = 0; k < 2; ++k) dst[n][k] = *(const PG8_LAS bf16x8*)(lds + PG8_SB(b, h) + boff + n * 2048 + k * 1024); } while (0)
; template <class Epi, class Sched, bool ALIGN_EPI = false, bool SP2 = false, bool HALFM = false>
; __device__ __forceinline__ void gemm_phase(PG8_LAS unsigned char* lds, const Gemm g, const Sched& S, const Epi& E) {
;     ...
;         const bool has_next = S.next(ui + 1, nxt);
;         const char* nA = has_next ? (const char*)g.A + (size_t)nxt.pm * tstep + (size_t)nxt.ko * 2 : cA; const char* nB = has_next ? (const char*)g.Bt + (size_t)nxt.pn * tstep + (size_t)nxt.ko * 2 : cB;
;         for (int t = 0; t < nt; t += 2) {
;             const bool last = (t == nt - 2);
;             const char* a1 = cA + (size_t)(t + 1) * kstep;
;             const char* a2 = last ? nA : cA + (size_t)(t + 2) * kstep; const char* b2 = last ? nB : cB + (size_t)(t + 2) * kstep;
;             const char* a3 = a2 + kstep; const char* b3 = b2 + kstep;
;             if (last && has_next) S.a_ready(nxt);
;             if constexpr (SP2) {
;             PG8_LDB(B0, 0, 0); PG8_LDB(B1, 0, 1); PG8_SCHED; PG8_LDA(At, 0, 0); PG8_STAGE(PG8_SA(1, 1), a1 + hstep, voffA);
;             PG8_WAIT_V(8); PG8_WAIT_L(0); PG8_BAR; PG8_MMA(0, 0, At, B0); PG8_MMA(0, 1, At, B1); PG8_BAR; PG8_SCHED;
;     ...
;         for (int a = 0; a < 2; ++a)
; #pragma unroll
;             for (int b = 0; b < 2; ++b)
; #pragma unroll
;                 for (int m = 0; m < 4; ++m)
; #pragma unroll
;                     for (int n = 0; n < 2; ++n) acc[a][b][m][n] = (f32x4){0.f, 0.f, 0.f, 0.f};
;         cur = nxt; cA = nA; cB = nB; ++ui;
.LBB0_1691:
	s_ashr_i32 s25, s24, 31
	s_lshl_b64 s[26:27], s[24:25], 19
	s_add_u32 s26, s18, s26
	s_addc_u32 s27, s19, s27
	s_and_b64 s[28:29], s[8:9], exec
	s_cselect_b32 s25, s27, s37
	s_cselect_b32 s31, s26, s36
	s_ashr_i32 s23, s22, 31
	s_lshl_b64 s[28:29], s[22:23], 19
	s_add_u32 s28, s48, s28
	s_addc_u32 s29, s49, s29
	s_and_b64 s[40:41], s[8:9], exec
	s_cselect_b32 s23, s29, s39
	s_cselect_b32 s50, s28, s38
	s_add_u32 s36, s36, 0x40080
	s_addc_u32 s37, s37, 0
	s_add_u32 s51, s38, 0x100
	v_mov_b32_e32 v2, 0
	s_addc_u32 s52, s39, 0
	s_mov_b32 s53, -2
	v_mov_b32_e32 v3, v2
	v_mov_b32_e32 v4, v2
	v_mov_b32_e32 v5, v2
	v_mov_b32_e32 v6, v2
	v_mov_b32_e32 v7, v2
	v_mov_b32_e32 v8, v2
	v_mov_b32_e32 v9, v2
	v_mov_b32_e32 v18, v2
	v_mov_b32_e32 v19, v2
	v_mov_b32_e32 v20, v2
	v_mov_b32_e32 v21, v2
	v_mov_b32_e32 v22, v2
	v_mov_b32_e32 v23, v2
	v_mov_b32_e32 v24, v2
	v_mov_b32_e32 v25, v2
	v_mov_b32_e32 v34, v2
	v_mov_b32_e32 v35, v2
	v_mov_b32_e32 v36, v2
	v_mov_b32_e32 v37, v2
	v_mov_b32_e32 v38, v2
	v_mov_b32_e32 v39, v2
	v_mov_b32_e32 v40, v2
	v_mov_b32_e32 v41, v2
	v_mov_b32_e32 v50, v2
	v_mov_b32_e32 v51, v2
	v_mov_b32_e32 v52, v2
	v_mov_b32_e32 v53, v2
	v_mov_b32_e32 v54, v2
	v_mov_b32_e32 v55, v2
	v_mov_b32_e32 v56, v2
	v_mov_b32_e32 v57, v2
	v_mov_b32_e32 v10, v2
	v_mov_b32_e32 v11, v2
	v_mov_b32_e32 v12, v2
	v_mov_b32_e32 v13, v2
	v_mov_b32_e32 v14, v2
	v_mov_b32_e32 v15, v2
	v_mov_b32_e32 v16, v2
	v_mov_b32_e32 v17, v2
	v_mov_b32_e32 v26, v2
	v_mov_b32_e32 v27, v2
	v_mov_b32_e32 v28, v2
	v_mov_b32_e32 v29, v2
	v_mov_b32_e32 v30, v2
	v_mov_b32_e32 v31, v2
	v_mov_b32_e32 v32, v2
	v_mov_b32_e32 v33, v2
	v_mov_b32_e32 v42, v2
	v_mov_b32_e32 v43, v2
	v_mov_b32_e32 v44, v2
	v_mov_b32_e32 v45, v2
	v_mov_b32_e32 v46, v2
	v_mov_b32_e32 v47, v2
	v_mov_b32_e32 v48, v2
	v_mov_b32_e32 v49, v2
	v_mov_b32_e32 v58, v2
	v_mov_b32_e32 v59, v2
	v_mov_b32_e32 v60, v2
	v_mov_b32_e32 v61, v2
	v_mov_b32_e32 v62, v2
	v_mov_b32_e32 v63, v2
	v_mov_b32_e32 v64, v2
	v_mov_b32_e32 v65, v2
	v_mov_b32_e32 v66, v2
	v_mov_b32_e32 v67, v2
	v_mov_b32_e32 v68, v2
	v_mov_b32_e32 v69, v2
	v_mov_b32_e32 v70, v2
	v_mov_b32_e32 v71, v2
	v_mov_b32_e32 v72, v2
	v_mov_b32_e32 v73, v2
	v_mov_b32_e32 v82, v2
	v_mov_b32_e32 v83, v2
	v_mov_b32_e32 v84, v2
	v_mov_b32_e32 v85, v2
	v_mov_b32_e32 v86, v2
	v_mov_b32_e32 v87, v2
	v_mov_b32_e32 v88, v2
	v_mov_b32_e32 v89, v2
	v_mov_b32_e32 v98, v2
	v_mov_b32_e32 v99, v2
	v_mov_b32_e32 v100, v2
	v_mov_b32_e32 v101, v2
	v_mov_b32_e32 v102, v2
	v_mov_b32_e32 v103, v2
	v_mov_b32_e32 v104, v2
	v_mov_b32_e32 v105, v2
	v_mov_b32_e32 v122, v2
	v_mov_b32_e32 v123, v2
	v_mov_b32_e32 v124, v2
	v_mov_b32_e32 v125, v2
	v_mov_b32_e32 v126, v2
	v_mov_b32_e32 v127, v2
	v_mov_b32_e32 v128, v2
	v_mov_b32_e32 v129, v2
	v_mov_b32_e32 v74, v2
	v_mov_b32_e32 v75, v2
	v_mov_b32_e32 v76, v2
	v_mov_b32_e32 v77, v2
	v_mov_b32_e32 v78, v2
	v_mov_b32_e32 v79, v2
	v_mov_b32_e32 v80, v2
	v_mov_b32_e32 v81, v2
	v_mov_b32_e32 v90, v2
	v_mov_b32_e32 v91, v2
	v_mov_b32_e32 v92, v2
	v_mov_b32_e32 v93, v2
	v_mov_b32_e32 v94, v2
	v_mov_b32_e32 v95, v2
	v_mov_b32_e32 v96, v2
	v_mov_b32_e32 v97, v2
	v_mov_b32_e32 v106, v2
	v_mov_b32_e32 v107, v2
	v_mov_b32_e32 v108, v2
	v_mov_b32_e32 v109, v2
	v_mov_b32_e32 v110, v2
	v_mov_b32_e32 v111, v2
	v_mov_b32_e32 v112, v2
	v_mov_b32_e32 v113, v2
	v_mov_b32_e32 v150, v2
	v_mov_b32_e32 v151, v2
	v_mov_b32_e32 v152, v2
	v_mov_b32_e32 v153, v2
	v_mov_b32_e32 v154, v2
	v_mov_b32_e32 v155, v2
	v_mov_b32_e32 v156, v2
	v_mov_b32_e32 v157, v2
	s_mov_b32 s100, 0xfffbff80
	s_mov_b32 s101, -1
	v_lshl_add_u64 v[210:211], s[36:37], 0, v[202:203]
	v_lshl_add_u64 v[210:211], v[210:211], 0, s[100:101]
	v_lshl_add_u64 v[212:213], s[36:37], 0, v[204:205]
	v_lshl_add_u64 v[212:213], v[212:213], 0, s[100:101]
.LBB0_1692:
	ds_read_b128 v[114:117], v246
	ds_read_b128 v[118:121], v246 offset:1024
	ds_read_b128 v[130:133], v246 offset:2048
	ds_read_b128 v[134:137], v246 offset:3072
	ds_read_b128 v[138:141], v247
	ds_read_b128 v[142:145], v247 offset:1024
	ds_read_b128 v[146:149], v247 offset:2048
	ds_read_b128 v[158:161], v247 offset:3072
	s_add_u32 s38, s36, 0xfffc0080
	s_addc_u32 s39, s37, -1
	s_cmp_eq_u32 s53, 12
	s_cselect_b32 s41, s25, s39
	s_cselect_b32 s40, s31, s38
	s_cselect_b32 s39, s23, s52
	s_cselect_b32 s38, s50, s51
	v_lshl_add_u64 v[206:207], s[36:37], 0, v[202:203]
	s_add_i32 m0, s1, 0xc000
	ds_read_b128 v[162:165], v248
	ds_read_b128 v[166:169], v248 offset:1024
	ds_read_b128 v[170:173], v248 offset:2048
	ds_read_b128 v[174:177], v248 offset:3072
	ds_read_b128 v[178:181], v248 offset:4096
	ds_read_b128 v[182:185], v248 offset:5120
	ds_read_b128 v[186:189], v248 offset:6144
	ds_read_b128 v[190:193], v248 offset:7168
	global_load_lds_dwordx4 v[206:207], off
	v_lshl_add_u64 v[206:207], s[36:37], 0, v[204:205]
	s_add_i32 m0, s1, 0xe000
	s_nop 0
	global_load_lds_dwordx4 v[206:207], off
	s_mov_b32 m0, s43
	v_lshl_add_u64 v[206:207], v[210:211], 0, s[10:11]
	global_load_lds_dwordx4 v[206:207], off
	s_mov_b32 m0, s44
	v_lshl_add_u64 v[206:207], v[212:213], 0, s[10:11]
	global_load_lds_dwordx4 v[206:207], off
	s_waitcnt vmcnt(10)
	s_waitcnt lgkmcnt(0)
	s_barrier
; #define PG8_STAGE(bufoff, gbase, voff) do { _Pragma("unroll") for (int _i = 0; _i < 2; ++_i) \
;         __builtin_amdgcn_global_load_lds((const unsigned*)((const char*)(gbase) + (voff)[_i]), (PG8_LAS unsigned*)(lds + (bufoff) + ldsw + _i * 8192), 16, 0, 0); } while (0)
; #define PG8_LDA(dst, b, h) do { _Pragma("unroll") for (int m = 0; m < 4; ++m) _Pragma("unroll") for (int k = 0; k < 2; ++k) dst[m][k] = *(const PG8_LAS bf16x8*)(lds + PG8_SA(b, h) + aoff + m * 2048 + k * 1024); } while (0)
; #define PG8_MMA(ai, bj, At, Bt) do { __builtin_amdgcn_s_setprio(1); _Pragma("unroll") for (int m = 0; m < 4; ++m) _Pragma("unroll") for (int n = 0; n < 2; ++n) _Pragma("unroll") for (int k = 0; k < 2; ++k) \
;         acc[ai][bj][m][n] = __builtin_amdgcn_mfma_f32_16x16x32_bf16(Bt[n][k], At[m][k], acc[ai][bj][m][n], 0, 0, 0); __builtin_amdgcn_s_setprio(0); } while (0)
; #define PG8_WAIT_V(n) asm volatile("s_waitcnt vmcnt(" #n ")" ::: "memory")
; #define PG8_WAIT_L(n) asm volatile("s_waitcnt lgkmcnt(" #n ")" ::: "memory")
; #define PG8_BAR __builtin_amdgcn_s_barrier()
; #define PG8_SCHED __builtin_amdgcn_sched_barrier(0)
; template <class Epi, class Sched, bool ALIGN_EPI = false, bool SP2 = false, bool HALFM = false>
; __device__ __forceinline__ void gemm_phase(PG8_LAS unsigned char* lds, const Gemm g, const Sched& S, const Epi& E) {
;     ...
;             PG8_WAIT_V(8); PG8_WAIT_L(0); PG8_BAR; PG8_MMA(0, 0, At, B0); PG8_MMA(0, 1, At, B1); PG8_BAR; PG8_SCHED;
;             PG8_LDA(At, 0, 1); PG8_STAGE(PG8_SB(0, 0), b2, voffB); PG8_STAGE(PG8_SB(0, 1), b2 + hstep, voffB); PG8_STAGE(PG8_SA(0, 0), a2, voffA);
;             PG8_WAIT_V(8); PG8_WAIT_L(0); PG8_BAR; if constexpr (!HALFM) { PG8_MMA(1, 0, At, B0); PG8_MMA(1, 1, At, B1); } PG8_BAR; PG8_SCHED;
	s_setprio 1
	s_waitcnt lgkmcnt(0)
	v_mfma_f32_16x16x32_bf16 v[154:157], v[114:117], v[162:165], v[154:157]
	v_mfma_f32_16x16x32_bf16 v[150:153], v[130:133], v[162:165], v[150:153]
	v_mfma_f32_16x16x32_bf16 v[110:113], v[114:117], v[170:173], v[110:113]
	v_mfma_f32_16x16x32_bf16 v[106:109], v[130:133], v[170:173], v[106:109]
	v_mfma_f32_16x16x32_bf16 v[94:97], v[114:117], v[178:181], v[94:97]
	v_mfma_f32_16x16x32_bf16 v[90:93], v[130:133], v[178:181], v[90:93]
	v_mfma_f32_16x16x32_bf16 v[78:81], v[114:117], v[186:189], v[78:81]
	v_mfma_f32_16x16x32_bf16 v[74:77], v[130:133], v[186:189], v[74:77]
	v_mfma_f32_16x16x32_bf16 v[154:157], v[118:121], v[166:169], v[154:157]
	v_mfma_f32_16x16x32_bf16 v[150:153], v[134:137], v[166:169], v[150:153]
	v_mfma_f32_16x16x32_bf16 v[110:113], v[118:121], v[174:177], v[110:113]
	v_mfma_f32_16x16x32_bf16 v[106:109], v[134:137], v[174:177], v[106:109]
	v_mfma_f32_16x16x32_bf16 v[94:97], v[118:121], v[182:185], v[94:97]
	v_mfma_f32_16x16x32_bf16 v[90:93], v[134:137], v[182:185], v[90:93]
	v_mfma_f32_16x16x32_bf16 v[78:81], v[118:121], v[190:193], v[78:81]
	v_mfma_f32_16x16x32_bf16 v[74:77], v[134:137], v[190:193], v[74:77]
	s_setprio 0
	s_setprio 1
	v_mfma_f32_16x16x32_bf16 v[126:129], v[138:141], v[162:165], v[126:129]
	v_mfma_f32_16x16x32_bf16 v[122:125], v[146:149], v[162:165], v[122:125]
	v_mfma_f32_16x16x32_bf16 v[102:105], v[138:141], v[170:173], v[102:105]
	v_mfma_f32_16x16x32_bf16 v[98:101], v[146:149], v[170:173], v[98:101]
	v_mfma_f32_16x16x32_bf16 v[86:89], v[138:141], v[178:181], v[86:89]
	v_mfma_f32_16x16x32_bf16 v[82:85], v[146:149], v[178:181], v[82:85]
	v_mfma_f32_16x16x32_bf16 v[70:73], v[138:141], v[186:189], v[70:73]
	v_mfma_f32_16x16x32_bf16 v[66:69], v[146:149], v[186:189], v[66:69]
	v_mfma_f32_16x16x32_bf16 v[126:129], v[142:145], v[166:169], v[126:129]
	v_mfma_f32_16x16x32_bf16 v[122:125], v[158:161], v[166:169], v[122:125]
	v_mfma_f32_16x16x32_bf16 v[102:105], v[142:145], v[174:177], v[102:105]
	v_mfma_f32_16x16x32_bf16 v[98:101], v[158:161], v[174:177], v[98:101]
	v_mfma_f32_16x16x32_bf16 v[86:89], v[142:145], v[182:185], v[86:89]
	v_mfma_f32_16x16x32_bf16 v[82:85], v[158:161], v[182:185], v[82:85]
	v_mfma_f32_16x16x32_bf16 v[70:73], v[142:145], v[190:193], v[70:73]
	v_mfma_f32_16x16x32_bf16 v[66:69], v[158:161], v[190:193], v[66:69]
	s_setprio 0
	s_barrier
	s_add_i32 s54, s46, s0
	v_lshl_add_u64 v[206:207], s[38:39], 0, v[196:197]
	s_mov_b32 m0, s54
	ds_read_b128 v[162:165], v248 offset:16384
	ds_read_b128 v[166:169], v248 offset:17408
	ds_read_b128 v[170:173], v248 offset:18432
	ds_read_b128 v[174:177], v248 offset:19456
	ds_read_b128 v[178:181], v248 offset:20480
	ds_read_b128 v[182:185], v248 offset:21504
	ds_read_b128 v[186:189], v248 offset:22528
	ds_read_b128 v[190:193], v248 offset:23552
	global_load_lds_dwordx4 v[206:207], off
	s_add_i32 m0, s54, 0x2000
	s_add_u32 s54, s38, 0x40000
	v_lshl_add_u64 v[208:209], s[38:39], 0, v[200:201]
	s_addc_u32 s55, s39, 0
	s_add_i32 s56, s47, s0
	global_load_lds_dwordx4 v[208:209], off
	v_lshl_add_u64 v[210:211], s[54:55], 0, v[196:197]
	s_mov_b32 m0, s56
	v_lshl_add_u64 v[212:213], s[40:41], 0, v[198:199]
	global_load_lds_dwordx4 v[210:211], off
	v_lshl_add_u64 v[210:211], s[54:55], 0, v[200:201]
	s_add_i32 m0, s56, 0x2000
	s_nop 0
	global_load_lds_dwordx4 v[210:211], off
	v_lshl_add_u64 v[210:211], s[40:41], 0, v[194:195]
	s_waitcnt vmcnt(4)
	s_waitcnt lgkmcnt(0)
	s_barrier
	s_setprio 1
	s_waitcnt lgkmcnt(0)
	v_mfma_f32_16x16x32_bf16 v[62:65], v[114:117], v[162:165], v[62:65]
	v_mfma_f32_16x16x32_bf16 v[58:61], v[130:133], v[162:165], v[58:61]
	v_mfma_f32_16x16x32_bf16 v[46:49], v[114:117], v[170:173], v[46:49]
	v_mfma_f32_16x16x32_bf16 v[42:45], v[130:133], v[170:173], v[42:45]
	v_mfma_f32_16x16x32_bf16 v[30:33], v[114:117], v[178:181], v[30:33]
	v_mfma_f32_16x16x32_bf16 v[26:29], v[130:133], v[178:181], v[26:29]
	v_mfma_f32_16x16x32_bf16 v[14:17], v[114:117], v[186:189], v[14:17]
	v_mfma_f32_16x16x32_bf16 v[10:13], v[130:133], v[186:189], v[10:13]
	v_mfma_f32_16x16x32_bf16 v[62:65], v[118:121], v[166:169], v[62:65]
	v_mfma_f32_16x16x32_bf16 v[58:61], v[134:137], v[166:169], v[58:61]
	v_mfma_f32_16x16x32_bf16 v[46:49], v[118:121], v[174:177], v[46:49]
	v_mfma_f32_16x16x32_bf16 v[42:45], v[134:137], v[174:177], v[42:45]
	v_mfma_f32_16x16x32_bf16 v[30:33], v[118:121], v[182:185], v[30:33]
	v_mfma_f32_16x16x32_bf16 v[26:29], v[134:137], v[182:185], v[26:29]
	v_mfma_f32_16x16x32_bf16 v[14:17], v[118:121], v[190:193], v[14:17]
	v_mfma_f32_16x16x32_bf16 v[10:13], v[134:137], v[190:193], v[10:13]
	s_setprio 0
	s_setprio 1
	v_mfma_f32_16x16x32_bf16 v[54:57], v[138:141], v[162:165], v[54:57]
	v_mfma_f32_16x16x32_bf16 v[50:53], v[146:149], v[162:165], v[50:53]
	v_mfma_f32_16x16x32_bf16 v[38:41], v[138:141], v[170:173], v[38:41]
	v_mfma_f32_16x16x32_bf16 v[34:37], v[146:149], v[170:173], v[34:37]
	v_mfma_f32_16x16x32_bf16 v[22:25], v[138:141], v[178:181], v[22:25]
	v_mfma_f32_16x16x32_bf16 v[18:21], v[146:149], v[178:181], v[18:21]
	v_mfma_f32_16x16x32_bf16 v[6:9], v[138:141], v[186:189], v[6:9]
	v_mfma_f32_16x16x32_bf16 v[2:5], v[146:149], v[186:189], v[2:5]
	v_mfma_f32_16x16x32_bf16 v[54:57], v[142:145], v[166:169], v[54:57]
	v_mfma_f32_16x16x32_bf16 v[50:53], v[158:161], v[166:169], v[50:53]
	v_mfma_f32_16x16x32_bf16 v[38:41], v[142:145], v[174:177], v[38:41]
	v_mfma_f32_16x16x32_bf16 v[34:37], v[158:161], v[174:177], v[34:37]
	v_mfma_f32_16x16x32_bf16 v[22:25], v[142:145], v[182:185], v[22:25]
	v_mfma_f32_16x16x32_bf16 v[18:21], v[158:161], v[182:185], v[18:21]
	v_mfma_f32_16x16x32_bf16 v[6:9], v[142:145], v[190:193], v[6:9]
	v_mfma_f32_16x16x32_bf16 v[2:5], v[158:161], v[190:193], v[2:5]
	s_setprio 0
	s_barrier
; #define PG8_STAGE(bufoff, gbase, voff) do { _Pragma("unroll") for (int _i = 0; _i < 2; ++_i) \
;         __builtin_amdgcn_global_load_lds((const unsigned*)((const char*)(gbase) + (voff)[_i]), (PG8_LAS unsigned*)(lds + (bufoff) + ldsw + _i * 8192), 16, 0, 0); } while (0)
; #define PG8_LDA(dst, b, h) do { _Pragma("unroll") for (int m = 0; m < 4; ++m) _Pragma("unroll") for (int k = 0; k < 2; ++k) dst[m][k] = *(const PG8_LAS bf16x8*)(lds + PG8_SA(b, h) + aoff + m * 2048 + k * 1024); } while (0)
; #define PG8_LDB(dst, b, h) do { _Pragma("unroll") for (int n = 0; n < 2; ++n) _Pragma("unroll") for (int k = 0; k < 2; ++k) dst[n][k] = *(const PG8_LAS bf16x8*)(lds + PG8_SB(b, h) + boff + n * 2048 + k * 1024); } while (0)
; #define PG8_MMA(ai, bj, At, Bt) do { __builtin_amdgcn_s_setprio(1); _Pragma("unroll") for (int m = 0; m < 4; ++m) _Pragma("unroll") for (int n = 0; n < 2; ++n) _Pragma("unroll") for (int k = 0; k < 2; ++k) \
;         acc[ai][bj][m][n] = __builtin_amdgcn_mfma_f32_16x16x32_bf16(Bt[n][k], At[m][k], acc[ai][bj][m][n], 0, 0, 0); __builtin_amdgcn_s_setprio(0); } while (0)
; #define PG8_WAIT_V(n) asm volatile("s_waitcnt vmcnt(" #n ")" ::: "memory")
; #define PG8_WAIT_L(n) asm volatile("s_waitcnt lgkmcnt(" #n ")" ::: "memory")
; #define PG8_BAR __builtin_amdgcn_s_barrier()
; #define PG8_SCHED __builtin_amdgcn_sched_barrier(0)
; template <class Epi, class Sched, bool ALIGN_EPI = false, bool SP2 = false, bool HALFM = false>
; __device__ __forceinline__ void gemm_phase(PG8_LAS unsigned char* lds, const Gemm g, const Sched& S, const Epi& E) {
;     ...
;             PG8_LDB(B0, 1, 0); PG8_LDB(B1, 1, 1); PG8_SCHED; PG8_LDA(At, 1, 0); PG8_STAGE(PG8_SA(0, 1), a2 + hstep, voffA);
;             PG8_WAIT_V(8); PG8_WAIT_L(0); PG8_BAR; PG8_MMA(0, 0, At, B0); PG8_MMA(0, 1, At, B1); PG8_BAR; PG8_SCHED;
	s_add_i32 s54, 0, 0x18000
	s_add_i32 s55, 0, 0x1c000
	v_add_u32_e32 v134, s54, v244
	v_add_u32_e32 v158, s55, v244
	ds_read_b128 v[114:117], v134
	ds_read_b128 v[118:121], v134 offset:1024
	ds_read_b128 v[130:133], v134 offset:2048
	ds_read_b128 v[134:137], v134 offset:3072
	ds_read_b128 v[138:141], v158
	ds_read_b128 v[142:145], v158 offset:1024
	ds_read_b128 v[146:149], v158 offset:2048
	ds_read_b128 v[158:161], v158 offset:3072
	s_add_u32 s40, s40, 0x40000
	s_addc_u32 s41, s41, 0
	s_mov_b32 m0, s3
	v_lshl_add_u64 v[214:215], s[40:41], 0, v[194:195]
	ds_read_b128 v[162:165], v248 offset:32768
	ds_read_b128 v[166:169], v248 offset:33792
	ds_read_b128 v[170:173], v248 offset:34816
	ds_read_b128 v[174:177], v248 offset:35840
	ds_read_b128 v[178:181], v248 offset:36864
	ds_read_b128 v[182:185], v248 offset:37888
	ds_read_b128 v[186:189], v248 offset:38912
	ds_read_b128 v[190:193], v248 offset:39936
	global_load_lds_dwordx4 v[214:215], off
	v_lshl_add_u64 v[214:215], s[40:41], 0, v[198:199]
	s_mov_b32 m0, s35
	s_nop 0
	global_load_lds_dwordx4 v[214:215], off
	s_mov_b32 m0, s1
	s_nop 0
	global_load_lds_dwordx4 v[210:211], off
	s_mov_b32 m0, s2
	s_nop 0
	global_load_lds_dwordx4 v[212:213], off
	s_waitcnt vmcnt(10)
	s_waitcnt lgkmcnt(0)
	s_barrier
	s_setprio 1
	s_waitcnt lgkmcnt(0)
	v_mfma_f32_16x16x32_bf16 v[154:157], v[114:117], v[162:165], v[154:157]
	v_mfma_f32_16x16x32_bf16 v[150:153], v[130:133], v[162:165], v[150:153]
	v_mfma_f32_16x16x32_bf16 v[110:113], v[114:117], v[170:173], v[110:113]
	v_mfma_f32_16x16x32_bf16 v[106:109], v[130:133], v[170:173], v[106:109]
	v_mfma_f32_16x16x32_bf16 v[94:97], v[114:117], v[178:181], v[94:97]
	v_mfma_f32_16x16x32_bf16 v[90:93], v[130:133], v[178:181], v[90:93]
	v_mfma_f32_16x16x32_bf16 v[78:81], v[114:117], v[186:189], v[78:81]
	v_mfma_f32_16x16x32_bf16 v[74:77], v[130:133], v[186:189], v[74:77]
	v_mfma_f32_16x16x32_bf16 v[154:157], v[118:121], v[166:169], v[154:157]
	v_mfma_f32_16x16x32_bf16 v[150:153], v[134:137], v[166:169], v[150:153]
	v_mfma_f32_16x16x32_bf16 v[110:113], v[118:121], v[174:177], v[110:113]
	v_mfma_f32_16x16x32_bf16 v[106:109], v[134:137], v[174:177], v[106:109]
	v_mfma_f32_16x16x32_bf16 v[94:97], v[118:121], v[182:185], v[94:97]
	v_mfma_f32_16x16x32_bf16 v[90:93], v[134:137], v[182:185], v[90:93]
	v_mfma_f32_16x16x32_bf16 v[78:81], v[118:121], v[190:193], v[78:81]
	v_mfma_f32_16x16x32_bf16 v[74:77], v[134:137], v[190:193], v[74:77]
	s_setprio 0
	s_setprio 1
	v_mfma_f32_16x16x32_bf16 v[126:129], v[138:141], v[162:165], v[126:129]
	v_mfma_f32_16x16x32_bf16 v[122:125], v[146:149], v[162:165], v[122:125]
	v_mfma_f32_16x16x32_bf16 v[102:105], v[138:141], v[170:173], v[102:105]
	v_mfma_f32_16x16x32_bf16 v[98:101], v[146:149], v[170:173], v[98:101]
	v_mfma_f32_16x16x32_bf16 v[86:89], v[138:141], v[178:181], v[86:89]
	v_mfma_f32_16x16x32_bf16 v[82:85], v[146:149], v[178:181], v[82:85]
	v_mfma_f32_16x16x32_bf16 v[70:73], v[138:141], v[186:189], v[70:73]
	v_mfma_f32_16x16x32_bf16 v[66:69], v[146:149], v[186:189], v[66:69]
	v_mfma_f32_16x16x32_bf16 v[126:129], v[142:145], v[166:169], v[126:129]
	v_mfma_f32_16x16x32_bf16 v[122:125], v[158:161], v[166:169], v[122:125]
	v_mfma_f32_16x16x32_bf16 v[102:105], v[142:145], v[174:177], v[102:105]
	v_mfma_f32_16x16x32_bf16 v[98:101], v[158:161], v[174:177], v[98:101]
	v_mfma_f32_16x16x32_bf16 v[86:89], v[142:145], v[182:185], v[86:89]
	v_mfma_f32_16x16x32_bf16 v[82:85], v[158:161], v[182:185], v[82:85]
	v_mfma_f32_16x16x32_bf16 v[70:73], v[142:145], v[190:193], v[70:73]
	v_mfma_f32_16x16x32_bf16 v[66:69], v[158:161], v[190:193], v[66:69]
	s_setprio 0
	s_barrier
; #define PG8_STAGE(bufoff, gbase, voff) do { _Pragma("unroll") for (int _i = 0; _i < 2; ++_i) \
;         __builtin_amdgcn_global_load_lds((const unsigned*)((const char*)(gbase) + (voff)[_i]), (PG8_LAS unsigned*)(lds + (bufoff) + ldsw + _i * 8192), 16, 0, 0); } while (0)
; #define PG8_LDA(dst, b, h) do { _Pragma("unroll") for (int m = 0; m < 4; ++m) _Pragma("unroll") for (int k = 0; k < 2; ++k) dst[m][k] = *(const PG8_LAS bf16x8*)(lds + PG8_SA(b, h) + aoff + m * 2048 + k * 1024); } while (0)
; #define PG8_MMA(ai, bj, At, Bt) do { __builtin_amdgcn_s_setprio(1); _Pragma("unroll") for (int m = 0; m < 4; ++m) _Pragma("unroll") for (int n = 0; n < 2; ++n) _Pragma("unroll") for (int k = 0; k < 2; ++k) \
;         acc[ai][bj][m][n] = __builtin_amdgcn_mfma_f32_16x16x32_bf16(Bt[n][k], At[m][k], acc[ai][bj][m][n], 0, 0, 0); __builtin_amdgcn_s_setprio(0); } while (0)
; #define PG8_WAIT_V(n) asm volatile("s_waitcnt vmcnt(" #n ")" ::: "memory")
; #define PG8_WAIT_L(n) asm volatile("s_waitcnt lgkmcnt(" #n ")" ::: "memory")
; #define PG8_BAR __builtin_amdgcn_s_barrier()
; #define PG8_SCHED __builtin_amdgcn_sched_barrier(0)
; template <class Epi, class Sched, bool ALIGN_EPI = false, bool SP2 = false, bool HALFM = false>
; __device__ __forceinline__ void gemm_phase(PG8_LAS unsigned char* lds, const Gemm g, const Sched& S, const Epi& E) {
;     ...
;             PG8_LDA(At, 1, 1); PG8_STAGE(PG8_SB(1, 0), b3, voffB); PG8_STAGE(PG8_SB(1, 1), b3 + hstep, voffB); PG8_STAGE(PG8_SA(1, 0), a3, voffA);
;             PG8_WAIT_V(8); PG8_WAIT_L(0); PG8_BAR; if constexpr (!HALFM) { PG8_MMA(1, 0, At, B0); PG8_MMA(1, 1, At, B1); } PG8_BAR; PG8_SCHED;
	s_add_i32 s40, s54, s0
	v_lshl_add_u64 v[206:207], v[206:207], 0, s[10:11]
	s_mov_b32 m0, s40
	ds_read_b128 v[162:165], v248 offset:49152
	ds_read_b128 v[166:169], v248 offset:50176
	ds_read_b128 v[170:173], v248 offset:51200
	ds_read_b128 v[174:177], v248 offset:52224
	ds_read_b128 v[178:181], v248 offset:53248
	ds_read_b128 v[182:185], v248 offset:54272
	ds_read_b128 v[186:189], v248 offset:55296
	ds_read_b128 v[190:193], v248 offset:56320
	global_load_lds_dwordx4 v[206:207], off
	s_add_i32 m0, s40, 0x2000
	s_add_u32 s38, s38, 0x40080
	v_lshl_add_u64 v[206:207], v[208:209], 0, s[10:11]
	s_addc_u32 s39, s39, 0
	s_add_i32 s40, s55, s0
	global_load_lds_dwordx4 v[206:207], off
	v_lshl_add_u64 v[206:207], s[38:39], 0, v[196:197]
	s_mov_b32 m0, s40
	s_nop 0
	global_load_lds_dwordx4 v[206:207], off
	v_lshl_add_u64 v[206:207], s[38:39], 0, v[200:201]
	s_add_i32 m0, s40, 0x2000
	s_nop 0
	global_load_lds_dwordx4 v[206:207], off
	s_waitcnt vmcnt(4)
	s_waitcnt lgkmcnt(0)
	s_barrier
	s_setprio 1
	s_waitcnt lgkmcnt(0)
	v_mfma_f32_16x16x32_bf16 v[62:65], v[114:117], v[162:165], v[62:65]
	v_mfma_f32_16x16x32_bf16 v[58:61], v[130:133], v[162:165], v[58:61]
	v_mfma_f32_16x16x32_bf16 v[46:49], v[114:117], v[170:173], v[46:49]
	v_mfma_f32_16x16x32_bf16 v[42:45], v[130:133], v[170:173], v[42:45]
	v_mfma_f32_16x16x32_bf16 v[30:33], v[114:117], v[178:181], v[30:33]
	v_mfma_f32_16x16x32_bf16 v[26:29], v[130:133], v[178:181], v[26:29]
	v_mfma_f32_16x16x32_bf16 v[14:17], v[114:117], v[186:189], v[14:17]
	v_mfma_f32_16x16x32_bf16 v[10:13], v[130:133], v[186:189], v[10:13]
	v_mfma_f32_16x16x32_bf16 v[62:65], v[118:121], v[166:169], v[62:65]
	v_mfma_f32_16x16x32_bf16 v[58:61], v[134:137], v[166:169], v[58:61]
	v_mfma_f32_16x16x32_bf16 v[46:49], v[118:121], v[174:177], v[46:49]
	v_mfma_f32_16x16x32_bf16 v[42:45], v[134:137], v[174:177], v[42:45]
	v_mfma_f32_16x16x32_bf16 v[30:33], v[118:121], v[182:185], v[30:33]
	v_mfma_f32_16x16x32_bf16 v[26:29], v[134:137], v[182:185], v[26:29]
	v_mfma_f32_16x16x32_bf16 v[14:17], v[118:121], v[190:193], v[14:17]
	v_mfma_f32_16x16x32_bf16 v[10:13], v[134:137], v[190:193], v[10:13]
	s_setprio 0
	s_setprio 1
	v_mfma_f32_16x16x32_bf16 v[54:57], v[138:141], v[162:165], v[54:57]
	v_mfma_f32_16x16x32_bf16 v[50:53], v[146:149], v[162:165], v[50:53]
	v_mfma_f32_16x16x32_bf16 v[38:41], v[138:141], v[170:173], v[38:41]
	v_mfma_f32_16x16x32_bf16 v[34:37], v[146:149], v[170:173], v[34:37]
	v_mfma_f32_16x16x32_bf16 v[22:25], v[138:141], v[178:181], v[22:25]
	v_mfma_f32_16x16x32_bf16 v[18:21], v[146:149], v[178:181], v[18:21]
	v_mfma_f32_16x16x32_bf16 v[6:9], v[138:141], v[186:189], v[6:9]
	v_mfma_f32_16x16x32_bf16 v[2:5], v[146:149], v[186:189], v[2:5]
	v_mfma_f32_16x16x32_bf16 v[54:57], v[142:145], v[166:169], v[54:57]
	v_mfma_f32_16x16x32_bf16 v[50:53], v[158:161], v[166:169], v[50:53]
	v_mfma_f32_16x16x32_bf16 v[38:41], v[142:145], v[174:177], v[38:41]
	v_mfma_f32_16x16x32_bf16 v[34:37], v[158:161], v[174:177], v[34:37]
	v_mfma_f32_16x16x32_bf16 v[22:25], v[142:145], v[182:185], v[22:25]
	v_mfma_f32_16x16x32_bf16 v[18:21], v[158:161], v[182:185], v[18:21]
	v_mfma_f32_16x16x32_bf16 v[6:9], v[142:145], v[190:193], v[6:9]
	v_mfma_f32_16x16x32_bf16 v[2:5], v[158:161], v[190:193], v[2:5]
	s_setprio 0
	s_barrier
	s_add_i32 s53, s53, 2
	s_add_u32 s36, s36, 0x100
	s_addc_u32 s37, s37, 0
	s_add_u32 s51, s51, 0x100
	s_addc_u32 s52, s52, 0
	s_cmp_gt_u32 s53, 13
	s_cbranch_scc0 .LBB0_1692
	s_and_b64 vcc, exec, s[14:15]
	s_cbranch_vccz .LBB0_1695
	s_barrier

;     __device__ __forceinline__ bool next(int i, Unit& u) const { const int L = L0 + i * G + c; if (L >= L1) return false; u.pm = L >> 2; u.pn = L & 3; u.ko = 0; return true; }
; #define PG8_STAGE(bufoff, gbase, voff) do { _Pragma("unroll") for (int _i = 0; _i < 2; ++_i) \
;         __builtin_amdgcn_global_load_lds((const unsigned*)((const char*)(gbase) + (voff)[_i]), (PG8_LAS unsigned*)(lds + (bufoff) + ldsw + _i * 8192), 16, 0, 0); } while (0)
; #define PG8_LDA(dst, b, h) do { _Pragma("unroll") for (int m = 0; m < 4; ++m) _Pragma("unroll") for (int k = 0; k < 2; ++k) dst[m][k] = *(const PG8_LAS bf16x8*)(lds + PG8_SA(b, h) + aoff + m * 2048 + k * 1024); } while (0)
; #define PG8_LDB(dst, b, h) do { _Pragma("unroll") for (int n = 0; n < 2; ++n) _Pragma("unroll") for (int k = 0; k < 2; ++k) dst[n][k] = *(const PG8_LAS bf16x8*)(lds + PG8_SB(b, h) + boff + n * 2048 + k * 1024); } while (0)
; template <class Epi, class Sched, bool ALIGN_EPI = false, bool SP2 = false, bool HALFM = false>
; __device__ __forceinline__ void gemm_phase(PG8_LAS unsigned char* lds, const Gemm g, const Sched& S, const Epi& E) {
;     ...
;         const bool has_next = S.next(ui + 1, nxt);
;         const char* nA = has_next ? (const char*)g.A + (size_t)nxt.pm * tstep + (size_t)nxt.ko * 2 : cA; const char* nB = has_next ? (const char*)g.Bt + (size_t)nxt.pn * tstep + (size_t)nxt.ko * 2 : cB;
;         for (int t = 0; t < nt; t += 2) {
;             const bool last = (t == nt - 2);
;             const char* a1 = cA + (size_t)(t + 1) * kstep;
;             const char* a2 = last ? nA : cA + (size_t)(t + 2) * kstep; const char* b2 = last ? nB : cB + (size_t)(t + 2) * kstep;
;             const char* a3 = a2 + kstep; const char* b3 = b2 + kstep;
;             if (last && has_next) S.a_ready(nxt);
;             if constexpr (SP2) {
;             PG8_LDB(B0, 0, 0); PG8_LDB(B1, 0, 1); PG8_SCHED; PG8_LDA(At, 0, 0); PG8_STAGE(PG8_SA(1, 1), a1 + hstep, voffA);
;             PG8_WAIT_V(8); PG8_WAIT_L(0); PG8_BAR; PG8_MMA(0, 0, At, B0); PG8_MMA(0, 1, At, B1); PG8_BAR; PG8_SCHED;
;     ...
;         for (int a = 0; a < 2; ++a)
; #pragma unroll
;             for (int b = 0; b < 2; ++b)
; #pragma unroll
;                 for (int m = 0; m < 4; ++m)
; #pragma unroll
;                     for (int n = 0; n < 2; ++n) acc[a][b][m][n] = (f32x4){0.f, 0.f, 0.f, 0.f};
;         cur = nxt; cA = nA; cB = nB; ++ui;
.LBB0_1804:
	s_ashr_i32 s27, s26, 31
	s_lshl_b64 s[28:29], s[26:27], 19
	s_add_u32 s28, s80, s28
	s_addc_u32 s29, s81, s29
	s_and_b64 s[30:31], s[10:11], exec
	s_cselect_b32 s27, s29, s37
	s_cselect_b32 s53, s28, s36
	s_ashr_i32 s25, s24, 31
	s_lshl_b64 s[30:31], s[24:25], 19
	s_add_u32 s30, s46, s30
	s_addc_u32 s31, s47, s31
	s_and_b64 s[40:41], s[10:11], exec
	s_cselect_b32 s25, s31, s39
	s_cselect_b32 s54, s30, s38
	s_add_u32 s36, s36, 0x40080
	s_addc_u32 s37, s37, 0
	s_add_u32 s55, s38, 0x100
	v_mov_b32_e32 v2, 0
	s_addc_u32 s56, s39, 0
	s_mov_b32 s57, -2
	v_mov_b32_e32 v3, v2
	v_mov_b32_e32 v4, v2
	v_mov_b32_e32 v5, v2
	v_mov_b32_e32 v6, v2
	v_mov_b32_e32 v7, v2
	v_mov_b32_e32 v8, v2
	v_mov_b32_e32 v9, v2
	v_mov_b32_e32 v18, v2
	v_mov_b32_e32 v19, v2
	v_mov_b32_e32 v20, v2
	v_mov_b32_e32 v21, v2
	v_mov_b32_e32 v22, v2
	v_mov_b32_e32 v23, v2
	v_mov_b32_e32 v24, v2
	v_mov_b32_e32 v25, v2
	v_mov_b32_e32 v34, v2
	v_mov_b32_e32 v35, v2
	v_mov_b32_e32 v36, v2
	v_mov_b32_e32 v37, v2
	v_mov_b32_e32 v38, v2
	v_mov_b32_e32 v39, v2
	v_mov_b32_e32 v40, v2
	v_mov_b32_e32 v41, v2
	v_mov_b32_e32 v50, v2
	v_mov_b32_e32 v51, v2
	v_mov_b32_e32 v52, v2
	v_mov_b32_e32 v53, v2
	v_mov_b32_e32 v54, v2
	v_mov_b32_e32 v55, v2
	v_mov_b32_e32 v56, v2
	v_mov_b32_e32 v57, v2
	v_mov_b32_e32 v10, v2
	v_mov_b32_e32 v11, v2
	v_mov_b32_e32 v12, v2
	v_mov_b32_e32 v13, v2
	v_mov_b32_e32 v14, v2
	v_mov_b32_e32 v15, v2
	v_mov_b32_e32 v16, v2
	v_mov_b32_e32 v17, v2
	v_mov_b32_e32 v26, v2
	v_mov_b32_e32 v27, v2
	v_mov_b32_e32 v28, v2
	v_mov_b32_e32 v29, v2
	v_mov_b32_e32 v30, v2
	v_mov_b32_e32 v31, v2
	v_mov_b32_e32 v32, v2
	v_mov_b32_e32 v33, v2
	v_mov_b32_e32 v42, v2
	v_mov_b32_e32 v43, v2
	v_mov_b32_e32 v44, v2
	v_mov_b32_e32 v45, v2
	v_mov_b32_e32 v46, v2
	v_mov_b32_e32 v47, v2
	v_mov_b32_e32 v48, v2
	v_mov_b32_e32 v49, v2
	v_mov_b32_e32 v58, v2
	v_mov_b32_e32 v59, v2
	v_mov_b32_e32 v60, v2
	v_mov_b32_e32 v61, v2
	v_mov_b32_e32 v62, v2
	v_mov_b32_e32 v63, v2
	v_mov_b32_e32 v64, v2
	v_mov_b32_e32 v65, v2
	v_mov_b32_e32 v66, v2
	v_mov_b32_e32 v67, v2
	v_mov_b32_e32 v68, v2
	v_mov_b32_e32 v69, v2
	v_mov_b32_e32 v70, v2
	v_mov_b32_e32 v71, v2
	v_mov_b32_e32 v72, v2
	v_mov_b32_e32 v73, v2
	v_mov_b32_e32 v82, v2
	v_mov_b32_e32 v83, v2
	v_mov_b32_e32 v84, v2
	v_mov_b32_e32 v85, v2
	v_mov_b32_e32 v86, v2
	v_mov_b32_e32 v87, v2
	v_mov_b32_e32 v88, v2
	v_mov_b32_e32 v89, v2
	v_mov_b32_e32 v98, v2
	v_mov_b32_e32 v99, v2
	v_mov_b32_e32 v100, v2
	v_mov_b32_e32 v101, v2
	v_mov_b32_e32 v102, v2
	v_mov_b32_e32 v103, v2
	v_mov_b32_e32 v104, v2
	v_mov_b32_e32 v105, v2
	v_mov_b32_e32 v122, v2
	v_mov_b32_e32 v123, v2
	v_mov_b32_e32 v124, v2
	v_mov_b32_e32 v125, v2
	v_mov_b32_e32 v126, v2
	v_mov_b32_e32 v127, v2
	v_mov_b32_e32 v128, v2
	v_mov_b32_e32 v129, v2
	v_mov_b32_e32 v74, v2
	v_mov_b32_e32 v75, v2
	v_mov_b32_e32 v76, v2
	v_mov_b32_e32 v77, v2
	v_mov_b32_e32 v78, v2
	v_mov_b32_e32 v79, v2
	v_mov_b32_e32 v80, v2
	v_mov_b32_e32 v81, v2
	v_mov_b32_e32 v90, v2
	v_mov_b32_e32 v91, v2
	v_mov_b32_e32 v92, v2
	v_mov_b32_e32 v93, v2
	v_mov_b32_e32 v94, v2
	v_mov_b32_e32 v95, v2
	v_mov_b32_e32 v96, v2
	v_mov_b32_e32 v97, v2
	v_mov_b32_e32 v106, v2
	v_mov_b32_e32 v107, v2
	v_mov_b32_e32 v108, v2
	v_mov_b32_e32 v109, v2
	v_mov_b32_e32 v110, v2
	v_mov_b32_e32 v111, v2
	v_mov_b32_e32 v112, v2
	v_mov_b32_e32 v113, v2
	v_mov_b32_e32 v114, v2
	v_mov_b32_e32 v115, v2
	v_mov_b32_e32 v116, v2
	v_mov_b32_e32 v117, v2
	v_mov_b32_e32 v118, v2
	v_mov_b32_e32 v119, v2
	v_mov_b32_e32 v120, v2
	v_mov_b32_e32 v121, v2
	s_mov_b32 s100, 0xfffbff80
	s_mov_b32 s101, -1
	v_lshl_add_u64 v[220:221], s[36:37], 0, v[138:139]
	v_lshl_add_u64 v[220:221], v[220:221], 0, s[100:101]
	v_lshl_add_u64 v[222:223], s[36:37], 0, v[140:141]
	v_lshl_add_u64 v[222:223], v[222:223], 0, s[100:101]
.LBB0_1805:
	ds_read_b128 v[154:157], v150
	ds_read_b128 v[158:161], v150 offset:1024
	ds_read_b128 v[162:165], v150 offset:2048
	ds_read_b128 v[166:169], v150 offset:3072
	ds_read_b128 v[170:173], v151
	ds_read_b128 v[174:177], v151 offset:1024
	ds_read_b128 v[178:181], v151 offset:2048
	ds_read_b128 v[182:185], v151 offset:3072
	s_add_u32 s38, s36, 0xfffc0080
	s_addc_u32 s39, s37, -1
	s_cmp_eq_u32 s57, 12
	s_cselect_b32 s41, s27, s39
	s_cselect_b32 s40, s53, s38
	s_cselect_b32 s39, s25, s56
	s_cselect_b32 s38, s54, s55
	v_lshl_add_u64 v[146:147], s[36:37], 0, v[138:139]
	s_add_i32 m0, s2, 0xc000
	ds_read_b128 v[186:189], v152
	ds_read_b128 v[190:193], v152 offset:1024
	ds_read_b128 v[194:197], v152 offset:2048
	ds_read_b128 v[198:201], v152 offset:3072
	ds_read_b128 v[202:205], v152 offset:4096
	ds_read_b128 v[206:209], v152 offset:5120
	ds_read_b128 v[210:213], v152 offset:6144
	ds_read_b128 v[214:217], v152 offset:7168
	global_load_lds_dwordx4 v[146:147], off
	v_lshl_add_u64 v[146:147], s[36:37], 0, v[140:141]
	s_add_i32 m0, s2, 0xe000
	s_nop 0
	global_load_lds_dwordx4 v[146:147], off
	s_mov_b32 m0, s44
	v_lshl_add_u64 v[146:147], v[220:221], 0, s[14:15]
	global_load_lds_dwordx4 v[146:147], off
	s_mov_b32 m0, s45
	v_lshl_add_u64 v[146:147], v[222:223], 0, s[14:15]
	global_load_lds_dwordx4 v[146:147], off
	s_waitcnt vmcnt(10)
	s_waitcnt lgkmcnt(0)
	s_barrier
; #define PG8_STAGE(bufoff, gbase, voff) do { _Pragma("unroll") for (int _i = 0; _i < 2; ++_i) \
;         __builtin_amdgcn_global_load_lds((const unsigned*)((const char*)(gbase) + (voff)[_i]), (PG8_LAS unsigned*)(lds + (bufoff) + ldsw + _i * 8192), 16, 0, 0); } while (0)
; #define PG8_LDA(dst, b, h) do { _Pragma("unroll") for (int m = 0; m < 4; ++m) _Pragma("unroll") for (int k = 0; k < 2; ++k) dst[m][k] = *(const PG8_LAS bf16x8*)(lds + PG8_SA(b, h) + aoff + m * 2048 + k * 1024); } while (0)
; #define PG8_LDB(dst, b, h) do { _Pragma("unroll") for (int n = 0; n < 2; ++n) _Pragma("unroll") for (int k = 0; k < 2; ++k) dst[n][k] = *(const PG8_LAS bf16x8*)(lds + PG8_SB(b, h) + boff + n * 2048 + k * 1024); } while (0)
; template <class Epi, class Sched, bool ALIGN_EPI = false, bool SP2 = false, bool HALFM = false>
; __device__ __forceinline__ void gemm_phase(PG8_LAS unsigned char* lds, const Gemm g, const Sched& S, const Epi& E) {
;     ...
;             const char* a1 = cA + (size_t)(t + 1) * kstep;
;             const char* a2 = last ? nA : cA + (size_t)(t + 2) * kstep; const char* b2 = last ? nB : cB + (size_t)(t + 2) * kstep;
;             const char* a3 = a2 + kstep; const char* b3 = b2 + kstep;
;             if (last && has_next) S.a_ready(nxt);
;             if constexpr (SP2) {
;             PG8_LDB(B0, 0, 0); PG8_LDB(B1, 0, 1); PG8_SCHED; PG8_LDA(At, 0, 0); PG8_STAGE(PG8_SA(1, 1), a1 + hstep, voffA);
;             PG8_WAIT_V(8); PG8_WAIT_L(0); PG8_BAR; PG8_MMA(0, 0, At, B0); PG8_MMA(0, 1, At, B1); PG8_BAR; PG8_SCHED;
;             PG8_LDA(At, 0, 1); PG8_STAGE(PG8_SB(0, 0), b2, voffB); PG8_STAGE(PG8_SB(0, 1), b2 + hstep, voffB); PG8_STAGE(PG8_SA(0, 0), a2, voffA);
;             PG8_WAIT_V(8); PG8_WAIT_L(0); PG8_BAR; if constexpr (!HALFM) { PG8_MMA(1, 0, At, B0); PG8_MMA(1, 1, At, B1); } PG8_BAR; PG8_SCHED;
;             PG8_LDB(B0, 1, 0); PG8_LDB(B1, 1, 1); PG8_SCHED; PG8_LDA(At, 1, 0); PG8_STAGE(PG8_SA(0, 1), a2 + hstep, voffA);
;             PG8_WAIT_V(8); PG8_WAIT_L(0); PG8_BAR; PG8_MMA(0, 0, At, B0); PG8_MMA(0, 1, At, B1); PG8_BAR; PG8_SCHED;
;             PG8_LDA(At, 1, 1); PG8_STAGE(PG8_SB(1, 0), b3, voffB); PG8_STAGE(PG8_SB(1, 1), b3 + hstep, voffB); PG8_STAGE(PG8_SA(1, 0), a3, voffA);
;             PG8_WAIT_V(8); PG8_WAIT_L(0); PG8_BAR; if constexpr (!HALFM) { PG8_MMA(1, 0, At, B0); PG8_MMA(1, 1, At, B1); } PG8_BAR; PG8_SCHED;
	s_setprio 1
	s_waitcnt lgkmcnt(0)
	v_mfma_f32_16x16x32_bf16 v[118:121], v[154:157], v[186:189], v[118:121]
	v_mfma_f32_16x16x32_bf16 v[114:117], v[162:165], v[186:189], v[114:117]
	v_mfma_f32_16x16x32_bf16 v[110:113], v[154:157], v[194:197], v[110:113]
	v_mfma_f32_16x16x32_bf16 v[106:109], v[162:165], v[194:197], v[106:109]
	v_mfma_f32_16x16x32_bf16 v[94:97], v[154:157], v[202:205], v[94:97]
	v_mfma_f32_16x16x32_bf16 v[90:93], v[162:165], v[202:205], v[90:93]
	v_mfma_f32_16x16x32_bf16 v[78:81], v[154:157], v[210:213], v[78:81]
	v_mfma_f32_16x16x32_bf16 v[74:77], v[162:165], v[210:213], v[74:77]
	v_mfma_f32_16x16x32_bf16 v[118:121], v[158:161], v[190:193], v[118:121]
	v_mfma_f32_16x16x32_bf16 v[114:117], v[166:169], v[190:193], v[114:117]
	v_mfma_f32_16x16x32_bf16 v[110:113], v[158:161], v[198:201], v[110:113]
	v_mfma_f32_16x16x32_bf16 v[106:109], v[166:169], v[198:201], v[106:109]
	v_mfma_f32_16x16x32_bf16 v[94:97], v[158:161], v[206:209], v[94:97]
	v_mfma_f32_16x16x32_bf16 v[90:93], v[166:169], v[206:209], v[90:93]
	v_mfma_f32_16x16x32_bf16 v[78:81], v[158:161], v[214:217], v[78:81]
	v_mfma_f32_16x16x32_bf16 v[74:77], v[166:169], v[214:217], v[74:77]
	s_setprio 0
	s_setprio 1
	v_mfma_f32_16x16x32_bf16 v[126:129], v[170:173], v[186:189], v[126:129]
	v_mfma_f32_16x16x32_bf16 v[122:125], v[178:181], v[186:189], v[122:125]
	v_mfma_f32_16x16x32_bf16 v[102:105], v[170:173], v[194:197], v[102:105]
	v_mfma_f32_16x16x32_bf16 v[98:101], v[178:181], v[194:197], v[98:101]
	v_mfma_f32_16x16x32_bf16 v[86:89], v[170:173], v[202:205], v[86:89]
	v_mfma_f32_16x16x32_bf16 v[82:85], v[178:181], v[202:205], v[82:85]
	v_mfma_f32_16x16x32_bf16 v[70:73], v[170:173], v[210:213], v[70:73]
	v_mfma_f32_16x16x32_bf16 v[66:69], v[178:181], v[210:213], v[66:69]
	v_mfma_f32_16x16x32_bf16 v[126:129], v[174:177], v[190:193], v[126:129]
	v_mfma_f32_16x16x32_bf16 v[122:125], v[182:185], v[190:193], v[122:125]
	v_mfma_f32_16x16x32_bf16 v[102:105], v[174:177], v[198:201], v[102:105]
	v_mfma_f32_16x16x32_bf16 v[98:101], v[182:185], v[198:201], v[98:101]
	v_mfma_f32_16x16x32_bf16 v[86:89], v[174:177], v[206:209], v[86:89]
	v_mfma_f32_16x16x32_bf16 v[82:85], v[182:185], v[206:209], v[82:85]
	v_mfma_f32_16x16x32_bf16 v[70:73], v[174:177], v[214:217], v[70:73]
	v_mfma_f32_16x16x32_bf16 v[66:69], v[182:185], v[214:217], v[66:69]
	s_setprio 0
	s_barrier
	s_add_i32 s58, s49, s0
	v_lshl_add_u64 v[146:147], s[38:39], 0, v[134:135]
	s_mov_b32 m0, s58
	ds_read_b128 v[186:189], v152 offset:16384
	ds_read_b128 v[190:193], v152 offset:17408
	ds_read_b128 v[194:197], v152 offset:18432
	ds_read_b128 v[198:201], v152 offset:19456
	ds_read_b128 v[202:205], v152 offset:20480
	ds_read_b128 v[206:209], v152 offset:21504
	ds_read_b128 v[210:213], v152 offset:22528
	ds_read_b128 v[214:217], v152 offset:23552
	global_load_lds_dwordx4 v[146:147], off
	s_add_i32 m0, s58, 0x2000
	s_add_u32 s58, s38, 0x40000
	v_lshl_add_u64 v[218:219], s[38:39], 0, v[130:131]
	s_addc_u32 s59, s39, 0
	s_add_i32 s60, s50, s0
	global_load_lds_dwordx4 v[218:219], off
	v_lshl_add_u64 v[220:221], s[58:59], 0, v[134:135]
	s_mov_b32 m0, s60
	v_lshl_add_u64 v[222:223], s[40:41], 0, v[132:133]
	global_load_lds_dwordx4 v[220:221], off
	v_lshl_add_u64 v[220:221], s[58:59], 0, v[130:131]
	s_add_i32 m0, s60, 0x2000
	s_nop 0
	global_load_lds_dwordx4 v[220:221], off
	v_lshl_add_u64 v[220:221], s[40:41], 0, v[136:137]
	s_waitcnt vmcnt(4)
	s_waitcnt lgkmcnt(0)
	s_barrier
	s_setprio 1
	s_waitcnt lgkmcnt(0)
	v_mfma_f32_16x16x32_bf16 v[62:65], v[154:157], v[186:189], v[62:65]
	v_mfma_f32_16x16x32_bf16 v[58:61], v[162:165], v[186:189], v[58:61]
	v_mfma_f32_16x16x32_bf16 v[46:49], v[154:157], v[194:197], v[46:49]
	v_mfma_f32_16x16x32_bf16 v[42:45], v[162:165], v[194:197], v[42:45]
	v_mfma_f32_16x16x32_bf16 v[30:33], v[154:157], v[202:205], v[30:33]
	v_mfma_f32_16x16x32_bf16 v[26:29], v[162:165], v[202:205], v[26:29]
	v_mfma_f32_16x16x32_bf16 v[14:17], v[154:157], v[210:213], v[14:17]
	v_mfma_f32_16x16x32_bf16 v[10:13], v[162:165], v[210:213], v[10:13]
	v_mfma_f32_16x16x32_bf16 v[62:65], v[158:161], v[190:193], v[62:65]
	v_mfma_f32_16x16x32_bf16 v[58:61], v[166:169], v[190:193], v[58:61]
	v_mfma_f32_16x16x32_bf16 v[46:49], v[158:161], v[198:201], v[46:49]
	v_mfma_f32_16x16x32_bf16 v[42:45], v[166:169], v[198:201], v[42:45]
	v_mfma_f32_16x16x32_bf16 v[30:33], v[158:161], v[206:209], v[30:33]
	v_mfma_f32_16x16x32_bf16 v[26:29], v[166:169], v[206:209], v[26:29]
	v_mfma_f32_16x16x32_bf16 v[14:17], v[158:161], v[214:217], v[14:17]
	v_mfma_f32_16x16x32_bf16 v[10:13], v[166:169], v[214:217], v[10:13]
	s_setprio 0
	s_setprio 1
	v_mfma_f32_16x16x32_bf16 v[54:57], v[170:173], v[186:189], v[54:57]
	v_mfma_f32_16x16x32_bf16 v[50:53], v[178:181], v[186:189], v[50:53]
	v_mfma_f32_16x16x32_bf16 v[38:41], v[170:173], v[194:197], v[38:41]
	v_mfma_f32_16x16x32_bf16 v[34:37], v[178:181], v[194:197], v[34:37]
	v_mfma_f32_16x16x32_bf16 v[22:25], v[170:173], v[202:205], v[22:25]
	v_mfma_f32_16x16x32_bf16 v[18:21], v[178:181], v[202:205], v[18:21]
	v_mfma_f32_16x16x32_bf16 v[6:9], v[170:173], v[210:213], v[6:9]
	v_mfma_f32_16x16x32_bf16 v[2:5], v[178:181], v[210:213], v[2:5]
	v_mfma_f32_16x16x32_bf16 v[54:57], v[174:177], v[190:193], v[54:57]
	v_mfma_f32_16x16x32_bf16 v[50:53], v[182:185], v[190:193], v[50:53]
	v_mfma_f32_16x16x32_bf16 v[38:41], v[174:177], v[198:201], v[38:41]
	v_mfma_f32_16x16x32_bf16 v[34:37], v[182:185], v[198:201], v[34:37]
	v_mfma_f32_16x16x32_bf16 v[22:25], v[174:177], v[206:209], v[22:25]
	v_mfma_f32_16x16x32_bf16 v[18:21], v[182:185], v[206:209], v[18:21]
	v_mfma_f32_16x16x32_bf16 v[6:9], v[174:177], v[214:217], v[6:9]
	v_mfma_f32_16x16x32_bf16 v[2:5], v[182:185], v[214:217], v[2:5]
	s_setprio 0
	s_barrier
; #define PG8_STAGE(bufoff, gbase, voff) do { _Pragma("unroll") for (int _i = 0; _i < 2; ++_i) \
;         __builtin_amdgcn_global_load_lds((const unsigned*)((const char*)(gbase) + (voff)[_i]), (PG8_LAS unsigned*)(lds + (bufoff) + ldsw + _i * 8192), 16, 0, 0); } while (0)
; #define PG8_LDA(dst, b, h) do { _Pragma("unroll") for (int m = 0; m < 4; ++m) _Pragma("unroll") for (int k = 0; k < 2; ++k) dst[m][k] = *(const PG8_LAS bf16x8*)(lds + PG8_SA(b, h) + aoff + m * 2048 + k * 1024); } while (0)
; #define PG8_LDB(dst, b, h) do { _Pragma("unroll") for (int n = 0; n < 2; ++n) _Pragma("unroll") for (int k = 0; k < 2; ++k) dst[n][k] = *(const PG8_LAS bf16x8*)(lds + PG8_SB(b, h) + boff + n * 2048 + k * 1024); } while (0)
; #define PG8_MMA(ai, bj, At, Bt) do { __builtin_amdgcn_s_setprio(1); _Pragma("unroll") for (int m = 0; m < 4; ++m) _Pragma("unroll") for (int n = 0; n < 2; ++n) _Pragma("unroll") for (int k = 0; k < 2; ++k) \
;         acc[ai][bj][m][n] = __builtin_amdgcn_mfma_f32_16x16x32_bf16(Bt[n][k], At[m][k], acc[ai][bj][m][n], 0, 0, 0); __builtin_amdgcn_s_setprio(0); } while (0)
; #define PG8_WAIT_V(n) asm volatile("s_waitcnt vmcnt(" #n ")" ::: "memory")
; #define PG8_WAIT_L(n) asm volatile("s_waitcnt lgkmcnt(" #n ")" ::: "memory")
; #define PG8_BAR __builtin_amdgcn_s_barrier()
; #define PG8_SCHED __builtin_amdgcn_sched_barrier(0)
; template <class Epi, class Sched, bool ALIGN_EPI = false, bool SP2 = false, bool HALFM = false>
; __device__ __forceinline__ void gemm_phase(PG8_LAS unsigned char* lds, const Gemm g, const Sched& S, const Epi& E) {
;     ...
;             PG8_LDB(B0, 1, 0); PG8_LDB(B1, 1, 1); PG8_SCHED; PG8_LDA(At, 1, 0); PG8_STAGE(PG8_SA(0, 1), a2 + hstep, voffA);
;             PG8_WAIT_V(8); PG8_WAIT_L(0); PG8_BAR; PG8_MMA(0, 0, At, B0); PG8_MMA(0, 1, At, B1); PG8_BAR; PG8_SCHED;
	s_add_i32 s58, 0, 0x18000
	s_add_i32 s59, 0, 0x1c000
	v_add_u32_e32 v166, s58, v148
	v_add_u32_e32 v182, s59, v148
	ds_read_b128 v[154:157], v166
	ds_read_b128 v[158:161], v166 offset:1024
	ds_read_b128 v[162:165], v166 offset:2048
	ds_read_b128 v[166:169], v166 offset:3072
	ds_read_b128 v[170:173], v182
	ds_read_b128 v[174:177], v182 offset:1024
	ds_read_b128 v[178:181], v182 offset:2048
	ds_read_b128 v[182:185], v182 offset:3072
	s_add_u32 s40, s40, 0x40000
	s_addc_u32 s41, s41, 0
	s_mov_b32 m0, s35
	v_lshl_add_u64 v[224:225], s[40:41], 0, v[136:137]
	ds_read_b128 v[186:189], v152 offset:32768
	ds_read_b128 v[190:193], v152 offset:33792
	ds_read_b128 v[194:197], v152 offset:34816
	ds_read_b128 v[198:201], v152 offset:35840
	ds_read_b128 v[202:205], v152 offset:36864
	ds_read_b128 v[206:209], v152 offset:37888
	ds_read_b128 v[210:213], v152 offset:38912
	ds_read_b128 v[214:217], v152 offset:39936
	global_load_lds_dwordx4 v[224:225], off
	v_lshl_add_u64 v[224:225], s[40:41], 0, v[132:133]
	s_mov_b32 m0, s42
	s_nop 0
	global_load_lds_dwordx4 v[224:225], off
	s_mov_b32 m0, s2
	s_nop 0
	global_load_lds_dwordx4 v[220:221], off
	s_mov_b32 m0, s3
	s_nop 0
	global_load_lds_dwordx4 v[222:223], off
	s_waitcnt vmcnt(10)
	s_waitcnt lgkmcnt(0)
	s_barrier
	s_setprio 1
	s_waitcnt lgkmcnt(0)
	v_mfma_f32_16x16x32_bf16 v[118:121], v[154:157], v[186:189], v[118:121]
	v_mfma_f32_16x16x32_bf16 v[114:117], v[162:165], v[186:189], v[114:117]
	v_mfma_f32_16x16x32_bf16 v[110:113], v[154:157], v[194:197], v[110:113]
	v_mfma_f32_16x16x32_bf16 v[106:109], v[162:165], v[194:197], v[106:109]
	v_mfma_f32_16x16x32_bf16 v[94:97], v[154:157], v[202:205], v[94:97]
	v_mfma_f32_16x16x32_bf16 v[90:93], v[162:165], v[202:205], v[90:93]
	v_mfma_f32_16x16x32_bf16 v[78:81], v[154:157], v[210:213], v[78:81]
	v_mfma_f32_16x16x32_bf16 v[74:77], v[162:165], v[210:213], v[74:77]
	v_mfma_f32_16x16x32_bf16 v[118:121], v[158:161], v[190:193], v[118:121]
	v_mfma_f32_16x16x32_bf16 v[114:117], v[166:169], v[190:193], v[114:117]
	v_mfma_f32_16x16x32_bf16 v[110:113], v[158:161], v[198:201], v[110:113]
	v_mfma_f32_16x16x32_bf16 v[106:109], v[166:169], v[198:201], v[106:109]
	v_mfma_f32_16x16x32_bf16 v[94:97], v[158:161], v[206:209], v[94:97]
	v_mfma_f32_16x16x32_bf16 v[90:93], v[166:169], v[206:209], v[90:93]
	v_mfma_f32_16x16x32_bf16 v[78:81], v[158:161], v[214:217], v[78:81]
	v_mfma_f32_16x16x32_bf16 v[74:77], v[166:169], v[214:217], v[74:77]
	s_setprio 0
	s_setprio 1
	v_mfma_f32_16x16x32_bf16 v[126:129], v[170:173], v[186:189], v[126:129]
	v_mfma_f32_16x16x32_bf16 v[122:125], v[178:181], v[186:189], v[122:125]
	v_mfma_f32_16x16x32_bf16 v[102:105], v[170:173], v[194:197], v[102:105]
	v_mfma_f32_16x16x32_bf16 v[98:101], v[178:181], v[194:197], v[98:101]
	v_mfma_f32_16x16x32_bf16 v[86:89], v[170:173], v[202:205], v[86:89]
	v_mfma_f32_16x16x32_bf16 v[82:85], v[178:181], v[202:205], v[82:85]
	v_mfma_f32_16x16x32_bf16 v[70:73], v[170:173], v[210:213], v[70:73]
	v_mfma_f32_16x16x32_bf16 v[66:69], v[178:181], v[210:213], v[66:69]
	v_mfma_f32_16x16x32_bf16 v[126:129], v[174:177], v[190:193], v[126:129]
	v_mfma_f32_16x16x32_bf16 v[122:125], v[182:185], v[190:193], v[122:125]
	v_mfma_f32_16x16x32_bf16 v[102:105], v[174:177], v[198:201], v[102:105]
	v_mfma_f32_16x16x32_bf16 v[98:101], v[182:185], v[198:201], v[98:101]
	v_mfma_f32_16x16x32_bf16 v[86:89], v[174:177], v[206:209], v[86:89]
	v_mfma_f32_16x16x32_bf16 v[82:85], v[182:185], v[206:209], v[82:85]
	v_mfma_f32_16x16x32_bf16 v[70:73], v[174:177], v[214:217], v[70:73]
	v_mfma_f32_16x16x32_bf16 v[66:69], v[182:185], v[214:217], v[66:69]
	s_setprio 0
	s_barrier
; #define PG8_STAGE(bufoff, gbase, voff) do { _Pragma("unroll") for (int _i = 0; _i < 2; ++_i) \
;         __builtin_amdgcn_global_load_lds((const unsigned*)((const char*)(gbase) + (voff)[_i]), (PG8_LAS unsigned*)(lds + (bufoff) + ldsw + _i * 8192), 16, 0, 0); } while (0)
; #define PG8_LDA(dst, b, h) do { _Pragma("unroll") for (int m = 0; m < 4; ++m) _Pragma("unroll") for (int k = 0; k < 2; ++k) dst[m][k] = *(const PG8_LAS bf16x8*)(lds + PG8_SA(b, h) + aoff + m * 2048 + k * 1024); } while (0)
; #define PG8_MMA(ai, bj, At, Bt) do { __builtin_amdgcn_s_setprio(1); _Pragma("unroll") for (int m = 0; m < 4; ++m) _Pragma("unroll") for (int n = 0; n < 2; ++n) _Pragma("unroll") for (int k = 0; k < 2; ++k) \
;         acc[ai][bj][m][n] = __builtin_amdgcn_mfma_f32_16x16x32_bf16(Bt[n][k], At[m][k], acc[ai][bj][m][n], 0, 0, 0); __builtin_amdgcn_s_setprio(0); } while (0)
; #define PG8_WAIT_V(n) asm volatile("s_waitcnt vmcnt(" #n ")" ::: "memory")
; #define PG8_WAIT_L(n) asm volatile("s_waitcnt lgkmcnt(" #n ")" ::: "memory")
; #define PG8_BAR __builtin_amdgcn_s_barrier()
; #define PG8_SCHED __builtin_amdgcn_sched_barrier(0)
; template <class Epi, class Sched, bool ALIGN_EPI = false, bool SP2 = false, bool HALFM = false>
; __device__ __forceinline__ void gemm_phase(PG8_LAS unsigned char* lds, const Gemm g, const Sched& S, const Epi& E) {
;     ...
;         for (int t = 0; t < nt; t += 2) {
;             const bool last = (t == nt - 2);
;     ...
;             PG8_LDA(At, 1, 1); PG8_STAGE(PG8_SB(1, 0), b3, voffB); PG8_STAGE(PG8_SB(1, 1), b3 + hstep, voffB); PG8_STAGE(PG8_SA(1, 0), a3, voffA);
;             PG8_WAIT_V(8); PG8_WAIT_L(0); PG8_BAR; if constexpr (!HALFM) { PG8_MMA(1, 0, At, B0); PG8_MMA(1, 1, At, B1); } PG8_BAR; PG8_SCHED;
	s_add_i32 s40, s58, s0
	v_lshl_add_u64 v[146:147], v[146:147], 0, s[14:15]
	s_mov_b32 m0, s40
	ds_read_b128 v[186:189], v152 offset:49152
	ds_read_b128 v[190:193], v152 offset:50176
	ds_read_b128 v[194:197], v152 offset:51200
	ds_read_b128 v[198:201], v152 offset:52224
	ds_read_b128 v[202:205], v152 offset:53248
	ds_read_b128 v[206:209], v152 offset:54272
	ds_read_b128 v[210:213], v152 offset:55296
	ds_read_b128 v[214:217], v152 offset:56320
	global_load_lds_dwordx4 v[146:147], off
	s_add_i32 m0, s40, 0x2000
	s_add_u32 s38, s38, 0x40080
	v_lshl_add_u64 v[146:147], v[218:219], 0, s[14:15]
	s_addc_u32 s39, s39, 0
	s_add_i32 s40, s59, s0
	global_load_lds_dwordx4 v[146:147], off
	v_lshl_add_u64 v[146:147], s[38:39], 0, v[134:135]
	s_mov_b32 m0, s40
	s_nop 0
	global_load_lds_dwordx4 v[146:147], off
	v_lshl_add_u64 v[146:147], s[38:39], 0, v[130:131]
	s_add_i32 m0, s40, 0x2000
	s_nop 0
	global_load_lds_dwordx4 v[146:147], off
	s_waitcnt vmcnt(4)
	s_waitcnt lgkmcnt(0)
	s_barrier
	s_setprio 1
	s_waitcnt lgkmcnt(0)
	v_mfma_f32_16x16x32_bf16 v[62:65], v[154:157], v[186:189], v[62:65]
	v_mfma_f32_16x16x32_bf16 v[58:61], v[162:165], v[186:189], v[58:61]
	v_mfma_f32_16x16x32_bf16 v[46:49], v[154:157], v[194:197], v[46:49]
	v_mfma_f32_16x16x32_bf16 v[42:45], v[162:165], v[194:197], v[42:45]
	v_mfma_f32_16x16x32_bf16 v[30:33], v[154:157], v[202:205], v[30:33]
	v_mfma_f32_16x16x32_bf16 v[26:29], v[162:165], v[202:205], v[26:29]
	v_mfma_f32_16x16x32_bf16 v[14:17], v[154:157], v[210:213], v[14:17]
	v_mfma_f32_16x16x32_bf16 v[10:13], v[162:165], v[210:213], v[10:13]
	v_mfma_f32_16x16x32_bf16 v[62:65], v[158:161], v[190:193], v[62:65]
	v_mfma_f32_16x16x32_bf16 v[58:61], v[166:169], v[190:193], v[58:61]
	v_mfma_f32_16x16x32_bf16 v[46:49], v[158:161], v[198:201], v[46:49]
	v_mfma_f32_16x16x32_bf16 v[42:45], v[166:169], v[198:201], v[42:45]
	v_mfma_f32_16x16x32_bf16 v[30:33], v[158:161], v[206:209], v[30:33]
	v_mfma_f32_16x16x32_bf16 v[26:29], v[166:169], v[206:209], v[26:29]
	v_mfma_f32_16x16x32_bf16 v[14:17], v[158:161], v[214:217], v[14:17]
	v_mfma_f32_16x16x32_bf16 v[10:13], v[166:169], v[214:217], v[10:13]
	s_setprio 0
	s_setprio 1
	v_mfma_f32_16x16x32_bf16 v[54:57], v[170:173], v[186:189], v[54:57]
	v_mfma_f32_16x16x32_bf16 v[50:53], v[178:181], v[186:189], v[50:53]
	v_mfma_f32_16x16x32_bf16 v[38:41], v[170:173], v[194:197], v[38:41]
	v_mfma_f32_16x16x32_bf16 v[34:37], v[178:181], v[194:197], v[34:37]
	v_mfma_f32_16x16x32_bf16 v[22:25], v[170:173], v[202:205], v[22:25]
	v_mfma_f32_16x16x32_bf16 v[18:21], v[178:181], v[202:205], v[18:21]
	v_mfma_f32_16x16x32_bf16 v[6:9], v[170:173], v[210:213], v[6:9]
	v_mfma_f32_16x16x32_bf16 v[2:5], v[178:181], v[210:213], v[2:5]
	v_mfma_f32_16x16x32_bf16 v[54:57], v[174:177], v[190:193], v[54:57]
	v_mfma_f32_16x16x32_bf16 v[50:53], v[182:185], v[190:193], v[50:53]
	v_mfma_f32_16x16x32_bf16 v[38:41], v[174:177], v[198:201], v[38:41]
	v_mfma_f32_16x16x32_bf16 v[34:37], v[182:185], v[198:201], v[34:37]
	v_mfma_f32_16x16x32_bf16 v[22:25], v[174:177], v[206:209], v[22:25]
	v_mfma_f32_16x16x32_bf16 v[18:21], v[182:185], v[206:209], v[18:21]
	v_mfma_f32_16x16x32_bf16 v[6:9], v[174:177], v[214:217], v[6:9]
	v_mfma_f32_16x16x32_bf16 v[2:5], v[182:185], v[214:217], v[2:5]
	s_setprio 0
	s_barrier
	s_add_i32 s57, s57, 2
	s_add_u32 s36, s36, 0x100
	s_addc_u32 s37, s37, 0
	s_add_u32 s55, s55, 0x100
	s_addc_u32 s56, s56, 0
	s_cmp_gt_u32 s57, 13
	s_cbranch_scc0 .LBB0_1805
	s_and_b64 vcc, exec, s[22:23]
	s_cbranch_vccz .LBB0_1808
	s_barrier

; #define PG8_STAGE(bufoff, gbase, voff) do { _Pragma("unroll") for (int _i = 0; _i < 2; ++_i) \
;         __builtin_amdgcn_global_load_lds((const unsigned*)((const char*)(gbase) + (voff)[_i]), (PG8_LAS unsigned*)(lds + (bufoff) + ldsw + _i * 8192), 16, 0, 0); } while (0)
; #define PG8_LDA(dst, b, h) do { _Pragma("unroll") for (int m = 0; m < 4; ++m) _Pragma("unroll") for (int k = 0; k < 2; ++k) dst[m][k] = *(const PG8_LAS bf16x8*)(lds + PG8_SA(b, h) + aoff + m * 2048 + k * 1024); } while (0)
; #define PG8_LDB(dst, b, h) do { _Pragma("unroll") for (int n = 0; n < 2; ++n) _Pragma("unroll") for (int k = 0; k < 2; ++k) dst[n][k] = *(const PG8_LAS bf16x8*)(lds + PG8_SB(b, h) + boff + n * 2048 + k * 1024); } while (0)
; #define PG8_MMA(ai, bj, At, Bt) do { __builtin_amdgcn_s_setprio(1); _Pragma("unroll") for (int m = 0; m < 4; ++m) _Pragma("unroll") for (int n = 0; n < 2; ++n) _Pragma("unroll") for (int k = 0; k < 2; ++k) \
;         acc[ai][bj][m][n] = __builtin_amdgcn_mfma_f32_16x16x32_bf16(Bt[n][k], At[m][k], acc[ai][bj][m][n], 0, 0, 0); __builtin_amdgcn_s_setprio(0); } while (0)
; #define PG8_WAIT_V(n) asm volatile("s_waitcnt vmcnt(" #n ")" ::: "memory")
; #define PG8_BAR __builtin_amdgcn_s_barrier()
; template <class Epi, class Sched, bool ALIGN_EPI = false, bool SP2 = false, bool HALFM = false>
; __device__ __forceinline__ void gemm_phase(PG8_LAS unsigned char* lds, const Gemm g, const Sched& S, const Epi& E) {
;     ...
;             const char* a1 = cA + (size_t)(t + 1) * kstep;
;             const char* a2 = last ? nA : cA + (size_t)(t + 2) * kstep; const char* b2 = last ? nB : cB + (size_t)(t + 2) * kstep;
;             const char* a3 = a2 + kstep; const char* b3 = b2 + kstep;
;             if (last && has_next) S.a_ready(nxt);
;             if constexpr (SP2) {
;             PG8_LDB(B0, 0, 0); PG8_LDB(B1, 0, 1); PG8_SCHED; PG8_LDA(At, 0, 0); PG8_STAGE(PG8_SA(1, 1), a1 + hstep, voffA);
;             PG8_WAIT_V(8); PG8_WAIT_L(0); PG8_BAR; PG8_MMA(0, 0, At, B0); PG8_MMA(0, 1, At, B1); PG8_BAR; PG8_SCHED;
;     ...
; #pragma unroll
;         for (int a = 0; a < 2; ++a)
; #pragma unroll
;             for (int b = 0; b < 2; ++b)
; #pragma unroll
;                 for (int m = 0; m < 4; ++m)
; #pragma unroll
;                     for (int n = 0; n < 2; ++n) acc[a][b][m][n] = (f32x4){0.f, 0.f, 0.f, 0.f};
;         cur = nxt; cA = nA; cB = nB; ++ui;
.LBB0_1927:
	s_add_u32 s53, s34, 0x100
	v_mov_b32_e32 v2, 0
	s_addc_u32 s54, s35, 0
	s_mov_b32 s55, -2
	v_mov_b32_e32 v3, v2
	v_mov_b32_e32 v4, v2
	v_mov_b32_e32 v5, v2
	v_mov_b32_e32 v6, v2
	v_mov_b32_e32 v7, v2
	v_mov_b32_e32 v8, v2
	v_mov_b32_e32 v9, v2
	v_mov_b32_e32 v18, v2
	v_mov_b32_e32 v19, v2
	v_mov_b32_e32 v20, v2
	v_mov_b32_e32 v21, v2
	v_mov_b32_e32 v22, v2
	v_mov_b32_e32 v23, v2
	v_mov_b32_e32 v24, v2
	v_mov_b32_e32 v25, v2
	v_mov_b32_e32 v34, v2
	v_mov_b32_e32 v35, v2
	v_mov_b32_e32 v36, v2
	v_mov_b32_e32 v37, v2
	v_mov_b32_e32 v38, v2
	v_mov_b32_e32 v39, v2
	v_mov_b32_e32 v40, v2
	v_mov_b32_e32 v41, v2
	v_mov_b32_e32 v50, v2
	v_mov_b32_e32 v51, v2
	v_mov_b32_e32 v52, v2
	v_mov_b32_e32 v53, v2
	v_mov_b32_e32 v54, v2
	v_mov_b32_e32 v55, v2
	v_mov_b32_e32 v56, v2
	v_mov_b32_e32 v57, v2
	v_mov_b32_e32 v10, v2
	v_mov_b32_e32 v11, v2
	v_mov_b32_e32 v12, v2
	v_mov_b32_e32 v13, v2
	v_mov_b32_e32 v14, v2
	v_mov_b32_e32 v15, v2
	v_mov_b32_e32 v16, v2
	v_mov_b32_e32 v17, v2
	v_mov_b32_e32 v26, v2
	v_mov_b32_e32 v27, v2
	v_mov_b32_e32 v28, v2
	v_mov_b32_e32 v29, v2
	v_mov_b32_e32 v30, v2
	v_mov_b32_e32 v31, v2
	v_mov_b32_e32 v32, v2
	v_mov_b32_e32 v33, v2
	v_mov_b32_e32 v42, v2
	v_mov_b32_e32 v43, v2
	v_mov_b32_e32 v44, v2
	v_mov_b32_e32 v45, v2
	v_mov_b32_e32 v46, v2
	v_mov_b32_e32 v47, v2
	v_mov_b32_e32 v48, v2
	v_mov_b32_e32 v49, v2
	v_mov_b32_e32 v58, v2
	v_mov_b32_e32 v59, v2
	v_mov_b32_e32 v60, v2
	v_mov_b32_e32 v61, v2
	v_mov_b32_e32 v62, v2
	v_mov_b32_e32 v63, v2
	v_mov_b32_e32 v64, v2
	v_mov_b32_e32 v65, v2
	v_mov_b32_e32 v66, v2
	v_mov_b32_e32 v67, v2
	v_mov_b32_e32 v68, v2
	v_mov_b32_e32 v69, v2
	v_mov_b32_e32 v70, v2
	v_mov_b32_e32 v71, v2
	v_mov_b32_e32 v72, v2
	v_mov_b32_e32 v73, v2
	v_mov_b32_e32 v82, v2
	v_mov_b32_e32 v83, v2
	v_mov_b32_e32 v84, v2
	v_mov_b32_e32 v85, v2
	v_mov_b32_e32 v86, v2
	v_mov_b32_e32 v87, v2
	v_mov_b32_e32 v88, v2
	v_mov_b32_e32 v89, v2
	v_mov_b32_e32 v98, v2
	v_mov_b32_e32 v99, v2
	v_mov_b32_e32 v100, v2
	v_mov_b32_e32 v101, v2
	v_mov_b32_e32 v102, v2
	v_mov_b32_e32 v103, v2
	v_mov_b32_e32 v104, v2
	v_mov_b32_e32 v105, v2
	v_mov_b32_e32 v122, v2
	v_mov_b32_e32 v123, v2
	v_mov_b32_e32 v124, v2
	v_mov_b32_e32 v125, v2
	v_mov_b32_e32 v126, v2
	v_mov_b32_e32 v127, v2
	v_mov_b32_e32 v128, v2
	v_mov_b32_e32 v129, v2
	v_mov_b32_e32 v74, v2
	v_mov_b32_e32 v75, v2
	v_mov_b32_e32 v76, v2
	v_mov_b32_e32 v77, v2
	v_mov_b32_e32 v78, v2
	v_mov_b32_e32 v79, v2
	v_mov_b32_e32 v80, v2
	v_mov_b32_e32 v81, v2
	v_mov_b32_e32 v90, v2
	v_mov_b32_e32 v91, v2
	v_mov_b32_e32 v92, v2
	v_mov_b32_e32 v93, v2
	v_mov_b32_e32 v94, v2
	v_mov_b32_e32 v95, v2
	v_mov_b32_e32 v96, v2
	v_mov_b32_e32 v97, v2
	v_mov_b32_e32 v106, v2
	v_mov_b32_e32 v107, v2
	v_mov_b32_e32 v108, v2
	v_mov_b32_e32 v109, v2
	v_mov_b32_e32 v110, v2
	v_mov_b32_e32 v111, v2
	v_mov_b32_e32 v112, v2
	v_mov_b32_e32 v113, v2
	v_mov_b32_e32 v150, v2
	v_mov_b32_e32 v151, v2
	v_mov_b32_e32 v152, v2
	v_mov_b32_e32 v153, v2
	v_mov_b32_e32 v154, v2
	v_mov_b32_e32 v155, v2
	v_mov_b32_e32 v156, v2
	v_mov_b32_e32 v157, v2
	s_mov_b32 s100, 0xfff4ff80
	s_mov_b32 s101, -1
	v_lshl_add_u64 v[210:211], s[30:31], 0, v[202:203]
	v_lshl_add_u64 v[210:211], v[210:211], 0, s[100:101]
	v_lshl_add_u64 v[212:213], s[30:31], 0, v[204:205]
	v_lshl_add_u64 v[212:213], v[212:213], 0, s[100:101]
.LBB0_1928:
	ds_read_b128 v[114:117], v246
	ds_read_b128 v[118:121], v246 offset:1024
	ds_read_b128 v[130:133], v246 offset:2048
	ds_read_b128 v[134:137], v246 offset:3072
	ds_read_b128 v[138:141], v247
	ds_read_b128 v[142:145], v247 offset:1024
	ds_read_b128 v[146:149], v247 offset:2048
	ds_read_b128 v[158:161], v247 offset:3072
	s_add_u32 s34, s30, 0x100
	s_addc_u32 s35, s31, 0
	s_cmp_eq_u32 s55, 40
	s_cselect_b32 s39, s15, s35
	s_cselect_b32 s38, s14, s34
	s_cselect_b32 s37, s29, s54
	s_cselect_b32 s36, s28, s53
	v_lshl_add_u64 v[206:207], s[30:31], 0, v[202:203]
	s_add_i32 m0, s1, 0xc000
	ds_read_b128 v[162:165], v248
	ds_read_b128 v[166:169], v248 offset:1024
	ds_read_b128 v[170:173], v248 offset:2048
	ds_read_b128 v[174:177], v248 offset:3072
	ds_read_b128 v[178:181], v248 offset:4096
	ds_read_b128 v[182:185], v248 offset:5120
	ds_read_b128 v[186:189], v248 offset:6144
	ds_read_b128 v[190:193], v248 offset:7168
	global_load_lds_dwordx4 v[206:207], off
	v_lshl_add_u64 v[206:207], s[30:31], 0, v[204:205]
	s_add_i32 m0, s1, 0xe000
	s_nop 0
	global_load_lds_dwordx4 v[206:207], off
	s_mov_b32 m0, s44
	v_lshl_add_u64 v[206:207], v[210:211], 0, s[24:25]
	global_load_lds_dwordx4 v[206:207], off
	s_mov_b32 m0, s45
	v_lshl_add_u64 v[206:207], v[212:213], 0, s[24:25]
	global_load_lds_dwordx4 v[206:207], off
	s_waitcnt vmcnt(10)
	s_waitcnt lgkmcnt(0)
	s_barrier
; #define PG8_STAGE(bufoff, gbase, voff) do { _Pragma("unroll") for (int _i = 0; _i < 2; ++_i) \
;         __builtin_amdgcn_global_load_lds((const unsigned*)((const char*)(gbase) + (voff)[_i]), (PG8_LAS unsigned*)(lds + (bufoff) + ldsw + _i * 8192), 16, 0, 0); } while (0)
; #define PG8_LDA(dst, b, h) do { _Pragma("unroll") for (int m = 0; m < 4; ++m) _Pragma("unroll") for (int k = 0; k < 2; ++k) dst[m][k] = *(const PG8_LAS bf16x8*)(lds + PG8_SA(b, h) + aoff + m * 2048 + k * 1024); } while (0)
; #define PG8_LDB(dst, b, h) do { _Pragma("unroll") for (int n = 0; n < 2; ++n) _Pragma("unroll") for (int k = 0; k < 2; ++k) dst[n][k] = *(const PG8_LAS bf16x8*)(lds + PG8_SB(b, h) + boff + n * 2048 + k * 1024); } while (0)
; template <class Epi, class Sched, bool ALIGN_EPI = false, bool SP2 = false, bool HALFM = false>
; __device__ __forceinline__ void gemm_phase(PG8_LAS unsigned char* lds, const Gemm g, const Sched& S, const Epi& E) {
;     ...
;             const char* a1 = cA + (size_t)(t + 1) * kstep;
;             const char* a2 = last ? nA : cA + (size_t)(t + 2) * kstep; const char* b2 = last ? nB : cB + (size_t)(t + 2) * kstep;
;             const char* a3 = a2 + kstep; const char* b3 = b2 + kstep;
;             if (last && has_next) S.a_ready(nxt);
;             if constexpr (SP2) {
;             PG8_LDB(B0, 0, 0); PG8_LDB(B1, 0, 1); PG8_SCHED; PG8_LDA(At, 0, 0); PG8_STAGE(PG8_SA(1, 1), a1 + hstep, voffA);
;             PG8_WAIT_V(8); PG8_WAIT_L(0); PG8_BAR; PG8_MMA(0, 0, At, B0); PG8_MMA(0, 1, At, B1); PG8_BAR; PG8_SCHED;
;             PG8_LDA(At, 0, 1); PG8_STAGE(PG8_SB(0, 0), b2, voffB); PG8_STAGE(PG8_SB(0, 1), b2 + hstep, voffB); PG8_STAGE(PG8_SA(0, 0), a2, voffA);
;             PG8_WAIT_V(8); PG8_WAIT_L(0); PG8_BAR; if constexpr (!HALFM) { PG8_MMA(1, 0, At, B0); PG8_MMA(1, 1, At, B1); } PG8_BAR; PG8_SCHED;
;             PG8_LDB(B0, 1, 0); PG8_LDB(B1, 1, 1); PG8_SCHED; PG8_LDA(At, 1, 0); PG8_STAGE(PG8_SA(0, 1), a2 + hstep, voffA);
;             PG8_WAIT_V(8); PG8_WAIT_L(0); PG8_BAR; PG8_MMA(0, 0, At, B0); PG8_MMA(0, 1, At, B1); PG8_BAR; PG8_SCHED;
;             PG8_LDA(At, 1, 1); PG8_STAGE(PG8_SB(1, 0), b3, voffB); PG8_STAGE(PG8_SB(1, 1), b3 + hstep, voffB); PG8_STAGE(PG8_SA(1, 0), a3, voffA);
;             PG8_WAIT_V(8); PG8_WAIT_L(0); PG8_BAR; if constexpr (!HALFM) { PG8_MMA(1, 0, At, B0); PG8_MMA(1, 1, At, B1); } PG8_BAR; PG8_SCHED;
	s_setprio 1
	s_waitcnt lgkmcnt(0)
	v_mfma_f32_16x16x32_bf16 v[154:157], v[114:117], v[162:165], v[154:157]
	v_mfma_f32_16x16x32_bf16 v[150:153], v[130:133], v[162:165], v[150:153]
	v_mfma_f32_16x16x32_bf16 v[110:113], v[114:117], v[170:173], v[110:113]
	v_mfma_f32_16x16x32_bf16 v[106:109], v[130:133], v[170:173], v[106:109]
	v_mfma_f32_16x16x32_bf16 v[94:97], v[114:117], v[178:181], v[94:97]
	v_mfma_f32_16x16x32_bf16 v[90:93], v[130:133], v[178:181], v[90:93]
	v_mfma_f32_16x16x32_bf16 v[78:81], v[114:117], v[186:189], v[78:81]
	v_mfma_f32_16x16x32_bf16 v[74:77], v[130:133], v[186:189], v[74:77]
	v_mfma_f32_16x16x32_bf16 v[154:157], v[118:121], v[166:169], v[154:157]
	v_mfma_f32_16x16x32_bf16 v[150:153], v[134:137], v[166:169], v[150:153]
	v_mfma_f32_16x16x32_bf16 v[110:113], v[118:121], v[174:177], v[110:113]
	v_mfma_f32_16x16x32_bf16 v[106:109], v[134:137], v[174:177], v[106:109]
	v_mfma_f32_16x16x32_bf16 v[94:97], v[118:121], v[182:185], v[94:97]
	v_mfma_f32_16x16x32_bf16 v[90:93], v[134:137], v[182:185], v[90:93]
	v_mfma_f32_16x16x32_bf16 v[78:81], v[118:121], v[190:193], v[78:81]
	v_mfma_f32_16x16x32_bf16 v[74:77], v[134:137], v[190:193], v[74:77]
	s_setprio 0
	s_setprio 1
	v_mfma_f32_16x16x32_bf16 v[126:129], v[138:141], v[162:165], v[126:129]
	v_mfma_f32_16x16x32_bf16 v[122:125], v[146:149], v[162:165], v[122:125]
	v_mfma_f32_16x16x32_bf16 v[102:105], v[138:141], v[170:173], v[102:105]
	v_mfma_f32_16x16x32_bf16 v[98:101], v[146:149], v[170:173], v[98:101]
	v_mfma_f32_16x16x32_bf16 v[86:89], v[138:141], v[178:181], v[86:89]
	v_mfma_f32_16x16x32_bf16 v[82:85], v[146:149], v[178:181], v[82:85]
	v_mfma_f32_16x16x32_bf16 v[70:73], v[138:141], v[186:189], v[70:73]
	v_mfma_f32_16x16x32_bf16 v[66:69], v[146:149], v[186:189], v[66:69]
	v_mfma_f32_16x16x32_bf16 v[126:129], v[142:145], v[166:169], v[126:129]
	v_mfma_f32_16x16x32_bf16 v[122:125], v[158:161], v[166:169], v[122:125]
	v_mfma_f32_16x16x32_bf16 v[102:105], v[142:145], v[174:177], v[102:105]
	v_mfma_f32_16x16x32_bf16 v[98:101], v[158:161], v[174:177], v[98:101]
	v_mfma_f32_16x16x32_bf16 v[86:89], v[142:145], v[182:185], v[86:89]
	v_mfma_f32_16x16x32_bf16 v[82:85], v[158:161], v[182:185], v[82:85]
	v_mfma_f32_16x16x32_bf16 v[70:73], v[142:145], v[190:193], v[70:73]
	v_mfma_f32_16x16x32_bf16 v[66:69], v[158:161], v[190:193], v[66:69]
	s_setprio 0
	s_barrier
	s_add_i32 s30, s47, s0
	v_lshl_add_u64 v[206:207], s[36:37], 0, v[196:197]
	s_mov_b32 m0, s30
	ds_read_b128 v[162:165], v248 offset:16384
	ds_read_b128 v[166:169], v248 offset:17408
	ds_read_b128 v[170:173], v248 offset:18432
	ds_read_b128 v[174:177], v248 offset:19456
	ds_read_b128 v[178:181], v248 offset:20480
	ds_read_b128 v[182:185], v248 offset:21504
	ds_read_b128 v[186:189], v248 offset:22528
	ds_read_b128 v[190:193], v248 offset:23552
	global_load_lds_dwordx4 v[206:207], off
	s_add_i32 m0, s30, 0x2000
	s_add_u32 s30, s36, 0xb0000
	v_lshl_add_u64 v[208:209], s[36:37], 0, v[200:201]
	s_addc_u32 s31, s37, 0
	s_add_i32 s56, s48, s0
	global_load_lds_dwordx4 v[208:209], off
	v_lshl_add_u64 v[210:211], s[30:31], 0, v[196:197]
	s_mov_b32 m0, s56
	v_lshl_add_u64 v[212:213], s[38:39], 0, v[198:199]
	global_load_lds_dwordx4 v[210:211], off
	v_lshl_add_u64 v[210:211], s[30:31], 0, v[200:201]
	s_add_i32 m0, s56, 0x2000
	s_nop 0
	global_load_lds_dwordx4 v[210:211], off
	v_lshl_add_u64 v[210:211], s[38:39], 0, v[194:195]
	s_waitcnt vmcnt(4)
	s_waitcnt lgkmcnt(0)
	s_barrier
	s_setprio 1
	s_waitcnt lgkmcnt(0)
	v_mfma_f32_16x16x32_bf16 v[62:65], v[114:117], v[162:165], v[62:65]
	v_mfma_f32_16x16x32_bf16 v[58:61], v[130:133], v[162:165], v[58:61]
	v_mfma_f32_16x16x32_bf16 v[46:49], v[114:117], v[170:173], v[46:49]
	v_mfma_f32_16x16x32_bf16 v[42:45], v[130:133], v[170:173], v[42:45]
	v_mfma_f32_16x16x32_bf16 v[30:33], v[114:117], v[178:181], v[30:33]
	v_mfma_f32_16x16x32_bf16 v[26:29], v[130:133], v[178:181], v[26:29]
	v_mfma_f32_16x16x32_bf16 v[14:17], v[114:117], v[186:189], v[14:17]
	v_mfma_f32_16x16x32_bf16 v[10:13], v[130:133], v[186:189], v[10:13]
	v_mfma_f32_16x16x32_bf16 v[62:65], v[118:121], v[166:169], v[62:65]
	v_mfma_f32_16x16x32_bf16 v[58:61], v[134:137], v[166:169], v[58:61]
	v_mfma_f32_16x16x32_bf16 v[46:49], v[118:121], v[174:177], v[46:49]
	v_mfma_f32_16x16x32_bf16 v[42:45], v[134:137], v[174:177], v[42:45]
	v_mfma_f32_16x16x32_bf16 v[30:33], v[118:121], v[182:185], v[30:33]
	v_mfma_f32_16x16x32_bf16 v[26:29], v[134:137], v[182:185], v[26:29]
	v_mfma_f32_16x16x32_bf16 v[14:17], v[118:121], v[190:193], v[14:17]
	v_mfma_f32_16x16x32_bf16 v[10:13], v[134:137], v[190:193], v[10:13]
	s_setprio 0
	s_setprio 1
	v_mfma_f32_16x16x32_bf16 v[54:57], v[138:141], v[162:165], v[54:57]
	v_mfma_f32_16x16x32_bf16 v[50:53], v[146:149], v[162:165], v[50:53]
	v_mfma_f32_16x16x32_bf16 v[38:41], v[138:141], v[170:173], v[38:41]
	v_mfma_f32_16x16x32_bf16 v[34:37], v[146:149], v[170:173], v[34:37]
	v_mfma_f32_16x16x32_bf16 v[22:25], v[138:141], v[178:181], v[22:25]
	v_mfma_f32_16x16x32_bf16 v[18:21], v[146:149], v[178:181], v[18:21]
	v_mfma_f32_16x16x32_bf16 v[6:9], v[138:141], v[186:189], v[6:9]
	v_mfma_f32_16x16x32_bf16 v[2:5], v[146:149], v[186:189], v[2:5]
	v_mfma_f32_16x16x32_bf16 v[54:57], v[142:145], v[166:169], v[54:57]
	v_mfma_f32_16x16x32_bf16 v[50:53], v[158:161], v[166:169], v[50:53]
	v_mfma_f32_16x16x32_bf16 v[38:41], v[142:145], v[174:177], v[38:41]
	v_mfma_f32_16x16x32_bf16 v[34:37], v[158:161], v[174:177], v[34:37]
	v_mfma_f32_16x16x32_bf16 v[22:25], v[142:145], v[182:185], v[22:25]
	v_mfma_f32_16x16x32_bf16 v[18:21], v[158:161], v[182:185], v[18:21]
	v_mfma_f32_16x16x32_bf16 v[6:9], v[142:145], v[190:193], v[6:9]
	v_mfma_f32_16x16x32_bf16 v[2:5], v[158:161], v[190:193], v[2:5]
	s_setprio 0
	s_barrier
; #define PG8_STAGE(bufoff, gbase, voff) do { _Pragma("unroll") for (int _i = 0; _i < 2; ++_i) \
;         __builtin_amdgcn_global_load_lds((const unsigned*)((const char*)(gbase) + (voff)[_i]), (PG8_LAS unsigned*)(lds + (bufoff) + ldsw + _i * 8192), 16, 0, 0); } while (0)
; #define PG8_LDA(dst, b, h) do { _Pragma("unroll") for (int m = 0; m < 4; ++m) _Pragma("unroll") for (int k = 0; k < 2; ++k) dst[m][k] = *(const PG8_LAS bf16x8*)(lds + PG8_SA(b, h) + aoff + m * 2048 + k * 1024); } while (0)
; #define PG8_LDB(dst, b, h) do { _Pragma("unroll") for (int n = 0; n < 2; ++n) _Pragma("unroll") for (int k = 0; k < 2; ++k) dst[n][k] = *(const PG8_LAS bf16x8*)(lds + PG8_SB(b, h) + boff + n * 2048 + k * 1024); } while (0)
; #define PG8_MMA(ai, bj, At, Bt) do { __builtin_amdgcn_s_setprio(1); _Pragma("unroll") for (int m = 0; m < 4; ++m) _Pragma("unroll") for (int n = 0; n < 2; ++n) _Pragma("unroll") for (int k = 0; k < 2; ++k) \
;         acc[ai][bj][m][n] = __builtin_amdgcn_mfma_f32_16x16x32_bf16(Bt[n][k], At[m][k], acc[ai][bj][m][n], 0, 0, 0); __builtin_amdgcn_s_setprio(0); } while (0)
; #define PG8_WAIT_V(n) asm volatile("s_waitcnt vmcnt(" #n ")" ::: "memory")
; #define PG8_WAIT_L(n) asm volatile("s_waitcnt lgkmcnt(" #n ")" ::: "memory")
; #define PG8_BAR __builtin_amdgcn_s_barrier()
; #define PG8_SCHED __builtin_amdgcn_sched_barrier(0)
; template <class Epi, class Sched, bool ALIGN_EPI = false, bool SP2 = false, bool HALFM = false>
; __device__ __forceinline__ void gemm_phase(PG8_LAS unsigned char* lds, const Gemm g, const Sched& S, const Epi& E) {
;     ...
;             PG8_LDB(B0, 1, 0); PG8_LDB(B1, 1, 1); PG8_SCHED; PG8_LDA(At, 1, 0); PG8_STAGE(PG8_SA(0, 1), a2 + hstep, voffA);
;             PG8_WAIT_V(8); PG8_WAIT_L(0); PG8_BAR; PG8_MMA(0, 0, At, B0); PG8_MMA(0, 1, At, B1); PG8_BAR; PG8_SCHED;
	s_add_i32 s56, 0, 0x18000
	s_add_i32 s57, 0, 0x1c000
	v_add_u32_e32 v134, s56, v244
	v_add_u32_e32 v158, s57, v244
	ds_read_b128 v[114:117], v134
	ds_read_b128 v[118:121], v134 offset:1024
	ds_read_b128 v[130:133], v134 offset:2048
	ds_read_b128 v[134:137], v134 offset:3072
	ds_read_b128 v[138:141], v158
	ds_read_b128 v[142:145], v158 offset:1024
	ds_read_b128 v[146:149], v158 offset:2048
	ds_read_b128 v[158:161], v158 offset:3072
	s_add_u32 s30, s38, 0xb0000
	s_addc_u32 s31, s39, 0
	s_mov_b32 m0, s3
	v_lshl_add_u64 v[214:215], s[30:31], 0, v[194:195]
	ds_read_b128 v[162:165], v248 offset:32768
	ds_read_b128 v[166:169], v248 offset:33792
	ds_read_b128 v[170:173], v248 offset:34816
	ds_read_b128 v[174:177], v248 offset:35840
	ds_read_b128 v[178:181], v248 offset:36864
	ds_read_b128 v[182:185], v248 offset:37888
	ds_read_b128 v[186:189], v248 offset:38912
	ds_read_b128 v[190:193], v248 offset:39936
	global_load_lds_dwordx4 v[214:215], off
	v_lshl_add_u64 v[214:215], s[30:31], 0, v[198:199]
	s_mov_b32 m0, s40
	s_nop 0
	global_load_lds_dwordx4 v[214:215], off
	s_mov_b32 m0, s1
	s_nop 0
	global_load_lds_dwordx4 v[210:211], off
	s_mov_b32 m0, s2
	s_nop 0
	global_load_lds_dwordx4 v[212:213], off
	s_waitcnt vmcnt(10)
	s_waitcnt lgkmcnt(0)
	s_barrier
	s_setprio 1
	s_waitcnt lgkmcnt(0)
	v_mfma_f32_16x16x32_bf16 v[154:157], v[114:117], v[162:165], v[154:157]
	v_mfma_f32_16x16x32_bf16 v[150:153], v[130:133], v[162:165], v[150:153]
	v_mfma_f32_16x16x32_bf16 v[110:113], v[114:117], v[170:173], v[110:113]
	v_mfma_f32_16x16x32_bf16 v[106:109], v[130:133], v[170:173], v[106:109]
	v_mfma_f32_16x16x32_bf16 v[94:97], v[114:117], v[178:181], v[94:97]
	v_mfma_f32_16x16x32_bf16 v[90:93], v[130:133], v[178:181], v[90:93]
	v_mfma_f32_16x16x32_bf16 v[78:81], v[114:117], v[186:189], v[78:81]
	v_mfma_f32_16x16x32_bf16 v[74:77], v[130:133], v[186:189], v[74:77]
	v_mfma_f32_16x16x32_bf16 v[154:157], v[118:121], v[166:169], v[154:157]
	v_mfma_f32_16x16x32_bf16 v[150:153], v[134:137], v[166:169], v[150:153]
	v_mfma_f32_16x16x32_bf16 v[110:113], v[118:121], v[174:177], v[110:113]
	v_mfma_f32_16x16x32_bf16 v[106:109], v[134:137], v[174:177], v[106:109]
	v_mfma_f32_16x16x32_bf16 v[94:97], v[118:121], v[182:185], v[94:97]
	v_mfma_f32_16x16x32_bf16 v[90:93], v[134:137], v[182:185], v[90:93]
	v_mfma_f32_16x16x32_bf16 v[78:81], v[118:121], v[190:193], v[78:81]
	v_mfma_f32_16x16x32_bf16 v[74:77], v[134:137], v[190:193], v[74:77]
	s_setprio 0
	s_setprio 1
	v_mfma_f32_16x16x32_bf16 v[126:129], v[138:141], v[162:165], v[126:129]
	v_mfma_f32_16x16x32_bf16 v[122:125], v[146:149], v[162:165], v[122:125]
	v_mfma_f32_16x16x32_bf16 v[102:105], v[138:141], v[170:173], v[102:105]
	v_mfma_f32_16x16x32_bf16 v[98:101], v[146:149], v[170:173], v[98:101]
	v_mfma_f32_16x16x32_bf16 v[86:89], v[138:141], v[178:181], v[86:89]
	v_mfma_f32_16x16x32_bf16 v[82:85], v[146:149], v[178:181], v[82:85]
	v_mfma_f32_16x16x32_bf16 v[70:73], v[138:141], v[186:189], v[70:73]
	v_mfma_f32_16x16x32_bf16 v[66:69], v[146:149], v[186:189], v[66:69]
	v_mfma_f32_16x16x32_bf16 v[126:129], v[142:145], v[166:169], v[126:129]
	v_mfma_f32_16x16x32_bf16 v[122:125], v[158:161], v[166:169], v[122:125]
	v_mfma_f32_16x16x32_bf16 v[102:105], v[142:145], v[174:177], v[102:105]
	v_mfma_f32_16x16x32_bf16 v[98:101], v[158:161], v[174:177], v[98:101]
	v_mfma_f32_16x16x32_bf16 v[86:89], v[142:145], v[182:185], v[86:89]
	v_mfma_f32_16x16x32_bf16 v[82:85], v[158:161], v[182:185], v[82:85]
	v_mfma_f32_16x16x32_bf16 v[70:73], v[142:145], v[190:193], v[70:73]
	v_mfma_f32_16x16x32_bf16 v[66:69], v[158:161], v[190:193], v[66:69]
	s_setprio 0
	s_barrier
; #define PG8_STAGE(bufoff, gbase, voff) do { _Pragma("unroll") for (int _i = 0; _i < 2; ++_i) \
;         __builtin_amdgcn_global_load_lds((const unsigned*)((const char*)(gbase) + (voff)[_i]), (PG8_LAS unsigned*)(lds + (bufoff) + ldsw + _i * 8192), 16, 0, 0); } while (0)
; #define PG8_LDA(dst, b, h) do { _Pragma("unroll") for (int m = 0; m < 4; ++m) _Pragma("unroll") for (int k = 0; k < 2; ++k) dst[m][k] = *(const PG8_LAS bf16x8*)(lds + PG8_SA(b, h) + aoff + m * 2048 + k * 1024); } while (0)
; #define PG8_MMA(ai, bj, At, Bt) do { __builtin_amdgcn_s_setprio(1); _Pragma("unroll") for (int m = 0; m < 4; ++m) _Pragma("unroll") for (int n = 0; n < 2; ++n) _Pragma("unroll") for (int k = 0; k < 2; ++k) \
;         acc[ai][bj][m][n] = __builtin_amdgcn_mfma_f32_16x16x32_bf16(Bt[n][k], At[m][k], acc[ai][bj][m][n], 0, 0, 0); __builtin_amdgcn_s_setprio(0); } while (0)
; #define PG8_WAIT_V(n) asm volatile("s_waitcnt vmcnt(" #n ")" ::: "memory")
; #define PG8_WAIT_L(n) asm volatile("s_waitcnt lgkmcnt(" #n ")" ::: "memory")
; #define PG8_BAR __builtin_amdgcn_s_barrier()
; #define PG8_SCHED __builtin_amdgcn_sched_barrier(0)
; template <class Epi, class Sched, bool ALIGN_EPI = false, bool SP2 = false, bool HALFM = false>
; __device__ __forceinline__ void gemm_phase(PG8_LAS unsigned char* lds, const Gemm g, const Sched& S, const Epi& E) {
;     ...
;         for (int t = 0; t < nt; t += 2) {
;             const bool last = (t == nt - 2);
;     ...
;             PG8_LDA(At, 1, 1); PG8_STAGE(PG8_SB(1, 0), b3, voffB); PG8_STAGE(PG8_SB(1, 1), b3 + hstep, voffB); PG8_STAGE(PG8_SA(1, 0), a3, voffA);
;             PG8_WAIT_V(8); PG8_WAIT_L(0); PG8_BAR; if constexpr (!HALFM) { PG8_MMA(1, 0, At, B0); PG8_MMA(1, 1, At, B1); } PG8_BAR; PG8_SCHED;
	s_add_i32 s30, s56, s0
	v_lshl_add_u64 v[206:207], v[206:207], 0, s[24:25]
	s_mov_b32 m0, s30
	ds_read_b128 v[162:165], v248 offset:49152
	ds_read_b128 v[166:169], v248 offset:50176
	ds_read_b128 v[170:173], v248 offset:51200
	ds_read_b128 v[174:177], v248 offset:52224
	ds_read_b128 v[178:181], v248 offset:53248
	ds_read_b128 v[182:185], v248 offset:54272
	ds_read_b128 v[186:189], v248 offset:55296
	ds_read_b128 v[190:193], v248 offset:56320
	global_load_lds_dwordx4 v[206:207], off
	s_add_i32 m0, s30, 0x2000
	s_add_u32 s30, s36, 0xb0080
	v_lshl_add_u64 v[206:207], v[208:209], 0, s[24:25]
	s_addc_u32 s31, s37, 0
	s_add_i32 s36, s57, s0
	global_load_lds_dwordx4 v[206:207], off
	v_lshl_add_u64 v[206:207], s[30:31], 0, v[196:197]
	s_mov_b32 m0, s36
	s_nop 0
	global_load_lds_dwordx4 v[206:207], off
	v_lshl_add_u64 v[206:207], s[30:31], 0, v[200:201]
	s_add_i32 m0, s36, 0x2000
	s_nop 0
	global_load_lds_dwordx4 v[206:207], off
	s_waitcnt vmcnt(4)
	s_waitcnt lgkmcnt(0)
	s_barrier
	s_setprio 1
	s_waitcnt lgkmcnt(0)
	v_mfma_f32_16x16x32_bf16 v[62:65], v[114:117], v[162:165], v[62:65]
	v_mfma_f32_16x16x32_bf16 v[58:61], v[130:133], v[162:165], v[58:61]
	v_mfma_f32_16x16x32_bf16 v[46:49], v[114:117], v[170:173], v[46:49]
	v_mfma_f32_16x16x32_bf16 v[42:45], v[130:133], v[170:173], v[42:45]
	v_mfma_f32_16x16x32_bf16 v[30:33], v[114:117], v[178:181], v[30:33]
	v_mfma_f32_16x16x32_bf16 v[26:29], v[130:133], v[178:181], v[26:29]
	v_mfma_f32_16x16x32_bf16 v[14:17], v[114:117], v[186:189], v[14:17]
	v_mfma_f32_16x16x32_bf16 v[10:13], v[130:133], v[186:189], v[10:13]
	v_mfma_f32_16x16x32_bf16 v[62:65], v[118:121], v[166:169], v[62:65]
	v_mfma_f32_16x16x32_bf16 v[58:61], v[134:137], v[166:169], v[58:61]
	v_mfma_f32_16x16x32_bf16 v[46:49], v[118:121], v[174:177], v[46:49]
	v_mfma_f32_16x16x32_bf16 v[42:45], v[134:137], v[174:177], v[42:45]
	v_mfma_f32_16x16x32_bf16 v[30:33], v[118:121], v[182:185], v[30:33]
	v_mfma_f32_16x16x32_bf16 v[26:29], v[134:137], v[182:185], v[26:29]
	v_mfma_f32_16x16x32_bf16 v[14:17], v[118:121], v[190:193], v[14:17]
	v_mfma_f32_16x16x32_bf16 v[10:13], v[134:137], v[190:193], v[10:13]
	s_setprio 0
	s_setprio 1
	v_mfma_f32_16x16x32_bf16 v[54:57], v[138:141], v[162:165], v[54:57]
	v_mfma_f32_16x16x32_bf16 v[50:53], v[146:149], v[162:165], v[50:53]
	v_mfma_f32_16x16x32_bf16 v[38:41], v[138:141], v[170:173], v[38:41]
	v_mfma_f32_16x16x32_bf16 v[34:37], v[146:149], v[170:173], v[34:37]
	v_mfma_f32_16x16x32_bf16 v[22:25], v[138:141], v[178:181], v[22:25]
	v_mfma_f32_16x16x32_bf16 v[18:21], v[146:149], v[178:181], v[18:21]
	v_mfma_f32_16x16x32_bf16 v[6:9], v[138:141], v[186:189], v[6:9]
	v_mfma_f32_16x16x32_bf16 v[2:5], v[146:149], v[186:189], v[2:5]
	v_mfma_f32_16x16x32_bf16 v[54:57], v[142:145], v[166:169], v[54:57]
	v_mfma_f32_16x16x32_bf16 v[50:53], v[158:161], v[166:169], v[50:53]
	v_mfma_f32_16x16x32_bf16 v[38:41], v[142:145], v[174:177], v[38:41]
	v_mfma_f32_16x16x32_bf16 v[34:37], v[158:161], v[174:177], v[34:37]
	v_mfma_f32_16x16x32_bf16 v[22:25], v[142:145], v[182:185], v[22:25]
	v_mfma_f32_16x16x32_bf16 v[18:21], v[158:161], v[182:185], v[18:21]
	v_mfma_f32_16x16x32_bf16 v[6:9], v[142:145], v[190:193], v[6:9]
	v_mfma_f32_16x16x32_bf16 v[2:5], v[158:161], v[190:193], v[2:5]
	s_setprio 0
	s_barrier
	s_add_i32 s55, s55, 2
	s_add_u32 s53, s53, 0x100
	s_addc_u32 s54, s54, 0
	s_cmp_gt_u32 s55, 41
	s_mov_b64 s[30:31], s[34:35]
	s_cbranch_scc0 .LBB0_1928
	s_and_b64 vcc, exec, s[26:27]
	s_cbranch_vccz .LBB0_1931
	s_barrier

; #define PG8_STAGE(bufoff, gbase, voff) do { _Pragma("unroll") for (int _i = 0; _i < 2; ++_i) \
;         __builtin_amdgcn_global_load_lds((const unsigned*)((const char*)(gbase) + (voff)[_i]), (PG8_LAS unsigned*)(lds + (bufoff) + ldsw + _i * 8192), 16, 0, 0); } while (0)
; #define PG8_LDA(dst, b, h) do { _Pragma("unroll") for (int m = 0; m < 4; ++m) _Pragma("unroll") for (int k = 0; k < 2; ++k) dst[m][k] = *(const PG8_LAS bf16x8*)(lds + PG8_SA(b, h) + aoff + m * 2048 + k * 1024); } while (0)
; #define PG8_LDB(dst, b, h) do { _Pragma("unroll") for (int n = 0; n < 2; ++n) _Pragma("unroll") for (int k = 0; k < 2; ++k) dst[n][k] = *(const PG8_LAS bf16x8*)(lds + PG8_SB(b, h) + boff + n * 2048 + k * 1024); } while (0)
; #define PG8_WAIT_V(n) asm volatile("s_waitcnt vmcnt(" #n ")" ::: "memory")
; #define PG8_WAIT_L(n) asm volatile("s_waitcnt lgkmcnt(" #n ")" ::: "memory")
; #define PG8_BAR __builtin_amdgcn_s_barrier()
; template <class Epi, class Sched, bool ALIGN_EPI = false, bool SP2 = false, bool HALFM = false>
; __device__ __forceinline__ void gemm_phase(PG8_LAS unsigned char* lds, const Gemm g, const Sched& S, const Epi& E) {
;     ...
;         const char* nA = has_next ? (const char*)g.A + (size_t)nxt.pm * tstep + (size_t)nxt.ko * 2 : cA; const char* nB = has_next ? (const char*)g.Bt + (size_t)nxt.pn * tstep + (size_t)nxt.ko * 2 : cB;
;         for (int t = 0; t < nt; t += 2) {
;             const bool last = (t == nt - 2);
;             const char* a1 = cA + (size_t)(t + 1) * kstep;
;             const char* a2 = last ? nA : cA + (size_t)(t + 2) * kstep; const char* b2 = last ? nB : cB + (size_t)(t + 2) * kstep;
;             const char* a3 = a2 + kstep; const char* b3 = b2 + kstep;
;             if (last && has_next) S.a_ready(nxt);
;             if constexpr (SP2) {
;             PG8_LDB(B0, 0, 0); PG8_LDB(B1, 0, 1); PG8_SCHED; PG8_LDA(At, 0, 0); PG8_STAGE(PG8_SA(1, 1), a1 + hstep, voffA);
;             PG8_WAIT_V(8); PG8_WAIT_L(0); PG8_BAR; PG8_MMA(0, 0, At, B0); PG8_MMA(0, 1, At, B1); PG8_BAR; PG8_SCHED;
;     ...
; #pragma unroll
;         for (int a = 0; a < 2; ++a)
; #pragma unroll
;             for (int b = 0; b < 2; ++b)
; #pragma unroll
;                 for (int m = 0; m < 4; ++m)
; #pragma unroll
;                     for (int n = 0; n < 2; ++n) acc[a][b][m][n] = (f32x4){0.f, 0.f, 0.f, 0.f};
;         cur = nxt; cA = nA; cB = nB; ++ui;
.LBB0_2048:
	s_ashr_i32 s27, s26, 31
	s_lshl_b64 s[28:29], s[26:27], 19
	s_add_u32 s28, s80, s28
	s_addc_u32 s29, s81, s29
	s_and_b64 s[30:31], s[4:5], exec
	s_cselect_b32 s27, s29, s37
	s_cselect_b32 s52, s28, s36
	s_ashr_i32 s25, s24, 31
	s_lshl_b64 s[30:31], s[24:25], 19
	s_add_u32 s30, s44, s30
	s_addc_u32 s31, s45, s31
	s_and_b64 s[40:41], s[4:5], exec
	s_cselect_b32 s25, s31, s39
	s_cselect_b32 s53, s30, s38
	s_add_u32 s36, s36, 0x40080
	s_addc_u32 s37, s37, 0
	s_add_u32 s54, s38, 0x100
	v_mov_b32_e32 v2, 0
	s_addc_u32 s55, s39, 0
	s_mov_b32 s56, -2
	v_mov_b32_e32 v3, v2
	v_mov_b32_e32 v4, v2
	v_mov_b32_e32 v5, v2
	v_mov_b32_e32 v6, v2
	v_mov_b32_e32 v7, v2
	v_mov_b32_e32 v8, v2
	v_mov_b32_e32 v9, v2
	v_mov_b32_e32 v18, v2
	v_mov_b32_e32 v19, v2
	v_mov_b32_e32 v20, v2
	v_mov_b32_e32 v21, v2
	v_mov_b32_e32 v22, v2
	v_mov_b32_e32 v23, v2
	v_mov_b32_e32 v24, v2
	v_mov_b32_e32 v25, v2
	v_mov_b32_e32 v34, v2
	v_mov_b32_e32 v35, v2
	v_mov_b32_e32 v36, v2
	v_mov_b32_e32 v37, v2
	v_mov_b32_e32 v38, v2
	v_mov_b32_e32 v39, v2
	v_mov_b32_e32 v40, v2
	v_mov_b32_e32 v41, v2
	v_mov_b32_e32 v50, v2
	v_mov_b32_e32 v51, v2
	v_mov_b32_e32 v52, v2
	v_mov_b32_e32 v53, v2
	v_mov_b32_e32 v54, v2
	v_mov_b32_e32 v55, v2
	v_mov_b32_e32 v56, v2
	v_mov_b32_e32 v57, v2
	v_mov_b32_e32 v10, v2
	v_mov_b32_e32 v11, v2
	v_mov_b32_e32 v12, v2
	v_mov_b32_e32 v13, v2
	v_mov_b32_e32 v14, v2
	v_mov_b32_e32 v15, v2
	v_mov_b32_e32 v16, v2
	v_mov_b32_e32 v17, v2
	v_mov_b32_e32 v26, v2
	v_mov_b32_e32 v27, v2
	v_mov_b32_e32 v28, v2
	v_mov_b32_e32 v29, v2
	v_mov_b32_e32 v30, v2
	v_mov_b32_e32 v31, v2
	v_mov_b32_e32 v32, v2
	v_mov_b32_e32 v33, v2
	v_mov_b32_e32 v42, v2
	v_mov_b32_e32 v43, v2
	v_mov_b32_e32 v44, v2
	v_mov_b32_e32 v45, v2
	v_mov_b32_e32 v46, v2
	v_mov_b32_e32 v47, v2
	v_mov_b32_e32 v48, v2
	v_mov_b32_e32 v49, v2
	v_mov_b32_e32 v58, v2
	v_mov_b32_e32 v59, v2
	v_mov_b32_e32 v60, v2
	v_mov_b32_e32 v61, v2
	v_mov_b32_e32 v62, v2
	v_mov_b32_e32 v63, v2
	v_mov_b32_e32 v64, v2
	v_mov_b32_e32 v65, v2
	v_mov_b32_e32 v66, v2
	v_mov_b32_e32 v67, v2
	v_mov_b32_e32 v68, v2
	v_mov_b32_e32 v69, v2
	v_mov_b32_e32 v70, v2
	v_mov_b32_e32 v71, v2
	v_mov_b32_e32 v72, v2
	v_mov_b32_e32 v73, v2
	v_mov_b32_e32 v82, v2
	v_mov_b32_e32 v83, v2
	v_mov_b32_e32 v84, v2
	v_mov_b32_e32 v85, v2
	v_mov_b32_e32 v86, v2
	v_mov_b32_e32 v87, v2
	v_mov_b32_e32 v88, v2
	v_mov_b32_e32 v89, v2
	v_mov_b32_e32 v98, v2
	v_mov_b32_e32 v99, v2
	v_mov_b32_e32 v100, v2
	v_mov_b32_e32 v101, v2
	v_mov_b32_e32 v102, v2
	v_mov_b32_e32 v103, v2
	v_mov_b32_e32 v104, v2
	v_mov_b32_e32 v105, v2
	v_mov_b32_e32 v114, v2
	v_mov_b32_e32 v115, v2
	v_mov_b32_e32 v116, v2
	v_mov_b32_e32 v117, v2
	v_mov_b32_e32 v118, v2
	v_mov_b32_e32 v119, v2
	v_mov_b32_e32 v120, v2
	v_mov_b32_e32 v121, v2
	v_mov_b32_e32 v74, v2
	v_mov_b32_e32 v75, v2
	v_mov_b32_e32 v76, v2
	v_mov_b32_e32 v77, v2
	v_mov_b32_e32 v78, v2
	v_mov_b32_e32 v79, v2
	v_mov_b32_e32 v80, v2
	v_mov_b32_e32 v81, v2
	v_mov_b32_e32 v90, v2
	v_mov_b32_e32 v91, v2
	v_mov_b32_e32 v92, v2
	v_mov_b32_e32 v93, v2
	v_mov_b32_e32 v94, v2
	v_mov_b32_e32 v95, v2
	v_mov_b32_e32 v96, v2
	v_mov_b32_e32 v97, v2
	v_mov_b32_e32 v106, v2
	v_mov_b32_e32 v107, v2
	v_mov_b32_e32 v108, v2
	v_mov_b32_e32 v109, v2
	v_mov_b32_e32 v110, v2
	v_mov_b32_e32 v111, v2
	v_mov_b32_e32 v112, v2
	v_mov_b32_e32 v113, v2
	v_mov_b32_e32 v122, v2
	v_mov_b32_e32 v123, v2
	v_mov_b32_e32 v124, v2
	v_mov_b32_e32 v125, v2
	v_mov_b32_e32 v134, v2
	v_mov_b32_e32 v135, v2
	v_mov_b32_e32 v136, v2
	v_mov_b32_e32 v137, v2
	s_mov_b32 s100, 0xfffbff80
	s_mov_b32 s101, -1
	v_lshl_add_u64 v[220:221], s[36:37], 0, v[186:187]
	v_lshl_add_u64 v[220:221], v[220:221], 0, s[100:101]
	v_lshl_add_u64 v[222:223], s[36:37], 0, v[188:189]
	v_lshl_add_u64 v[222:223], v[222:223], 0, s[100:101]
.LBB0_2049:
	ds_read_b128 v[126:129], v212
	ds_read_b128 v[130:133], v212 offset:1024
	ds_read_b128 v[138:141], v212 offset:2048
	ds_read_b128 v[142:145], v212 offset:3072
	ds_read_b128 v[146:149], v213
	ds_read_b128 v[150:153], v213 offset:1024
	ds_read_b128 v[154:157], v213 offset:2048
	ds_read_b128 v[158:161], v213 offset:3072
	s_add_u32 s38, s36, 0xfffc0080
	s_addc_u32 s39, s37, -1
	s_cmp_eq_u32 s56, 12
	s_cselect_b32 s41, s27, s39
	s_cselect_b32 s40, s52, s38
	s_cselect_b32 s39, s25, s55
	s_cselect_b32 s38, s53, s54
	v_lshl_add_u64 v[216:217], s[36:37], 0, v[186:187]
	s_add_i32 m0, s1, 0xc000
	ds_read_b128 v[162:165], v214
	ds_read_b128 v[166:169], v214 offset:1024
	ds_read_b128 v[170:173], v214 offset:2048
	ds_read_b128 v[174:177], v214 offset:3072
	ds_read_b128 v[194:197], v214 offset:4096
	ds_read_b128 v[198:201], v214 offset:5120
	ds_read_b128 v[202:205], v214 offset:6144
	ds_read_b128 v[206:209], v214 offset:7168
	global_load_lds_dwordx4 v[216:217], off
	v_lshl_add_u64 v[216:217], s[36:37], 0, v[188:189]
	s_add_i32 m0, s1, 0xe000
	s_nop 0
	global_load_lds_dwordx4 v[216:217], off
	s_mov_b32 m0, s43
	v_lshl_add_u64 v[216:217], v[220:221], 0, s[10:11]
	global_load_lds_dwordx4 v[216:217], off
	s_mov_b32 m0, s46
	v_lshl_add_u64 v[216:217], v[222:223], 0, s[10:11]
	global_load_lds_dwordx4 v[216:217], off
	s_waitcnt vmcnt(10)
	s_waitcnt lgkmcnt(0)
	s_barrier
; #define PG8_STAGE(bufoff, gbase, voff) do { _Pragma("unroll") for (int _i = 0; _i < 2; ++_i) \
;         __builtin_amdgcn_global_load_lds((const unsigned*)((const char*)(gbase) + (voff)[_i]), (PG8_LAS unsigned*)(lds + (bufoff) + ldsw + _i * 8192), 16, 0, 0); } while (0)
; #define PG8_LDA(dst, b, h) do { _Pragma("unroll") for (int m = 0; m < 4; ++m) _Pragma("unroll") for (int k = 0; k < 2; ++k) dst[m][k] = *(const PG8_LAS bf16x8*)(lds + PG8_SA(b, h) + aoff + m * 2048 + k * 1024); } while (0)
; #define PG8_LDB(dst, b, h) do { _Pragma("unroll") for (int n = 0; n < 2; ++n) _Pragma("unroll") for (int k = 0; k < 2; ++k) dst[n][k] = *(const PG8_LAS bf16x8*)(lds + PG8_SB(b, h) + boff + n * 2048 + k * 1024); } while (0)
; template <class Epi, class Sched, bool ALIGN_EPI = false, bool SP2 = false, bool HALFM = false>
; __device__ __forceinline__ void gemm_phase(PG8_LAS unsigned char* lds, const Gemm g, const Sched& S, const Epi& E) {
;     ...
;             const char* a1 = cA + (size_t)(t + 1) * kstep;
;             const char* a2 = last ? nA : cA + (size_t)(t + 2) * kstep; const char* b2 = last ? nB : cB + (size_t)(t + 2) * kstep;
;             const char* a3 = a2 + kstep; const char* b3 = b2 + kstep;
;             if (last && has_next) S.a_ready(nxt);
;             if constexpr (SP2) {
;             PG8_LDB(B0, 0, 0); PG8_LDB(B1, 0, 1); PG8_SCHED; PG8_LDA(At, 0, 0); PG8_STAGE(PG8_SA(1, 1), a1 + hstep, voffA);
;             PG8_WAIT_V(8); PG8_WAIT_L(0); PG8_BAR; PG8_MMA(0, 0, At, B0); PG8_MMA(0, 1, At, B1); PG8_BAR; PG8_SCHED;
;             PG8_LDA(At, 0, 1); PG8_STAGE(PG8_SB(0, 0), b2, voffB); PG8_STAGE(PG8_SB(0, 1), b2 + hstep, voffB); PG8_STAGE(PG8_SA(0, 0), a2, voffA);
;             PG8_WAIT_V(8); PG8_WAIT_L(0); PG8_BAR; if constexpr (!HALFM) { PG8_MMA(1, 0, At, B0); PG8_MMA(1, 1, At, B1); } PG8_BAR; PG8_SCHED;
;             PG8_LDB(B0, 1, 0); PG8_LDB(B1, 1, 1); PG8_SCHED; PG8_LDA(At, 1, 0); PG8_STAGE(PG8_SA(0, 1), a2 + hstep, voffA);
;             PG8_WAIT_V(8); PG8_WAIT_L(0); PG8_BAR; PG8_MMA(0, 0, At, B0); PG8_MMA(0, 1, At, B1); PG8_BAR; PG8_SCHED;
;             PG8_LDA(At, 1, 1); PG8_STAGE(PG8_SB(1, 0), b3, voffB); PG8_STAGE(PG8_SB(1, 1), b3 + hstep, voffB); PG8_STAGE(PG8_SA(1, 0), a3, voffA);
;             PG8_WAIT_V(8); PG8_WAIT_L(0); PG8_BAR; if constexpr (!HALFM) { PG8_MMA(1, 0, At, B0); PG8_MMA(1, 1, At, B1); } PG8_BAR; PG8_SCHED;
	s_setprio 1
	s_waitcnt lgkmcnt(0)
	v_mfma_f32_16x16x32_bf16 v[134:137], v[126:129], v[162:165], v[134:137]
	v_mfma_f32_16x16x32_bf16 v[122:125], v[138:141], v[162:165], v[122:125]
	v_mfma_f32_16x16x32_bf16 v[110:113], v[126:129], v[170:173], v[110:113]
	v_mfma_f32_16x16x32_bf16 v[106:109], v[138:141], v[170:173], v[106:109]
	v_mfma_f32_16x16x32_bf16 v[94:97], v[126:129], v[194:197], v[94:97]
	v_mfma_f32_16x16x32_bf16 v[90:93], v[138:141], v[194:197], v[90:93]
	v_mfma_f32_16x16x32_bf16 v[78:81], v[126:129], v[202:205], v[78:81]
	v_mfma_f32_16x16x32_bf16 v[74:77], v[138:141], v[202:205], v[74:77]
	v_mfma_f32_16x16x32_bf16 v[134:137], v[130:133], v[166:169], v[134:137]
	v_mfma_f32_16x16x32_bf16 v[122:125], v[142:145], v[166:169], v[122:125]
	v_mfma_f32_16x16x32_bf16 v[110:113], v[130:133], v[174:177], v[110:113]
	v_mfma_f32_16x16x32_bf16 v[106:109], v[142:145], v[174:177], v[106:109]
	v_mfma_f32_16x16x32_bf16 v[94:97], v[130:133], v[198:201], v[94:97]
	v_mfma_f32_16x16x32_bf16 v[90:93], v[142:145], v[198:201], v[90:93]
	v_mfma_f32_16x16x32_bf16 v[78:81], v[130:133], v[206:209], v[78:81]
	v_mfma_f32_16x16x32_bf16 v[74:77], v[142:145], v[206:209], v[74:77]
	s_setprio 0
	s_setprio 1
	v_mfma_f32_16x16x32_bf16 v[118:121], v[146:149], v[162:165], v[118:121]
	v_mfma_f32_16x16x32_bf16 v[114:117], v[154:157], v[162:165], v[114:117]
	v_mfma_f32_16x16x32_bf16 v[102:105], v[146:149], v[170:173], v[102:105]
	v_mfma_f32_16x16x32_bf16 v[98:101], v[154:157], v[170:173], v[98:101]
	v_mfma_f32_16x16x32_bf16 v[86:89], v[146:149], v[194:197], v[86:89]
	v_mfma_f32_16x16x32_bf16 v[82:85], v[154:157], v[194:197], v[82:85]
	v_mfma_f32_16x16x32_bf16 v[70:73], v[146:149], v[202:205], v[70:73]
	v_mfma_f32_16x16x32_bf16 v[66:69], v[154:157], v[202:205], v[66:69]
	v_mfma_f32_16x16x32_bf16 v[118:121], v[150:153], v[166:169], v[118:121]
	v_mfma_f32_16x16x32_bf16 v[114:117], v[158:161], v[166:169], v[114:117]
	v_mfma_f32_16x16x32_bf16 v[102:105], v[150:153], v[174:177], v[102:105]
	v_mfma_f32_16x16x32_bf16 v[98:101], v[158:161], v[174:177], v[98:101]
	v_mfma_f32_16x16x32_bf16 v[86:89], v[150:153], v[198:201], v[86:89]
	v_mfma_f32_16x16x32_bf16 v[82:85], v[158:161], v[198:201], v[82:85]
	v_mfma_f32_16x16x32_bf16 v[70:73], v[150:153], v[206:209], v[70:73]
	v_mfma_f32_16x16x32_bf16 v[66:69], v[158:161], v[206:209], v[66:69]
	s_setprio 0
	s_barrier
	s_add_i32 s57, s48, s0
	v_lshl_add_u64 v[216:217], s[38:39], 0, v[180:181]
	s_mov_b32 m0, s57
	ds_read_b128 v[162:165], v214 offset:16384
	ds_read_b128 v[166:169], v214 offset:17408
	ds_read_b128 v[170:173], v214 offset:18432
	ds_read_b128 v[174:177], v214 offset:19456
	ds_read_b128 v[194:197], v214 offset:20480
	ds_read_b128 v[198:201], v214 offset:21504
	ds_read_b128 v[202:205], v214 offset:22528
	ds_read_b128 v[206:209], v214 offset:23552
	global_load_lds_dwordx4 v[216:217], off
	s_add_i32 m0, s57, 0x2000
	s_add_u32 s58, s38, 0x40000
	v_lshl_add_u64 v[218:219], s[38:39], 0, v[184:185]
	s_addc_u32 s59, s39, 0
	s_add_i32 s57, s49, s0
	global_load_lds_dwordx4 v[218:219], off
	v_lshl_add_u64 v[220:221], s[58:59], 0, v[180:181]
	s_mov_b32 m0, s57
	v_lshl_add_u64 v[222:223], s[40:41], 0, v[182:183]
	global_load_lds_dwordx4 v[220:221], off
	v_lshl_add_u64 v[220:221], s[58:59], 0, v[184:185]
	s_add_i32 m0, s57, 0x2000
	s_nop 0
	global_load_lds_dwordx4 v[220:221], off
	v_lshl_add_u64 v[220:221], s[40:41], 0, v[178:179]
	s_waitcnt vmcnt(4)
	s_waitcnt lgkmcnt(0)
	s_barrier
	s_setprio 1
	s_waitcnt lgkmcnt(0)
	v_mfma_f32_16x16x32_bf16 v[62:65], v[126:129], v[162:165], v[62:65]
	v_mfma_f32_16x16x32_bf16 v[58:61], v[138:141], v[162:165], v[58:61]
	v_mfma_f32_16x16x32_bf16 v[46:49], v[126:129], v[170:173], v[46:49]
	v_mfma_f32_16x16x32_bf16 v[42:45], v[138:141], v[170:173], v[42:45]
	v_mfma_f32_16x16x32_bf16 v[30:33], v[126:129], v[194:197], v[30:33]
	v_mfma_f32_16x16x32_bf16 v[26:29], v[138:141], v[194:197], v[26:29]
	v_mfma_f32_16x16x32_bf16 v[14:17], v[126:129], v[202:205], v[14:17]
	v_mfma_f32_16x16x32_bf16 v[10:13], v[138:141], v[202:205], v[10:13]
	v_mfma_f32_16x16x32_bf16 v[62:65], v[130:133], v[166:169], v[62:65]
	v_mfma_f32_16x16x32_bf16 v[58:61], v[142:145], v[166:169], v[58:61]
	v_mfma_f32_16x16x32_bf16 v[46:49], v[130:133], v[174:177], v[46:49]
	v_mfma_f32_16x16x32_bf16 v[42:45], v[142:145], v[174:177], v[42:45]
	v_mfma_f32_16x16x32_bf16 v[30:33], v[130:133], v[198:201], v[30:33]
	v_mfma_f32_16x16x32_bf16 v[26:29], v[142:145], v[198:201], v[26:29]
	v_mfma_f32_16x16x32_bf16 v[14:17], v[130:133], v[206:209], v[14:17]
	v_mfma_f32_16x16x32_bf16 v[10:13], v[142:145], v[206:209], v[10:13]
	s_setprio 0
	s_setprio 1
	v_mfma_f32_16x16x32_bf16 v[54:57], v[146:149], v[162:165], v[54:57]
	v_mfma_f32_16x16x32_bf16 v[50:53], v[154:157], v[162:165], v[50:53]
	v_mfma_f32_16x16x32_bf16 v[38:41], v[146:149], v[170:173], v[38:41]
	v_mfma_f32_16x16x32_bf16 v[34:37], v[154:157], v[170:173], v[34:37]
	v_mfma_f32_16x16x32_bf16 v[22:25], v[146:149], v[194:197], v[22:25]
	v_mfma_f32_16x16x32_bf16 v[18:21], v[154:157], v[194:197], v[18:21]
	v_mfma_f32_16x16x32_bf16 v[6:9], v[146:149], v[202:205], v[6:9]
	v_mfma_f32_16x16x32_bf16 v[2:5], v[154:157], v[202:205], v[2:5]
	v_mfma_f32_16x16x32_bf16 v[54:57], v[150:153], v[166:169], v[54:57]
	v_mfma_f32_16x16x32_bf16 v[50:53], v[158:161], v[166:169], v[50:53]
	v_mfma_f32_16x16x32_bf16 v[38:41], v[150:153], v[174:177], v[38:41]
	v_mfma_f32_16x16x32_bf16 v[34:37], v[158:161], v[174:177], v[34:37]
	v_mfma_f32_16x16x32_bf16 v[22:25], v[150:153], v[198:201], v[22:25]
	v_mfma_f32_16x16x32_bf16 v[18:21], v[158:161], v[198:201], v[18:21]
	v_mfma_f32_16x16x32_bf16 v[6:9], v[150:153], v[206:209], v[6:9]
	v_mfma_f32_16x16x32_bf16 v[2:5], v[158:161], v[206:209], v[2:5]
	s_setprio 0
	s_barrier
; #define PG8_STAGE(bufoff, gbase, voff) do { _Pragma("unroll") for (int _i = 0; _i < 2; ++_i) \
;         __builtin_amdgcn_global_load_lds((const unsigned*)((const char*)(gbase) + (voff)[_i]), (PG8_LAS unsigned*)(lds + (bufoff) + ldsw + _i * 8192), 16, 0, 0); } while (0)
; #define PG8_LDA(dst, b, h) do { _Pragma("unroll") for (int m = 0; m < 4; ++m) _Pragma("unroll") for (int k = 0; k < 2; ++k) dst[m][k] = *(const PG8_LAS bf16x8*)(lds + PG8_SA(b, h) + aoff + m * 2048 + k * 1024); } while (0)
; #define PG8_LDB(dst, b, h) do { _Pragma("unroll") for (int n = 0; n < 2; ++n) _Pragma("unroll") for (int k = 0; k < 2; ++k) dst[n][k] = *(const PG8_LAS bf16x8*)(lds + PG8_SB(b, h) + boff + n * 2048 + k * 1024); } while (0)
; #define PG8_MMA(ai, bj, At, Bt) do { __builtin_amdgcn_s_setprio(1); _Pragma("unroll") for (int m = 0; m < 4; ++m) _Pragma("unroll") for (int n = 0; n < 2; ++n) _Pragma("unroll") for (int k = 0; k < 2; ++k) \
;         acc[ai][bj][m][n] = __builtin_amdgcn_mfma_f32_16x16x32_bf16(Bt[n][k], At[m][k], acc[ai][bj][m][n], 0, 0, 0); __builtin_amdgcn_s_setprio(0); } while (0)
; #define PG8_WAIT_V(n) asm volatile("s_waitcnt vmcnt(" #n ")" ::: "memory")
; #define PG8_WAIT_L(n) asm volatile("s_waitcnt lgkmcnt(" #n ")" ::: "memory")
; #define PG8_BAR __builtin_amdgcn_s_barrier()
; #define PG8_SCHED __builtin_amdgcn_sched_barrier(0)
; template <class Epi, class Sched, bool ALIGN_EPI = false, bool SP2 = false, bool HALFM = false>
; __device__ __forceinline__ void gemm_phase(PG8_LAS unsigned char* lds, const Gemm g, const Sched& S, const Epi& E) {
;     ...
;             PG8_LDB(B0, 1, 0); PG8_LDB(B1, 1, 1); PG8_SCHED; PG8_LDA(At, 1, 0); PG8_STAGE(PG8_SA(0, 1), a2 + hstep, voffA);
;             PG8_WAIT_V(8); PG8_WAIT_L(0); PG8_BAR; PG8_MMA(0, 0, At, B0); PG8_MMA(0, 1, At, B1); PG8_BAR; PG8_SCHED;
	s_add_i32 s57, 0, 0x18000
	s_add_i32 s58, 0, 0x1c000
	v_add_u32_e32 v142, s57, v210
	v_add_u32_e32 v158, s58, v210
	ds_read_b128 v[126:129], v142
	ds_read_b128 v[130:133], v142 offset:1024
	ds_read_b128 v[138:141], v142 offset:2048
	ds_read_b128 v[142:145], v142 offset:3072
	ds_read_b128 v[146:149], v158
	ds_read_b128 v[150:153], v158 offset:1024
	ds_read_b128 v[154:157], v158 offset:2048
	ds_read_b128 v[158:161], v158 offset:3072
	s_add_u32 s40, s40, 0x40000
	s_addc_u32 s41, s41, 0
	s_mov_b32 m0, s3
	v_lshl_add_u64 v[224:225], s[40:41], 0, v[178:179]
	ds_read_b128 v[162:165], v214 offset:32768
	ds_read_b128 v[166:169], v214 offset:33792
	ds_read_b128 v[170:173], v214 offset:34816
	ds_read_b128 v[174:177], v214 offset:35840
	ds_read_b128 v[194:197], v214 offset:36864
	ds_read_b128 v[198:201], v214 offset:37888
	ds_read_b128 v[202:205], v214 offset:38912
	ds_read_b128 v[206:209], v214 offset:39936
	global_load_lds_dwordx4 v[224:225], off
	v_lshl_add_u64 v[224:225], s[40:41], 0, v[182:183]
	s_mov_b32 m0, s35
	s_nop 0
	global_load_lds_dwordx4 v[224:225], off
	s_mov_b32 m0, s1
	s_nop 0
	global_load_lds_dwordx4 v[220:221], off
	s_mov_b32 m0, s2
	s_nop 0
	global_load_lds_dwordx4 v[222:223], off
	s_waitcnt vmcnt(10)
	s_waitcnt lgkmcnt(0)
	s_barrier
	s_setprio 1
	s_waitcnt lgkmcnt(0)
	v_mfma_f32_16x16x32_bf16 v[134:137], v[126:129], v[162:165], v[134:137]
	v_mfma_f32_16x16x32_bf16 v[122:125], v[138:141], v[162:165], v[122:125]
	v_mfma_f32_16x16x32_bf16 v[110:113], v[126:129], v[170:173], v[110:113]
	v_mfma_f32_16x16x32_bf16 v[106:109], v[138:141], v[170:173], v[106:109]
	v_mfma_f32_16x16x32_bf16 v[94:97], v[126:129], v[194:197], v[94:97]
	v_mfma_f32_16x16x32_bf16 v[90:93], v[138:141], v[194:197], v[90:93]
	v_mfma_f32_16x16x32_bf16 v[78:81], v[126:129], v[202:205], v[78:81]
	v_mfma_f32_16x16x32_bf16 v[74:77], v[138:141], v[202:205], v[74:77]
	v_mfma_f32_16x16x32_bf16 v[134:137], v[130:133], v[166:169], v[134:137]
	v_mfma_f32_16x16x32_bf16 v[122:125], v[142:145], v[166:169], v[122:125]
	v_mfma_f32_16x16x32_bf16 v[110:113], v[130:133], v[174:177], v[110:113]
	v_mfma_f32_16x16x32_bf16 v[106:109], v[142:145], v[174:177], v[106:109]
	v_mfma_f32_16x16x32_bf16 v[94:97], v[130:133], v[198:201], v[94:97]
	v_mfma_f32_16x16x32_bf16 v[90:93], v[142:145], v[198:201], v[90:93]
	v_mfma_f32_16x16x32_bf16 v[78:81], v[130:133], v[206:209], v[78:81]
	v_mfma_f32_16x16x32_bf16 v[74:77], v[142:145], v[206:209], v[74:77]
	s_setprio 0
	s_setprio 1
	v_mfma_f32_16x16x32_bf16 v[118:121], v[146:149], v[162:165], v[118:121]
	v_mfma_f32_16x16x32_bf16 v[114:117], v[154:157], v[162:165], v[114:117]
	v_mfma_f32_16x16x32_bf16 v[102:105], v[146:149], v[170:173], v[102:105]
	v_mfma_f32_16x16x32_bf16 v[98:101], v[154:157], v[170:173], v[98:101]
	v_mfma_f32_16x16x32_bf16 v[86:89], v[146:149], v[194:197], v[86:89]
	v_mfma_f32_16x16x32_bf16 v[82:85], v[154:157], v[194:197], v[82:85]
	v_mfma_f32_16x16x32_bf16 v[70:73], v[146:149], v[202:205], v[70:73]
	v_mfma_f32_16x16x32_bf16 v[66:69], v[154:157], v[202:205], v[66:69]
	v_mfma_f32_16x16x32_bf16 v[118:121], v[150:153], v[166:169], v[118:121]
	v_mfma_f32_16x16x32_bf16 v[114:117], v[158:161], v[166:169], v[114:117]
	v_mfma_f32_16x16x32_bf16 v[102:105], v[150:153], v[174:177], v[102:105]
	v_mfma_f32_16x16x32_bf16 v[98:101], v[158:161], v[174:177], v[98:101]
	v_mfma_f32_16x16x32_bf16 v[86:89], v[150:153], v[198:201], v[86:89]
	v_mfma_f32_16x16x32_bf16 v[82:85], v[158:161], v[198:201], v[82:85]
	v_mfma_f32_16x16x32_bf16 v[70:73], v[150:153], v[206:209], v[70:73]
	v_mfma_f32_16x16x32_bf16 v[66:69], v[158:161], v[206:209], v[66:69]
	s_setprio 0
	s_barrier
; #define PG8_STAGE(bufoff, gbase, voff) do { _Pragma("unroll") for (int _i = 0; _i < 2; ++_i) \
;         __builtin_amdgcn_global_load_lds((const unsigned*)((const char*)(gbase) + (voff)[_i]), (PG8_LAS unsigned*)(lds + (bufoff) + ldsw + _i * 8192), 16, 0, 0); } while (0)
; #define PG8_LDA(dst, b, h) do { _Pragma("unroll") for (int m = 0; m < 4; ++m) _Pragma("unroll") for (int k = 0; k < 2; ++k) dst[m][k] = *(const PG8_LAS bf16x8*)(lds + PG8_SA(b, h) + aoff + m * 2048 + k * 1024); } while (0)
; #define PG8_MMA(ai, bj, At, Bt) do { __builtin_amdgcn_s_setprio(1); _Pragma("unroll") for (int m = 0; m < 4; ++m) _Pragma("unroll") for (int n = 0; n < 2; ++n) _Pragma("unroll") for (int k = 0; k < 2; ++k) \
;         acc[ai][bj][m][n] = __builtin_amdgcn_mfma_f32_16x16x32_bf16(Bt[n][k], At[m][k], acc[ai][bj][m][n], 0, 0, 0); __builtin_amdgcn_s_setprio(0); } while (0)
; #define PG8_WAIT_V(n) asm volatile("s_waitcnt vmcnt(" #n ")" ::: "memory")
; #define PG8_WAIT_L(n) asm volatile("s_waitcnt lgkmcnt(" #n ")" ::: "memory")
; #define PG8_BAR __builtin_amdgcn_s_barrier()
; #define PG8_SCHED __builtin_amdgcn_sched_barrier(0)
; template <class Epi, class Sched, bool ALIGN_EPI = false, bool SP2 = false, bool HALFM = false>
; __device__ __forceinline__ void gemm_phase(PG8_LAS unsigned char* lds, const Gemm g, const Sched& S, const Epi& E) {
;     ...
;         for (int t = 0; t < nt; t += 2) {
;             const bool last = (t == nt - 2);
;     ...
;             PG8_LDA(At, 1, 1); PG8_STAGE(PG8_SB(1, 0), b3, voffB); PG8_STAGE(PG8_SB(1, 1), b3 + hstep, voffB); PG8_STAGE(PG8_SA(1, 0), a3, voffA);
;             PG8_WAIT_V(8); PG8_WAIT_L(0); PG8_BAR; if constexpr (!HALFM) { PG8_MMA(1, 0, At, B0); PG8_MMA(1, 1, At, B1); } PG8_BAR; PG8_SCHED;
	s_add_i32 s40, s57, s0
	v_lshl_add_u64 v[216:217], v[216:217], 0, s[10:11]
	s_mov_b32 m0, s40
	ds_read_b128 v[162:165], v214 offset:49152
	ds_read_b128 v[166:169], v214 offset:50176
	ds_read_b128 v[170:173], v214 offset:51200
	ds_read_b128 v[174:177], v214 offset:52224
	ds_read_b128 v[194:197], v214 offset:53248
	ds_read_b128 v[198:201], v214 offset:54272
	ds_read_b128 v[202:205], v214 offset:55296
	ds_read_b128 v[206:209], v214 offset:56320
	global_load_lds_dwordx4 v[216:217], off
	s_add_i32 m0, s40, 0x2000
	s_add_u32 s38, s38, 0x40080
	v_lshl_add_u64 v[216:217], v[218:219], 0, s[10:11]
	s_addc_u32 s39, s39, 0
	s_add_i32 s40, s58, s0
	global_load_lds_dwordx4 v[216:217], off
	v_lshl_add_u64 v[216:217], s[38:39], 0, v[180:181]
	s_mov_b32 m0, s40
	s_nop 0
	global_load_lds_dwordx4 v[216:217], off
	v_lshl_add_u64 v[216:217], s[38:39], 0, v[184:185]
	s_add_i32 m0, s40, 0x2000
	s_nop 0
	global_load_lds_dwordx4 v[216:217], off
	s_waitcnt vmcnt(4)
	s_waitcnt lgkmcnt(0)
	s_barrier
	s_setprio 1
	s_waitcnt lgkmcnt(0)
	v_mfma_f32_16x16x32_bf16 v[62:65], v[126:129], v[162:165], v[62:65]
	v_mfma_f32_16x16x32_bf16 v[58:61], v[138:141], v[162:165], v[58:61]
	v_mfma_f32_16x16x32_bf16 v[46:49], v[126:129], v[170:173], v[46:49]
	v_mfma_f32_16x16x32_bf16 v[42:45], v[138:141], v[170:173], v[42:45]
	v_mfma_f32_16x16x32_bf16 v[30:33], v[126:129], v[194:197], v[30:33]
	v_mfma_f32_16x16x32_bf16 v[26:29], v[138:141], v[194:197], v[26:29]
	v_mfma_f32_16x16x32_bf16 v[14:17], v[126:129], v[202:205], v[14:17]
	v_mfma_f32_16x16x32_bf16 v[10:13], v[138:141], v[202:205], v[10:13]
	v_mfma_f32_16x16x32_bf16 v[62:65], v[130:133], v[166:169], v[62:65]
	v_mfma_f32_16x16x32_bf16 v[58:61], v[142:145], v[166:169], v[58:61]
	v_mfma_f32_16x16x32_bf16 v[46:49], v[130:133], v[174:177], v[46:49]
	v_mfma_f32_16x16x32_bf16 v[42:45], v[142:145], v[174:177], v[42:45]
	v_mfma_f32_16x16x32_bf16 v[30:33], v[130:133], v[198:201], v[30:33]
	v_mfma_f32_16x16x32_bf16 v[26:29], v[142:145], v[198:201], v[26:29]
	v_mfma_f32_16x16x32_bf16 v[14:17], v[130:133], v[206:209], v[14:17]
	v_mfma_f32_16x16x32_bf16 v[10:13], v[142:145], v[206:209], v[10:13]
	s_setprio 0
	s_setprio 1
	v_mfma_f32_16x16x32_bf16 v[54:57], v[146:149], v[162:165], v[54:57]
	v_mfma_f32_16x16x32_bf16 v[50:53], v[154:157], v[162:165], v[50:53]
	v_mfma_f32_16x16x32_bf16 v[38:41], v[146:149], v[170:173], v[38:41]
	v_mfma_f32_16x16x32_bf16 v[34:37], v[154:157], v[170:173], v[34:37]
	v_mfma_f32_16x16x32_bf16 v[22:25], v[146:149], v[194:197], v[22:25]
	v_mfma_f32_16x16x32_bf16 v[18:21], v[154:157], v[194:197], v[18:21]
	v_mfma_f32_16x16x32_bf16 v[6:9], v[146:149], v[202:205], v[6:9]
	v_mfma_f32_16x16x32_bf16 v[2:5], v[154:157], v[202:205], v[2:5]
	v_mfma_f32_16x16x32_bf16 v[54:57], v[150:153], v[166:169], v[54:57]
	v_mfma_f32_16x16x32_bf16 v[50:53], v[158:161], v[166:169], v[50:53]
	v_mfma_f32_16x16x32_bf16 v[38:41], v[150:153], v[174:177], v[38:41]
	v_mfma_f32_16x16x32_bf16 v[34:37], v[158:161], v[174:177], v[34:37]
	v_mfma_f32_16x16x32_bf16 v[22:25], v[150:153], v[198:201], v[22:25]
	v_mfma_f32_16x16x32_bf16 v[18:21], v[158:161], v[198:201], v[18:21]
	v_mfma_f32_16x16x32_bf16 v[6:9], v[150:153], v[206:209], v[6:9]
	v_mfma_f32_16x16x32_bf16 v[2:5], v[158:161], v[206:209], v[2:5]
	s_setprio 0
	s_barrier
	s_add_i32 s56, s56, 2
	s_add_u32 s36, s36, 0x100
	s_addc_u32 s37, s37, 0
	s_add_u32 s54, s54, 0x100
	s_addc_u32 s55, s55, 0
	s_cmp_gt_u32 s56, 13
	s_cbranch_scc0 .LBB0_2049
	s_and_b64 vcc, exec, s[12:13]
	s_cbranch_vccz .LBB0_2052
	s_barrier

; __global__ void __launch_bounds__(NWAVES * 64, 2) fwd(Args args) {
	.amdhsa_kernel _Z3fwd4Args
		.amdhsa_group_segment_fixed_size 0
		.amdhsa_private_segment_fixed_size 0
		.amdhsa_kernarg_size 528
		.amdhsa_user_sgpr_count 2
		.amdhsa_user_sgpr_dispatch_ptr 0
		.amdhsa_user_sgpr_queue_ptr 0
		.amdhsa_user_sgpr_kernarg_segment_ptr 1
		.amdhsa_user_sgpr_dispatch_id 0
		.amdhsa_user_sgpr_kernarg_preload_length 0
		.amdhsa_user_sgpr_kernarg_preload_offset 0
		.amdhsa_user_sgpr_private_segment_size 0
		.amdhsa_uses_dynamic_stack 0
		.amdhsa_enable_private_segment 0
		.amdhsa_system_sgpr_workgroup_id_x 1
		.amdhsa_system_sgpr_workgroup_id_y 0
		.amdhsa_system_sgpr_workgroup_id_z 0
		.amdhsa_system_sgpr_workgroup_info 0
		.amdhsa_system_vgpr_workitem_id 0
		.amdhsa_next_free_vgpr 255
		.amdhsa_next_free_sgpr 102
		.amdhsa_accum_offset 256
		.amdhsa_reserve_vcc 1
		.amdhsa_float_round_mode_32 0
		.amdhsa_float_round_mode_16_64 0
		.amdhsa_float_denorm_mode_32 3
		.amdhsa_float_denorm_mode_16_64 3
		.amdhsa_dx10_clamp 1
		.amdhsa_ieee_mode 1
		.amdhsa_fp16_overflow 0
		.amdhsa_tg_split 0
		.amdhsa_exception_fp_ieee_invalid_op 0
		.amdhsa_exception_fp_denorm_src 0
		.amdhsa_exception_fp_ieee_div_zero 0
		.amdhsa_exception_fp_ieee_overflow 0
		.amdhsa_exception_fp_ieee_underflow 0
		.amdhsa_exception_fp_ieee_inexact 0
		.amdhsa_exception_int_div_zero 0
	.end_amdhsa_kernel

; __global__ void __launch_bounds__(NWAVES * 64, 2) fwd(Args args) {
amdhsa.kernels:
  - .agpr_count:     0
    .args:
      - .offset:         0
        .size:           272
        .value_kind:     by_value
      - .offset:         272
        .size:           4
        .value_kind:     hidden_block_count_x
      - .offset:         276
        .size:           4
        .value_kind:     hidden_block_count_y
      - .offset:         280
        .size:           4
        .value_kind:     hidden_block_count_z
      - .offset:         284
        .size:           2
        .value_kind:     hidden_group_size_x
      - .offset:         286
        .size:           2
        .value_kind:     hidden_group_size_y
      - .offset:         288
        .size:           2
        .value_kind:     hidden_group_size_z
      - .offset:         290
        .size:           2
        .value_kind:     hidden_remainder_x
      - .offset:         292
        .size:           2
        .value_kind:     hidden_remainder_y
      - .offset:         294
        .size:           2
        .value_kind:     hidden_remainder_z
      - .offset:         312
        .size:           8
        .value_kind:     hidden_global_offset_x
      - .offset:         320
        .size:           8
        .value_kind:     hidden_global_offset_y
      - .offset:         328
        .size:           8
        .value_kind:     hidden_global_offset_z
      - .offset:         336
        .size:           2
        .value_kind:     hidden_grid_dims
      - .offset:         392
        .size:           4
        .value_kind:     hidden_dynamic_lds_size
    .group_segment_fixed_size: 0
    .kernarg_segment_align: 8
    .kernarg_segment_size: 528
    .language:       OpenCL C
    .language_version:
      - 2
      - 0
    .max_flat_workgroup_size: 512
    .name:           _Z3fwd4Args
    .private_segment_fixed_size: 0
    .sgpr_count:     108
    .sgpr_spill_count: 71
    .symbol:         _Z3fwd4Args.kd
    .uniform_work_group_size: 1
    .uses_dynamic_stack: false
    .vgpr_count:     255
    .vgpr_spill_count: 0
    .wavefront_size: 64
